# gemm_in: bq rmsnorm + iq tiles get own paired-16B-store epilogue; gate bias / bq norm weights loaded before next-tile DMA with counted vmcnt(12)
# speedup vs baseline: 1.0037x; 1.0037x over previous
.Lg2_k:
	s_waitcnt vmcnt(0)
	s_barrier
	s_add_i32 m0, s58, 0xc000
	s_nop 0
	global_load_lds_dwordx4 v74, s[56:57]
	s_add_i32 m0, s58, 0xd000
	s_nop 0
	global_load_lds_dwordx4 v75, s[56:57]
	s_add_i32 m0, s58, 0xe000
	s_nop 0
	global_load_lds_dwordx4 v76, s[56:57]
	s_add_i32 m0, s58, 0xf000
	s_nop 0
	global_load_lds_dwordx4 v77, s[56:57]
	s_add_u32 s56, s56, 0x80
	s_addc_u32 s57, s57, 0
	ds_read_b128 v[148:151], v78 offset:0
	ds_read_b128 v[152:155], v78 offset:2048
	ds_read_b128 v[156:159], v78 offset:4096
	ds_read_b128 v[160:163], v78 offset:6144
	ds_read_b128 v[188:191], v79 offset:32768
	ds_read_b128 v[192:195], v79 offset:34816
	ds_read_b128 v[208:211], v79 offset:36864
	ds_read_b128 v[212:215], v79 offset:38912
	ds_read_b128 v[164:167], v78 offset:16384
	ds_read_b128 v[168:171], v78 offset:18432
	ds_read_b128 v[174:177], v78 offset:20480
	ds_read_b128 v[182:185], v78 offset:22528
	s_setprio 1
	s_waitcnt lgkmcnt(4)
	v_mfma_f32_16x16x32_bf16 v[62:65], v[188:191], v[148:151], v[62:65]
	v_mfma_f32_16x16x32_bf16 v[58:61], v[192:195], v[148:151], v[58:61]
	v_mfma_f32_16x16x32_bf16 v[54:57], v[208:211], v[148:151], v[54:57]
	v_mfma_f32_16x16x32_bf16 v[50:53], v[212:215], v[148:151], v[50:53]
	v_mfma_f32_16x16x32_bf16 v[46:49], v[188:191], v[152:155], v[46:49]
	v_mfma_f32_16x16x32_bf16 v[42:45], v[192:195], v[152:155], v[42:45]
	v_mfma_f32_16x16x32_bf16 v[38:41], v[208:211], v[152:155], v[38:41]
	v_mfma_f32_16x16x32_bf16 v[34:37], v[212:215], v[152:155], v[34:37]
	v_mfma_f32_16x16x32_bf16 v[30:33], v[188:191], v[156:159], v[30:33]
	v_mfma_f32_16x16x32_bf16 v[26:29], v[192:195], v[156:159], v[26:29]
	v_mfma_f32_16x16x32_bf16 v[22:25], v[208:211], v[156:159], v[22:25]
	v_mfma_f32_16x16x32_bf16 v[18:21], v[212:215], v[156:159], v[18:21]
	v_mfma_f32_16x16x32_bf16 v[14:17], v[188:191], v[160:163], v[14:17]
	v_mfma_f32_16x16x32_bf16 v[10:13], v[192:195], v[160:163], v[10:13]
	v_mfma_f32_16x16x32_bf16 v[6:9], v[208:211], v[160:163], v[6:9]
	v_mfma_f32_16x16x32_bf16 v[2:5], v[212:215], v[160:163], v[2:5]
	s_waitcnt lgkmcnt(0)
	v_mfma_f32_16x16x32_bf16 v[66:69], v[188:191], v[164:167], v[66:69]
	v_mfma_f32_16x16x32_bf16 v[70:73], v[192:195], v[164:167], v[70:73]
	v_mfma_f32_16x16x32_bf16 v[82:85], v[208:211], v[164:167], v[82:85]
	v_mfma_f32_16x16x32_bf16 v[88:91], v[212:215], v[164:167], v[88:91]
	v_mfma_f32_16x16x32_bf16 v[92:95], v[188:191], v[168:171], v[92:95]
	v_mfma_f32_16x16x32_bf16 v[96:99], v[192:195], v[168:171], v[96:99]
	v_mfma_f32_16x16x32_bf16 v[100:103], v[208:211], v[168:171], v[100:103]
	v_mfma_f32_16x16x32_bf16 v[106:109], v[212:215], v[168:171], v[106:109]
	v_mfma_f32_16x16x32_bf16 v[110:113], v[188:191], v[174:177], v[110:113]
	v_mfma_f32_16x16x32_bf16 v[114:117], v[192:195], v[174:177], v[114:117]
	v_mfma_f32_16x16x32_bf16 v[118:121], v[208:211], v[174:177], v[118:121]
	v_mfma_f32_16x16x32_bf16 v[122:125], v[212:215], v[174:177], v[122:125]
	v_mfma_f32_16x16x32_bf16 v[126:129], v[188:191], v[182:185], v[126:129]
	v_mfma_f32_16x16x32_bf16 v[136:139], v[192:195], v[182:185], v[136:139]
	v_mfma_f32_16x16x32_bf16 v[140:143], v[208:211], v[182:185], v[140:143]
	v_mfma_f32_16x16x32_bf16 v[144:147], v[212:215], v[182:185], v[144:147]
	s_setprio 0
	ds_read_b128 v[148:151], v80 offset:0
	ds_read_b128 v[152:155], v80 offset:2048
	ds_read_b128 v[156:159], v80 offset:4096
	ds_read_b128 v[160:163], v80 offset:6144
	ds_read_b128 v[188:191], v81 offset:32768
	ds_read_b128 v[192:195], v81 offset:34816
	ds_read_b128 v[208:211], v81 offset:36864
	ds_read_b128 v[212:215], v81 offset:38912
	ds_read_b128 v[164:167], v80 offset:16384
	ds_read_b128 v[168:171], v80 offset:18432
	ds_read_b128 v[174:177], v80 offset:20480
	ds_read_b128 v[182:185], v80 offset:22528
	s_waitcnt lgkmcnt(0)
	s_barrier
	s_add_i32 m0, s58, 0x0
	s_nop 0
	global_load_lds_dwordx4 v74, s[50:51]
	s_add_i32 m0, s58, 0x1000
	s_nop 0
	global_load_lds_dwordx4 v75, s[50:51]
	s_add_i32 m0, s58, 0x2000
	s_nop 0
	global_load_lds_dwordx4 v76, s[50:51]
	s_add_i32 m0, s58, 0x3000
	s_nop 0
	global_load_lds_dwordx4 v77, s[50:51]
	s_add_i32 m0, s58, 0x4000
	s_nop 0
	global_load_lds_dwordx4 v74, s[52:53]
	s_add_i32 m0, s58, 0x5000
	s_nop 0
	global_load_lds_dwordx4 v75, s[52:53]
	s_add_i32 m0, s58, 0x6000
	s_nop 0
	global_load_lds_dwordx4 v76, s[52:53]
	s_add_i32 m0, s58, 0x7000
	s_nop 0
	global_load_lds_dwordx4 v77, s[52:53]
	s_add_u32 s50, s50, 0x80
	s_addc_u32 s51, s51, 0
	s_add_u32 s52, s52, 0x80
	s_addc_u32 s53, s53, 0
	s_setprio 1
	v_mfma_f32_16x16x32_bf16 v[62:65], v[188:191], v[148:151], v[62:65]
	v_mfma_f32_16x16x32_bf16 v[58:61], v[192:195], v[148:151], v[58:61]
	v_mfma_f32_16x16x32_bf16 v[54:57], v[208:211], v[148:151], v[54:57]
	v_mfma_f32_16x16x32_bf16 v[50:53], v[212:215], v[148:151], v[50:53]
	v_mfma_f32_16x16x32_bf16 v[46:49], v[188:191], v[152:155], v[46:49]
	v_mfma_f32_16x16x32_bf16 v[42:45], v[192:195], v[152:155], v[42:45]
	v_mfma_f32_16x16x32_bf16 v[38:41], v[208:211], v[152:155], v[38:41]
	v_mfma_f32_16x16x32_bf16 v[34:37], v[212:215], v[152:155], v[34:37]
	v_mfma_f32_16x16x32_bf16 v[30:33], v[188:191], v[156:159], v[30:33]
	v_mfma_f32_16x16x32_bf16 v[26:29], v[192:195], v[156:159], v[26:29]
	v_mfma_f32_16x16x32_bf16 v[22:25], v[208:211], v[156:159], v[22:25]
	v_mfma_f32_16x16x32_bf16 v[18:21], v[212:215], v[156:159], v[18:21]
	v_mfma_f32_16x16x32_bf16 v[14:17], v[188:191], v[160:163], v[14:17]
	v_mfma_f32_16x16x32_bf16 v[10:13], v[192:195], v[160:163], v[10:13]
	v_mfma_f32_16x16x32_bf16 v[6:9], v[208:211], v[160:163], v[6:9]
	v_mfma_f32_16x16x32_bf16 v[2:5], v[212:215], v[160:163], v[2:5]
	v_mfma_f32_16x16x32_bf16 v[66:69], v[188:191], v[164:167], v[66:69]
	v_mfma_f32_16x16x32_bf16 v[70:73], v[192:195], v[164:167], v[70:73]
	v_mfma_f32_16x16x32_bf16 v[82:85], v[208:211], v[164:167], v[82:85]
	v_mfma_f32_16x16x32_bf16 v[88:91], v[212:215], v[164:167], v[88:91]
	v_mfma_f32_16x16x32_bf16 v[92:95], v[188:191], v[168:171], v[92:95]
	v_mfma_f32_16x16x32_bf16 v[96:99], v[192:195], v[168:171], v[96:99]
	v_mfma_f32_16x16x32_bf16 v[100:103], v[208:211], v[168:171], v[100:103]
	v_mfma_f32_16x16x32_bf16 v[106:109], v[212:215], v[168:171], v[106:109]
	v_mfma_f32_16x16x32_bf16 v[110:113], v[188:191], v[174:177], v[110:113]
	v_mfma_f32_16x16x32_bf16 v[114:117], v[192:195], v[174:177], v[114:117]
	v_mfma_f32_16x16x32_bf16 v[118:121], v[208:211], v[174:177], v[118:121]
	v_mfma_f32_16x16x32_bf16 v[122:125], v[212:215], v[174:177], v[122:125]
	v_mfma_f32_16x16x32_bf16 v[126:129], v[188:191], v[182:185], v[126:129]
	v_mfma_f32_16x16x32_bf16 v[136:139], v[192:195], v[182:185], v[136:139]
	v_mfma_f32_16x16x32_bf16 v[140:143], v[208:211], v[182:185], v[140:143]
	v_mfma_f32_16x16x32_bf16 v[144:147], v[212:215], v[182:185], v[144:147]
	s_setprio 0
	s_waitcnt vmcnt(0)
	s_barrier
	s_add_i32 m0, s58, 0x8000
	s_nop 0
	global_load_lds_dwordx4 v74, s[56:57]
	s_add_i32 m0, s58, 0x9000
	s_nop 0
	global_load_lds_dwordx4 v75, s[56:57]
	s_add_i32 m0, s58, 0xa000
	s_nop 0
	global_load_lds_dwordx4 v76, s[56:57]
	s_add_i32 m0, s58, 0xb000
	s_nop 0
	global_load_lds_dwordx4 v77, s[56:57]
	s_add_u32 s56, s56, 0x80
	s_addc_u32 s57, s57, 0
	ds_read_b128 v[148:151], v78 offset:0
	ds_read_b128 v[152:155], v78 offset:2048
	ds_read_b128 v[156:159], v78 offset:4096
	ds_read_b128 v[160:163], v78 offset:6144
	ds_read_b128 v[188:191], v79 offset:49152
	ds_read_b128 v[192:195], v79 offset:51200
	ds_read_b128 v[208:211], v79 offset:53248
	ds_read_b128 v[212:215], v79 offset:55296
	ds_read_b128 v[164:167], v78 offset:16384
	ds_read_b128 v[168:171], v78 offset:18432
	ds_read_b128 v[174:177], v78 offset:20480
	ds_read_b128 v[182:185], v78 offset:22528
	s_setprio 1
	s_waitcnt lgkmcnt(4)
	v_mfma_f32_16x16x32_bf16 v[62:65], v[188:191], v[148:151], v[62:65]
	v_mfma_f32_16x16x32_bf16 v[58:61], v[192:195], v[148:151], v[58:61]
	v_mfma_f32_16x16x32_bf16 v[54:57], v[208:211], v[148:151], v[54:57]
	v_mfma_f32_16x16x32_bf16 v[50:53], v[212:215], v[148:151], v[50:53]
	v_mfma_f32_16x16x32_bf16 v[46:49], v[188:191], v[152:155], v[46:49]
	v_mfma_f32_16x16x32_bf16 v[42:45], v[192:195], v[152:155], v[42:45]
	v_mfma_f32_16x16x32_bf16 v[38:41], v[208:211], v[152:155], v[38:41]
	v_mfma_f32_16x16x32_bf16 v[34:37], v[212:215], v[152:155], v[34:37]
	v_mfma_f32_16x16x32_bf16 v[30:33], v[188:191], v[156:159], v[30:33]
	v_mfma_f32_16x16x32_bf16 v[26:29], v[192:195], v[156:159], v[26:29]
	v_mfma_f32_16x16x32_bf16 v[22:25], v[208:211], v[156:159], v[22:25]
	v_mfma_f32_16x16x32_bf16 v[18:21], v[212:215], v[156:159], v[18:21]
	v_mfma_f32_16x16x32_bf16 v[14:17], v[188:191], v[160:163], v[14:17]
	v_mfma_f32_16x16x32_bf16 v[10:13], v[192:195], v[160:163], v[10:13]
	v_mfma_f32_16x16x32_bf16 v[6:9], v[208:211], v[160:163], v[6:9]
	v_mfma_f32_16x16x32_bf16 v[2:5], v[212:215], v[160:163], v[2:5]
	s_waitcnt lgkmcnt(0)
	v_mfma_f32_16x16x32_bf16 v[66:69], v[188:191], v[164:167], v[66:69]
	v_mfma_f32_16x16x32_bf16 v[70:73], v[192:195], v[164:167], v[70:73]
	v_mfma_f32_16x16x32_bf16 v[82:85], v[208:211], v[164:167], v[82:85]
	v_mfma_f32_16x16x32_bf16 v[88:91], v[212:215], v[164:167], v[88:91]
	v_mfma_f32_16x16x32_bf16 v[92:95], v[188:191], v[168:171], v[92:95]
	v_mfma_f32_16x16x32_bf16 v[96:99], v[192:195], v[168:171], v[96:99]
	v_mfma_f32_16x16x32_bf16 v[100:103], v[208:211], v[168:171], v[100:103]
	v_mfma_f32_16x16x32_bf16 v[106:109], v[212:215], v[168:171], v[106:109]
	v_mfma_f32_16x16x32_bf16 v[110:113], v[188:191], v[174:177], v[110:113]
	v_mfma_f32_16x16x32_bf16 v[114:117], v[192:195], v[174:177], v[114:117]
	v_mfma_f32_16x16x32_bf16 v[118:121], v[208:211], v[174:177], v[118:121]
	v_mfma_f32_16x16x32_bf16 v[122:125], v[212:215], v[174:177], v[122:125]
	v_mfma_f32_16x16x32_bf16 v[126:129], v[188:191], v[182:185], v[126:129]
	v_mfma_f32_16x16x32_bf16 v[136:139], v[192:195], v[182:185], v[136:139]
	v_mfma_f32_16x16x32_bf16 v[140:143], v[208:211], v[182:185], v[140:143]
	v_mfma_f32_16x16x32_bf16 v[144:147], v[212:215], v[182:185], v[144:147]
	s_setprio 0
	ds_read_b128 v[148:151], v80 offset:0
	ds_read_b128 v[152:155], v80 offset:2048
	ds_read_b128 v[156:159], v80 offset:4096
	ds_read_b128 v[160:163], v80 offset:6144
	ds_read_b128 v[188:191], v81 offset:49152
	ds_read_b128 v[192:195], v81 offset:51200
	ds_read_b128 v[208:211], v81 offset:53248
	ds_read_b128 v[212:215], v81 offset:55296
	ds_read_b128 v[164:167], v80 offset:16384
	ds_read_b128 v[168:171], v80 offset:18432
	ds_read_b128 v[174:177], v80 offset:20480
	ds_read_b128 v[182:185], v80 offset:22528
	s_waitcnt lgkmcnt(0)
	s_barrier
	s_add_i32 m0, s58, 0x0
	s_nop 0
	global_load_lds_dwordx4 v74, s[50:51]
	s_add_i32 m0, s58, 0x1000
	s_nop 0
	global_load_lds_dwordx4 v75, s[50:51]
	s_add_i32 m0, s58, 0x2000
	s_nop 0
	global_load_lds_dwordx4 v76, s[50:51]
	s_add_i32 m0, s58, 0x3000
	s_nop 0
	global_load_lds_dwordx4 v77, s[50:51]
	s_add_i32 m0, s58, 0x4000
	s_nop 0
	global_load_lds_dwordx4 v74, s[52:53]
	s_add_i32 m0, s58, 0x5000
	s_nop 0
	global_load_lds_dwordx4 v75, s[52:53]
	s_add_i32 m0, s58, 0x6000
	s_nop 0
	global_load_lds_dwordx4 v76, s[52:53]
	s_add_i32 m0, s58, 0x7000
	s_nop 0
	global_load_lds_dwordx4 v77, s[52:53]
	s_add_u32 s50, s50, 0x80
	s_addc_u32 s51, s51, 0
	s_add_u32 s52, s52, 0x80
	s_addc_u32 s53, s53, 0
	s_setprio 1
	v_mfma_f32_16x16x32_bf16 v[62:65], v[188:191], v[148:151], v[62:65]
	v_mfma_f32_16x16x32_bf16 v[58:61], v[192:195], v[148:151], v[58:61]
	v_mfma_f32_16x16x32_bf16 v[54:57], v[208:211], v[148:151], v[54:57]
	v_mfma_f32_16x16x32_bf16 v[50:53], v[212:215], v[148:151], v[50:53]
	v_mfma_f32_16x16x32_bf16 v[46:49], v[188:191], v[152:155], v[46:49]
	v_mfma_f32_16x16x32_bf16 v[42:45], v[192:195], v[152:155], v[42:45]
	v_mfma_f32_16x16x32_bf16 v[38:41], v[208:211], v[152:155], v[38:41]
	v_mfma_f32_16x16x32_bf16 v[34:37], v[212:215], v[152:155], v[34:37]
	v_mfma_f32_16x16x32_bf16 v[30:33], v[188:191], v[156:159], v[30:33]
	v_mfma_f32_16x16x32_bf16 v[26:29], v[192:195], v[156:159], v[26:29]
	v_mfma_f32_16x16x32_bf16 v[22:25], v[208:211], v[156:159], v[22:25]
	v_mfma_f32_16x16x32_bf16 v[18:21], v[212:215], v[156:159], v[18:21]
	v_mfma_f32_16x16x32_bf16 v[14:17], v[188:191], v[160:163], v[14:17]
	v_mfma_f32_16x16x32_bf16 v[10:13], v[192:195], v[160:163], v[10:13]
	v_mfma_f32_16x16x32_bf16 v[6:9], v[208:211], v[160:163], v[6:9]
	v_mfma_f32_16x16x32_bf16 v[2:5], v[212:215], v[160:163], v[2:5]
	v_mfma_f32_16x16x32_bf16 v[66:69], v[188:191], v[164:167], v[66:69]
	v_mfma_f32_16x16x32_bf16 v[70:73], v[192:195], v[164:167], v[70:73]
	v_mfma_f32_16x16x32_bf16 v[82:85], v[208:211], v[164:167], v[82:85]
	v_mfma_f32_16x16x32_bf16 v[88:91], v[212:215], v[164:167], v[88:91]
	v_mfma_f32_16x16x32_bf16 v[92:95], v[188:191], v[168:171], v[92:95]
	v_mfma_f32_16x16x32_bf16 v[96:99], v[192:195], v[168:171], v[96:99]
	v_mfma_f32_16x16x32_bf16 v[100:103], v[208:211], v[168:171], v[100:103]
	v_mfma_f32_16x16x32_bf16 v[106:109], v[212:215], v[168:171], v[106:109]
	v_mfma_f32_16x16x32_bf16 v[110:113], v[188:191], v[174:177], v[110:113]
	v_mfma_f32_16x16x32_bf16 v[114:117], v[192:195], v[174:177], v[114:117]
	v_mfma_f32_16x16x32_bf16 v[118:121], v[208:211], v[174:177], v[118:121]
	v_mfma_f32_16x16x32_bf16 v[122:125], v[212:215], v[174:177], v[122:125]
	v_mfma_f32_16x16x32_bf16 v[126:129], v[188:191], v[182:185], v[126:129]
	v_mfma_f32_16x16x32_bf16 v[136:139], v[192:195], v[182:185], v[136:139]
	v_mfma_f32_16x16x32_bf16 v[140:143], v[208:211], v[182:185], v[140:143]
	v_mfma_f32_16x16x32_bf16 v[144:147], v[212:215], v[182:185], v[144:147]
	s_setprio 0
	s_add_i32 s59, s59, -1
	s_cmp_lg_u32 s59, 0
	s_cbranch_scc1 .Lg2_k
	s_waitcnt vmcnt(0)
	s_barrier
	s_add_i32 m0, s58, 0xc000
	s_nop 0
	global_load_lds_dwordx4 v74, s[56:57]
	s_add_i32 m0, s58, 0xd000
	s_nop 0
	global_load_lds_dwordx4 v75, s[56:57]
	s_add_i32 m0, s58, 0xe000
	s_nop 0
	global_load_lds_dwordx4 v76, s[56:57]
	s_add_i32 m0, s58, 0xf000
	s_nop 0
	global_load_lds_dwordx4 v77, s[56:57]
	s_add_u32 s56, s56, 0x80
	s_addc_u32 s57, s57, 0
	ds_read_b128 v[148:151], v78 offset:0
	ds_read_b128 v[152:155], v78 offset:2048
	ds_read_b128 v[156:159], v78 offset:4096
	ds_read_b128 v[160:163], v78 offset:6144
	ds_read_b128 v[188:191], v79 offset:32768
	ds_read_b128 v[192:195], v79 offset:34816
	ds_read_b128 v[208:211], v79 offset:36864
	ds_read_b128 v[212:215], v79 offset:38912
	ds_read_b128 v[164:167], v78 offset:16384
	ds_read_b128 v[168:171], v78 offset:18432
	ds_read_b128 v[174:177], v78 offset:20480
	ds_read_b128 v[182:185], v78 offset:22528
	s_setprio 1
	s_waitcnt lgkmcnt(4)
	v_mfma_f32_16x16x32_bf16 v[62:65], v[188:191], v[148:151], v[62:65]
	v_mfma_f32_16x16x32_bf16 v[58:61], v[192:195], v[148:151], v[58:61]
	v_mfma_f32_16x16x32_bf16 v[54:57], v[208:211], v[148:151], v[54:57]
	v_mfma_f32_16x16x32_bf16 v[50:53], v[212:215], v[148:151], v[50:53]
	v_mfma_f32_16x16x32_bf16 v[46:49], v[188:191], v[152:155], v[46:49]
	v_mfma_f32_16x16x32_bf16 v[42:45], v[192:195], v[152:155], v[42:45]
	v_mfma_f32_16x16x32_bf16 v[38:41], v[208:211], v[152:155], v[38:41]
	v_mfma_f32_16x16x32_bf16 v[34:37], v[212:215], v[152:155], v[34:37]
	v_mfma_f32_16x16x32_bf16 v[30:33], v[188:191], v[156:159], v[30:33]
	v_mfma_f32_16x16x32_bf16 v[26:29], v[192:195], v[156:159], v[26:29]
	v_mfma_f32_16x16x32_bf16 v[22:25], v[208:211], v[156:159], v[22:25]
	v_mfma_f32_16x16x32_bf16 v[18:21], v[212:215], v[156:159], v[18:21]
	v_mfma_f32_16x16x32_bf16 v[14:17], v[188:191], v[160:163], v[14:17]
	v_mfma_f32_16x16x32_bf16 v[10:13], v[192:195], v[160:163], v[10:13]
	v_mfma_f32_16x16x32_bf16 v[6:9], v[208:211], v[160:163], v[6:9]
	v_mfma_f32_16x16x32_bf16 v[2:5], v[212:215], v[160:163], v[2:5]
	s_waitcnt lgkmcnt(0)
	v_mfma_f32_16x16x32_bf16 v[66:69], v[188:191], v[164:167], v[66:69]
	v_mfma_f32_16x16x32_bf16 v[70:73], v[192:195], v[164:167], v[70:73]
	v_mfma_f32_16x16x32_bf16 v[82:85], v[208:211], v[164:167], v[82:85]
	v_mfma_f32_16x16x32_bf16 v[88:91], v[212:215], v[164:167], v[88:91]
	v_mfma_f32_16x16x32_bf16 v[92:95], v[188:191], v[168:171], v[92:95]
	v_mfma_f32_16x16x32_bf16 v[96:99], v[192:195], v[168:171], v[96:99]
	v_mfma_f32_16x16x32_bf16 v[100:103], v[208:211], v[168:171], v[100:103]
	v_mfma_f32_16x16x32_bf16 v[106:109], v[212:215], v[168:171], v[106:109]
	v_mfma_f32_16x16x32_bf16 v[110:113], v[188:191], v[174:177], v[110:113]
	v_mfma_f32_16x16x32_bf16 v[114:117], v[192:195], v[174:177], v[114:117]
	v_mfma_f32_16x16x32_bf16 v[118:121], v[208:211], v[174:177], v[118:121]
	v_mfma_f32_16x16x32_bf16 v[122:125], v[212:215], v[174:177], v[122:125]
	v_mfma_f32_16x16x32_bf16 v[126:129], v[188:191], v[182:185], v[126:129]
	v_mfma_f32_16x16x32_bf16 v[136:139], v[192:195], v[182:185], v[136:139]
	v_mfma_f32_16x16x32_bf16 v[140:143], v[208:211], v[182:185], v[140:143]
	v_mfma_f32_16x16x32_bf16 v[144:147], v[212:215], v[182:185], v[144:147]
	s_setprio 0
	ds_read_b128 v[148:151], v80 offset:0
	ds_read_b128 v[152:155], v80 offset:2048
	ds_read_b128 v[156:159], v80 offset:4096
	ds_read_b128 v[160:163], v80 offset:6144
	ds_read_b128 v[188:191], v81 offset:32768
	ds_read_b128 v[192:195], v81 offset:34816
	ds_read_b128 v[208:211], v81 offset:36864
	ds_read_b128 v[212:215], v81 offset:38912
	ds_read_b128 v[164:167], v80 offset:16384
	ds_read_b128 v[168:171], v80 offset:18432
	ds_read_b128 v[174:177], v80 offset:20480
	ds_read_b128 v[182:185], v80 offset:22528
	s_waitcnt lgkmcnt(0)
	s_barrier
	s_add_i32 m0, s58, 0x0
	s_nop 0
	global_load_lds_dwordx4 v74, s[50:51]
	s_add_i32 m0, s58, 0x1000
	s_nop 0
	global_load_lds_dwordx4 v75, s[50:51]
	s_add_i32 m0, s58, 0x2000
	s_nop 0
	global_load_lds_dwordx4 v76, s[50:51]
	s_add_i32 m0, s58, 0x3000
	s_nop 0
	global_load_lds_dwordx4 v77, s[50:51]
	s_add_i32 m0, s58, 0x4000
	s_nop 0
	global_load_lds_dwordx4 v74, s[52:53]
	s_add_i32 m0, s58, 0x5000
	s_nop 0
	global_load_lds_dwordx4 v75, s[52:53]
	s_add_i32 m0, s58, 0x6000
	s_nop 0
	global_load_lds_dwordx4 v76, s[52:53]
	s_add_i32 m0, s58, 0x7000
	s_nop 0
	global_load_lds_dwordx4 v77, s[52:53]
	s_add_u32 s50, s50, 0x80
	s_addc_u32 s51, s51, 0
	s_add_u32 s52, s52, 0x80
	s_addc_u32 s53, s53, 0
	s_setprio 1
	v_mfma_f32_16x16x32_bf16 v[62:65], v[188:191], v[148:151], v[62:65]
	v_mfma_f32_16x16x32_bf16 v[58:61], v[192:195], v[148:151], v[58:61]
	v_mfma_f32_16x16x32_bf16 v[54:57], v[208:211], v[148:151], v[54:57]
	v_mfma_f32_16x16x32_bf16 v[50:53], v[212:215], v[148:151], v[50:53]
	v_mfma_f32_16x16x32_bf16 v[46:49], v[188:191], v[152:155], v[46:49]
	v_mfma_f32_16x16x32_bf16 v[42:45], v[192:195], v[152:155], v[42:45]
	v_mfma_f32_16x16x32_bf16 v[38:41], v[208:211], v[152:155], v[38:41]
	v_mfma_f32_16x16x32_bf16 v[34:37], v[212:215], v[152:155], v[34:37]
	v_mfma_f32_16x16x32_bf16 v[30:33], v[188:191], v[156:159], v[30:33]
	v_mfma_f32_16x16x32_bf16 v[26:29], v[192:195], v[156:159], v[26:29]
	v_mfma_f32_16x16x32_bf16 v[22:25], v[208:211], v[156:159], v[22:25]
	v_mfma_f32_16x16x32_bf16 v[18:21], v[212:215], v[156:159], v[18:21]
	v_mfma_f32_16x16x32_bf16 v[14:17], v[188:191], v[160:163], v[14:17]
	v_mfma_f32_16x16x32_bf16 v[10:13], v[192:195], v[160:163], v[10:13]
	v_mfma_f32_16x16x32_bf16 v[6:9], v[208:211], v[160:163], v[6:9]
	v_mfma_f32_16x16x32_bf16 v[2:5], v[212:215], v[160:163], v[2:5]
	v_mfma_f32_16x16x32_bf16 v[66:69], v[188:191], v[164:167], v[66:69]
	v_mfma_f32_16x16x32_bf16 v[70:73], v[192:195], v[164:167], v[70:73]
	v_mfma_f32_16x16x32_bf16 v[82:85], v[208:211], v[164:167], v[82:85]
	v_mfma_f32_16x16x32_bf16 v[88:91], v[212:215], v[164:167], v[88:91]
	v_mfma_f32_16x16x32_bf16 v[92:95], v[188:191], v[168:171], v[92:95]
	v_mfma_f32_16x16x32_bf16 v[96:99], v[192:195], v[168:171], v[96:99]
	v_mfma_f32_16x16x32_bf16 v[100:103], v[208:211], v[168:171], v[100:103]
	v_mfma_f32_16x16x32_bf16 v[106:109], v[212:215], v[168:171], v[106:109]
	v_mfma_f32_16x16x32_bf16 v[110:113], v[188:191], v[174:177], v[110:113]
	v_mfma_f32_16x16x32_bf16 v[114:117], v[192:195], v[174:177], v[114:117]
	v_mfma_f32_16x16x32_bf16 v[118:121], v[208:211], v[174:177], v[118:121]
	v_mfma_f32_16x16x32_bf16 v[122:125], v[212:215], v[174:177], v[122:125]
	v_mfma_f32_16x16x32_bf16 v[126:129], v[188:191], v[182:185], v[126:129]
	v_mfma_f32_16x16x32_bf16 v[136:139], v[192:195], v[182:185], v[136:139]
	v_mfma_f32_16x16x32_bf16 v[140:143], v[208:211], v[182:185], v[140:143]
	v_mfma_f32_16x16x32_bf16 v[144:147], v[212:215], v[182:185], v[144:147]
	s_setprio 0
	s_waitcnt vmcnt(0)
	s_barrier
	ds_read_b128 v[148:151], v78 offset:0
	ds_read_b128 v[152:155], v78 offset:2048
	ds_read_b128 v[156:159], v78 offset:4096
	ds_read_b128 v[160:163], v78 offset:6144
	ds_read_b128 v[188:191], v79 offset:49152
	ds_read_b128 v[192:195], v79 offset:51200
	ds_read_b128 v[208:211], v79 offset:53248
	ds_read_b128 v[212:215], v79 offset:55296
	ds_read_b128 v[164:167], v78 offset:16384
	ds_read_b128 v[168:171], v78 offset:18432
	ds_read_b128 v[174:177], v78 offset:20480
	ds_read_b128 v[182:185], v78 offset:22528
	s_setprio 1
	s_waitcnt lgkmcnt(4)
	v_mfma_f32_16x16x32_bf16 v[62:65], v[188:191], v[148:151], v[62:65]
	v_mfma_f32_16x16x32_bf16 v[58:61], v[192:195], v[148:151], v[58:61]
	v_mfma_f32_16x16x32_bf16 v[54:57], v[208:211], v[148:151], v[54:57]
	v_mfma_f32_16x16x32_bf16 v[50:53], v[212:215], v[148:151], v[50:53]
	v_mfma_f32_16x16x32_bf16 v[46:49], v[188:191], v[152:155], v[46:49]
	v_mfma_f32_16x16x32_bf16 v[42:45], v[192:195], v[152:155], v[42:45]
	v_mfma_f32_16x16x32_bf16 v[38:41], v[208:211], v[152:155], v[38:41]
	v_mfma_f32_16x16x32_bf16 v[34:37], v[212:215], v[152:155], v[34:37]
	v_mfma_f32_16x16x32_bf16 v[30:33], v[188:191], v[156:159], v[30:33]
	v_mfma_f32_16x16x32_bf16 v[26:29], v[192:195], v[156:159], v[26:29]
	v_mfma_f32_16x16x32_bf16 v[22:25], v[208:211], v[156:159], v[22:25]
	v_mfma_f32_16x16x32_bf16 v[18:21], v[212:215], v[156:159], v[18:21]
	v_mfma_f32_16x16x32_bf16 v[14:17], v[188:191], v[160:163], v[14:17]
	v_mfma_f32_16x16x32_bf16 v[10:13], v[192:195], v[160:163], v[10:13]
	v_mfma_f32_16x16x32_bf16 v[6:9], v[208:211], v[160:163], v[6:9]
	v_mfma_f32_16x16x32_bf16 v[2:5], v[212:215], v[160:163], v[2:5]
	s_waitcnt lgkmcnt(0)
	v_mfma_f32_16x16x32_bf16 v[66:69], v[188:191], v[164:167], v[66:69]
	v_mfma_f32_16x16x32_bf16 v[70:73], v[192:195], v[164:167], v[70:73]
	v_mfma_f32_16x16x32_bf16 v[82:85], v[208:211], v[164:167], v[82:85]
	v_mfma_f32_16x16x32_bf16 v[88:91], v[212:215], v[164:167], v[88:91]
	v_mfma_f32_16x16x32_bf16 v[92:95], v[188:191], v[168:171], v[92:95]
	v_mfma_f32_16x16x32_bf16 v[96:99], v[192:195], v[168:171], v[96:99]
	v_mfma_f32_16x16x32_bf16 v[100:103], v[208:211], v[168:171], v[100:103]
	v_mfma_f32_16x16x32_bf16 v[106:109], v[212:215], v[168:171], v[106:109]
	v_mfma_f32_16x16x32_bf16 v[110:113], v[188:191], v[174:177], v[110:113]
	v_mfma_f32_16x16x32_bf16 v[114:117], v[192:195], v[174:177], v[114:117]
	v_mfma_f32_16x16x32_bf16 v[118:121], v[208:211], v[174:177], v[118:121]
	v_mfma_f32_16x16x32_bf16 v[122:125], v[212:215], v[174:177], v[122:125]
	v_mfma_f32_16x16x32_bf16 v[126:129], v[188:191], v[182:185], v[126:129]
	v_mfma_f32_16x16x32_bf16 v[136:139], v[192:195], v[182:185], v[136:139]
	v_mfma_f32_16x16x32_bf16 v[140:143], v[208:211], v[182:185], v[140:143]
	v_mfma_f32_16x16x32_bf16 v[144:147], v[212:215], v[182:185], v[144:147]
	s_setprio 0
	ds_read_b128 v[148:151], v80 offset:0
	ds_read_b128 v[152:155], v80 offset:2048
	ds_read_b128 v[156:159], v80 offset:4096
	ds_read_b128 v[160:163], v80 offset:6144
	ds_read_b128 v[188:191], v81 offset:49152
	ds_read_b128 v[192:195], v81 offset:51200
	ds_read_b128 v[208:211], v81 offset:53248
	ds_read_b128 v[212:215], v81 offset:55296
	ds_read_b128 v[164:167], v80 offset:16384
	ds_read_b128 v[168:171], v80 offset:18432
	ds_read_b128 v[174:177], v80 offset:20480
	ds_read_b128 v[182:185], v80 offset:22528
	s_setprio 1
	s_waitcnt lgkmcnt(4)
	v_mfma_f32_16x16x32_bf16 v[62:65], v[188:191], v[148:151], v[62:65]
	v_mfma_f32_16x16x32_bf16 v[58:61], v[192:195], v[148:151], v[58:61]
	v_mfma_f32_16x16x32_bf16 v[54:57], v[208:211], v[148:151], v[54:57]
	v_mfma_f32_16x16x32_bf16 v[50:53], v[212:215], v[148:151], v[50:53]
	v_mfma_f32_16x16x32_bf16 v[46:49], v[188:191], v[152:155], v[46:49]
	v_mfma_f32_16x16x32_bf16 v[42:45], v[192:195], v[152:155], v[42:45]
	v_mfma_f32_16x16x32_bf16 v[38:41], v[208:211], v[152:155], v[38:41]
	v_mfma_f32_16x16x32_bf16 v[34:37], v[212:215], v[152:155], v[34:37]
	v_mfma_f32_16x16x32_bf16 v[30:33], v[188:191], v[156:159], v[30:33]
	v_mfma_f32_16x16x32_bf16 v[26:29], v[192:195], v[156:159], v[26:29]
	v_mfma_f32_16x16x32_bf16 v[22:25], v[208:211], v[156:159], v[22:25]
	v_mfma_f32_16x16x32_bf16 v[18:21], v[212:215], v[156:159], v[18:21]
	v_mfma_f32_16x16x32_bf16 v[14:17], v[188:191], v[160:163], v[14:17]
	v_mfma_f32_16x16x32_bf16 v[10:13], v[192:195], v[160:163], v[10:13]
	v_mfma_f32_16x16x32_bf16 v[6:9], v[208:211], v[160:163], v[6:9]
	v_mfma_f32_16x16x32_bf16 v[2:5], v[212:215], v[160:163], v[2:5]
	s_waitcnt lgkmcnt(0)
	v_mfma_f32_16x16x32_bf16 v[66:69], v[188:191], v[164:167], v[66:69]
	v_mfma_f32_16x16x32_bf16 v[70:73], v[192:195], v[164:167], v[70:73]
	v_mfma_f32_16x16x32_bf16 v[82:85], v[208:211], v[164:167], v[82:85]
	v_mfma_f32_16x16x32_bf16 v[88:91], v[212:215], v[164:167], v[88:91]
	v_mfma_f32_16x16x32_bf16 v[92:95], v[188:191], v[168:171], v[92:95]
	v_mfma_f32_16x16x32_bf16 v[96:99], v[192:195], v[168:171], v[96:99]
	v_mfma_f32_16x16x32_bf16 v[100:103], v[208:211], v[168:171], v[100:103]
	v_mfma_f32_16x16x32_bf16 v[106:109], v[212:215], v[168:171], v[106:109]
	v_mfma_f32_16x16x32_bf16 v[110:113], v[188:191], v[174:177], v[110:113]
	v_mfma_f32_16x16x32_bf16 v[114:117], v[192:195], v[174:177], v[114:117]
	v_mfma_f32_16x16x32_bf16 v[118:121], v[208:211], v[174:177], v[118:121]
	v_mfma_f32_16x16x32_bf16 v[122:125], v[212:215], v[174:177], v[122:125]
	v_mfma_f32_16x16x32_bf16 v[126:129], v[188:191], v[182:185], v[126:129]
	v_mfma_f32_16x16x32_bf16 v[136:139], v[192:195], v[182:185], v[136:139]
	v_mfma_f32_16x16x32_bf16 v[140:143], v[208:211], v[182:185], v[140:143]
	v_mfma_f32_16x16x32_bf16 v[144:147], v[212:215], v[182:185], v[144:147]
	s_setprio 0
	s_nop 7
	s_nop 7
	s_nop 7
	v_mov_b32_e32 v148, v66
	v_mov_b32_e32 v149, v67
	v_mov_b32_e32 v150, v68
	v_mov_b32_e32 v151, v69
	v_mov_b32_e32 v152, v70
	v_mov_b32_e32 v153, v71
	v_mov_b32_e32 v154, v72
	v_mov_b32_e32 v155, v73
	v_mov_b32_e32 v156, v82
	v_mov_b32_e32 v157, v83
	v_mov_b32_e32 v158, v84
	v_mov_b32_e32 v159, v85
	v_mov_b32_e32 v160, v88
	v_mov_b32_e32 v161, v89
	v_mov_b32_e32 v162, v90
	v_mov_b32_e32 v163, v91
	v_mov_b32_e32 v164, v92
	v_mov_b32_e32 v165, v93
	v_mov_b32_e32 v166, v94
	v_mov_b32_e32 v167, v95
	v_mov_b32_e32 v168, v96
	v_mov_b32_e32 v169, v97
	v_mov_b32_e32 v170, v98
	v_mov_b32_e32 v171, v99
	v_mov_b32_e32 v174, v100
	v_mov_b32_e32 v175, v101
	v_mov_b32_e32 v176, v102
	v_mov_b32_e32 v177, v103
	v_mov_b32_e32 v182, v106
	v_mov_b32_e32 v183, v107
	v_mov_b32_e32 v184, v108
	v_mov_b32_e32 v185, v109
	v_mov_b32_e32 v188, v110
	v_mov_b32_e32 v189, v111
	v_mov_b32_e32 v190, v112
	v_mov_b32_e32 v191, v113
	v_mov_b32_e32 v192, v114
	v_mov_b32_e32 v193, v115
	v_mov_b32_e32 v194, v116
	v_mov_b32_e32 v195, v117
	v_mov_b32_e32 v208, v118
	v_mov_b32_e32 v209, v119
	v_mov_b32_e32 v210, v120
	v_mov_b32_e32 v211, v121
	v_mov_b32_e32 v212, v122
	v_mov_b32_e32 v213, v123
	v_mov_b32_e32 v214, v124
	v_mov_b32_e32 v215, v125
	v_mov_b32_e32 v216, v126
	v_mov_b32_e32 v217, v127
	v_mov_b32_e32 v218, v128
	v_mov_b32_e32 v219, v129
	v_mov_b32_e32 v220, v136
	v_mov_b32_e32 v221, v137
	v_mov_b32_e32 v222, v138
	v_mov_b32_e32 v223, v139
	v_mov_b32_e32 v242, v140
	v_mov_b32_e32 v243, v141
	v_mov_b32_e32 v244, v142
	v_mov_b32_e32 v245, v143
	v_mov_b32_e32 v199, v144
	v_mov_b32_e32 v206, v145
	v_mov_b32_e32 v207, v146
	v_mov_b32_e32 v226, v147
	s_cmp_lt_u32 s37, 29
	s_cbranch_scc1 .Lg2_pl1
	s_load_dwordx2 s[98:99], s[84:85], 0x58
	v_bfe_u32 v149, v196, 6, 1
	v_bfe_u32 v150, v196, 4, 2
	v_lshlrev_b32_e32 v160, 8, v149
	v_lshl_or_b32 v160, v150, 4, v160
	v_readlane_b32 s2, v249, 52
	s_sub_i32 s3, s37, 29
	s_nop 0
	s_mul_i32 s2, s2, 0x3000
	s_lshl_b32 s20, s3, 9
	s_add_i32 s2, s2, s20
	s_branch .Lg2_pl3
.Lg2_pl1:
	s_cmp_lt_u32 s37, 8
	s_cbranch_scc1 .Lg2_pl2
	s_cmp_lt_u32 s37, 12
	s_cbranch_scc0 .Lg2_pl2
	s_load_dwordx2 s[98:99], s[84:85], 0x78
	v_bfe_u32 v150, v196, 4, 2
	v_lshlrev_b32_e32 v160, 4, v150
	v_readlane_b32 s2, v249, 52
	s_nop 1
	s_lshl_b32 s2, s2, 8
.Lg2_pl3:
	s_waitcnt lgkmcnt(0)
	s_add_u32 s98, s98, s2
	s_addc_u32 s99, s99, 0
	global_load_dwordx4 v[188:191], v160, s[98:99]
	global_load_dwordx4 v[192:195], v160, s[98:99] offset:64
	global_load_dwordx4 v[208:211], v160, s[98:99] offset:128
	global_load_dwordx4 v[212:215], v160, s[98:99] offset:192
.Lg2_pl2:
	s_add_i32 s48, s48, 1
	s_mov_b32 s65, 0
	v_readlane_b32 s2, v249, 0
	s_nop 0
	s_and_b32 s3, s2, 7
	s_lshr_b32 s2, s2, 3
	s_cmp_lt_u32 s2, 40
	s_cselect_b32 s38, 7, 6
	s_cmp_lt_u32 s48, s38
	s_cbranch_scc0 .Lg2_c1_extra
	s_lshl_b32 s20, s48, 6
	s_add_i32 s20, s20, s2
	s_cmp_ge_u32 s20, 0xd4
	s_cselect_b32 s21, 1, 0
	s_mul_i32 s60, s21, 0xd4
	s_sub_i32 s20, s20, s60
	s_lshr_b32 s61, s20, 2
	s_and_b32 s20, s20, 3
	s_lshl_b32 s21, s21, 3
	s_add_i32 s20, s20, s21
	s_lshl_b32 s20, s20, 3
	s_add_i32 s60, s20, s3
	s_add_i32 s64, s60, 32
	s_branch .Lg2_c1_have

.Lg2_nopf:
	s_cmp_lt_u32 s37, 29
	s_cbranch_scc1 .Lg2_c17
	s_load_dwordx2 s[92:93], s[84:85], 0x198
	v_lshrrev_b32_e32 v148, 7, v196
	v_and_b32_e32 v149, 15, v196
	v_lshl_or_b32 v148, v148, 6, v149
	v_mul_u32_u24_e32 v148, 0x1800, v148
	v_bfe_u32 v149, v196, 6, 1
	v_bfe_u32 v150, v196, 4, 2
	v_lshlrev_b32_e32 v160, 8, v149
	v_lshl_or_b32 v160, v150, 4, v160
	v_lshlrev_b32_e32 v149, 7, v149
	v_lshl_or_b32 v149, v150, 3, v149
	v_and_b32_e32 v150, 1, v150
	v_mul_u32_u24_e32 v150, 24, v150
	v_add3_u32 v156, v148, v149, v150
	v_add_u32_e32 v157, 0x18000, v156
	v_add_u32_e32 v158, 0x30000, v156
	v_add_u32_e32 v159, 0x48000, v156
	v_readlane_b32 s2, v249, 52
	s_sub_i32 s3, s37, 29
	s_mul_i32 s2, s2, 0x3000
	s_lshl_b32 s20, s3, 9
	s_add_i32 s2, s2, s20
	s_waitcnt lgkmcnt(0)
	s_lshl_b32 s20, s3, 8
	s_mul_i32 s2, s0, 0xc0000
	s_add_i32 s2, s2, s20
	s_add_u32 s96, s92, s2
	s_addc_u32 s97, s93, 0
	s_cmp_eq_u32 s65, 0
	s_cbranch_scc1 .Lg2_w0g
	s_waitcnt vmcnt(12)
	s_branch .Lg2_w1g

.Lg2_w1g:
	v_pk_add_f32 v[148:149], v[62:63], v[188:189]
	v_pk_add_f32 v[150:151], v[64:65], v[190:191]
	v_mul_f32_e32 v148, 0xbfb8aa3b, v148
	v_mul_f32_e32 v149, 0xbfb8aa3b, v149
	v_mul_f32_e32 v150, 0xbfb8aa3b, v150
	v_mul_f32_e32 v151, 0xbfb8aa3b, v151
	v_exp_f32_e32 v148, v148
	v_exp_f32_e32 v149, v149
	v_exp_f32_e32 v150, v150
	v_exp_f32_e32 v151, v151
	v_add_f32_e32 v148, 1.0, v148
	v_add_f32_e32 v149, 1.0, v149
	v_add_f32_e32 v150, 1.0, v150
	v_add_f32_e32 v151, 1.0, v151
	v_rcp_f32_e32 v148, v148
	v_rcp_f32_e32 v149, v149
	v_rcp_f32_e32 v150, v150
	v_rcp_f32_e32 v151, v151
	s_nop 0
	v_cvt_pk_bf16_f32 v164, v148, v149
	v_cvt_pk_bf16_f32 v165, v150, v151
	v_pk_add_f32 v[148:149], v[58:59], v[192:193]
	v_pk_add_f32 v[150:151], v[60:61], v[194:195]
	v_mul_f32_e32 v148, 0xbfb8aa3b, v148
	v_mul_f32_e32 v149, 0xbfb8aa3b, v149
	v_mul_f32_e32 v150, 0xbfb8aa3b, v150
	v_mul_f32_e32 v151, 0xbfb8aa3b, v151
	v_exp_f32_e32 v148, v148
	v_exp_f32_e32 v149, v149
	v_exp_f32_e32 v150, v150
	v_exp_f32_e32 v151, v151
	v_add_f32_e32 v148, 1.0, v148
	v_add_f32_e32 v149, 1.0, v149
	v_add_f32_e32 v150, 1.0, v150
	v_add_f32_e32 v151, 1.0, v151
	v_rcp_f32_e32 v148, v148
	v_rcp_f32_e32 v149, v149
	v_rcp_f32_e32 v150, v150
	v_rcp_f32_e32 v151, v151
	s_nop 0
	v_cvt_pk_bf16_f32 v166, v148, v149
	v_cvt_pk_bf16_f32 v167, v150, v151
	s_nop 1
	v_permlane16_swap_b32 v164, v166
	v_permlane16_swap_b32 v165, v167
	s_nop 1
	global_store_dwordx4 v156, v[164:167], s[96:97]
	v_pk_add_f32 v[148:149], v[54:55], v[208:209]
	v_pk_add_f32 v[150:151], v[56:57], v[210:211]
	v_mul_f32_e32 v148, 0xbfb8aa3b, v148
	v_mul_f32_e32 v149, 0xbfb8aa3b, v149
	v_mul_f32_e32 v150, 0xbfb8aa3b, v150
	v_mul_f32_e32 v151, 0xbfb8aa3b, v151
	v_exp_f32_e32 v148, v148
	v_exp_f32_e32 v149, v149
	v_exp_f32_e32 v150, v150
	v_exp_f32_e32 v151, v151
	v_add_f32_e32 v148, 1.0, v148
	v_add_f32_e32 v149, 1.0, v149
	v_add_f32_e32 v150, 1.0, v150
	v_add_f32_e32 v151, 1.0, v151
	v_rcp_f32_e32 v148, v148
	v_rcp_f32_e32 v149, v149
	v_rcp_f32_e32 v150, v150
	v_rcp_f32_e32 v151, v151
	s_nop 0
	v_cvt_pk_bf16_f32 v168, v148, v149
	v_cvt_pk_bf16_f32 v169, v150, v151
	v_pk_add_f32 v[148:149], v[50:51], v[212:213]
	v_pk_add_f32 v[150:151], v[52:53], v[214:215]
	v_mul_f32_e32 v148, 0xbfb8aa3b, v148
	v_mul_f32_e32 v149, 0xbfb8aa3b, v149
	v_mul_f32_e32 v150, 0xbfb8aa3b, v150
	v_mul_f32_e32 v151, 0xbfb8aa3b, v151
	v_exp_f32_e32 v148, v148
	v_exp_f32_e32 v149, v149
	v_exp_f32_e32 v150, v150
	v_exp_f32_e32 v151, v151
	v_add_f32_e32 v148, 1.0, v148
	v_add_f32_e32 v149, 1.0, v149
	v_add_f32_e32 v150, 1.0, v150
	v_add_f32_e32 v151, 1.0, v151
	v_rcp_f32_e32 v148, v148
	v_rcp_f32_e32 v149, v149
	v_rcp_f32_e32 v150, v150
	v_rcp_f32_e32 v151, v151
	s_nop 0
	v_cvt_pk_bf16_f32 v170, v148, v149
	v_cvt_pk_bf16_f32 v171, v150, v151
	s_nop 1
	v_permlane16_swap_b32 v168, v170
	v_permlane16_swap_b32 v169, v171
	s_nop 1
	global_store_dwordx4 v156, v[168:171], s[96:97] offset:64
	v_pk_add_f32 v[148:149], v[46:47], v[188:189]
	v_pk_add_f32 v[150:151], v[48:49], v[190:191]
	v_mul_f32_e32 v148, 0xbfb8aa3b, v148
	v_mul_f32_e32 v149, 0xbfb8aa3b, v149
	v_mul_f32_e32 v150, 0xbfb8aa3b, v150
	v_mul_f32_e32 v151, 0xbfb8aa3b, v151
	v_exp_f32_e32 v148, v148
	v_exp_f32_e32 v149, v149
	v_exp_f32_e32 v150, v150
	v_exp_f32_e32 v151, v151
	v_add_f32_e32 v148, 1.0, v148
	v_add_f32_e32 v149, 1.0, v149
	v_add_f32_e32 v150, 1.0, v150
	v_add_f32_e32 v151, 1.0, v151
	v_rcp_f32_e32 v148, v148
	v_rcp_f32_e32 v149, v149
	v_rcp_f32_e32 v150, v150
	v_rcp_f32_e32 v151, v151
	s_nop 0
	v_cvt_pk_bf16_f32 v164, v148, v149
	v_cvt_pk_bf16_f32 v165, v150, v151
	v_pk_add_f32 v[148:149], v[42:43], v[192:193]
	v_pk_add_f32 v[150:151], v[44:45], v[194:195]
	v_mul_f32_e32 v148, 0xbfb8aa3b, v148
	v_mul_f32_e32 v149, 0xbfb8aa3b, v149
	v_mul_f32_e32 v150, 0xbfb8aa3b, v150
	v_mul_f32_e32 v151, 0xbfb8aa3b, v151
	v_exp_f32_e32 v148, v148
	v_exp_f32_e32 v149, v149
	v_exp_f32_e32 v150, v150
	v_exp_f32_e32 v151, v151
	v_add_f32_e32 v148, 1.0, v148
	v_add_f32_e32 v149, 1.0, v149
	v_add_f32_e32 v150, 1.0, v150
	v_add_f32_e32 v151, 1.0, v151
	v_rcp_f32_e32 v148, v148
	v_rcp_f32_e32 v149, v149
	v_rcp_f32_e32 v150, v150
	v_rcp_f32_e32 v151, v151
	s_nop 0
	v_cvt_pk_bf16_f32 v166, v148, v149
	v_cvt_pk_bf16_f32 v167, v150, v151
	s_nop 1
	v_permlane16_swap_b32 v164, v166
	v_permlane16_swap_b32 v165, v167
	s_nop 1
	global_store_dwordx4 v157, v[164:167], s[96:97]
	v_pk_add_f32 v[148:149], v[38:39], v[208:209]
	v_pk_add_f32 v[150:151], v[40:41], v[210:211]
	v_mul_f32_e32 v148, 0xbfb8aa3b, v148
	v_mul_f32_e32 v149, 0xbfb8aa3b, v149
	v_mul_f32_e32 v150, 0xbfb8aa3b, v150
	v_mul_f32_e32 v151, 0xbfb8aa3b, v151
	v_exp_f32_e32 v148, v148
	v_exp_f32_e32 v149, v149
	v_exp_f32_e32 v150, v150
	v_exp_f32_e32 v151, v151
	v_add_f32_e32 v148, 1.0, v148
	v_add_f32_e32 v149, 1.0, v149
	v_add_f32_e32 v150, 1.0, v150
	v_add_f32_e32 v151, 1.0, v151
	v_rcp_f32_e32 v148, v148
	v_rcp_f32_e32 v149, v149
	v_rcp_f32_e32 v150, v150
	v_rcp_f32_e32 v151, v151
	s_nop 0
	v_cvt_pk_bf16_f32 v168, v148, v149
	v_cvt_pk_bf16_f32 v169, v150, v151
	v_pk_add_f32 v[148:149], v[34:35], v[212:213]
	v_pk_add_f32 v[150:151], v[36:37], v[214:215]
	v_mul_f32_e32 v148, 0xbfb8aa3b, v148
	v_mul_f32_e32 v149, 0xbfb8aa3b, v149
	v_mul_f32_e32 v150, 0xbfb8aa3b, v150
	v_mul_f32_e32 v151, 0xbfb8aa3b, v151
	v_exp_f32_e32 v148, v148
	v_exp_f32_e32 v149, v149
	v_exp_f32_e32 v150, v150
	v_exp_f32_e32 v151, v151
	v_add_f32_e32 v148, 1.0, v148
	v_add_f32_e32 v149, 1.0, v149
	v_add_f32_e32 v150, 1.0, v150
	v_add_f32_e32 v151, 1.0, v151
	v_rcp_f32_e32 v148, v148
	v_rcp_f32_e32 v149, v149
	v_rcp_f32_e32 v150, v150
	v_rcp_f32_e32 v151, v151
	s_nop 0
	v_cvt_pk_bf16_f32 v170, v148, v149
	v_cvt_pk_bf16_f32 v171, v150, v151
	s_nop 1
	v_permlane16_swap_b32 v168, v170
	v_permlane16_swap_b32 v169, v171
	s_nop 1
	global_store_dwordx4 v157, v[168:171], s[96:97] offset:64
	v_pk_add_f32 v[148:149], v[30:31], v[188:189]
	v_pk_add_f32 v[150:151], v[32:33], v[190:191]
	v_mul_f32_e32 v148, 0xbfb8aa3b, v148
	v_mul_f32_e32 v149, 0xbfb8aa3b, v149
	v_mul_f32_e32 v150, 0xbfb8aa3b, v150
	v_mul_f32_e32 v151, 0xbfb8aa3b, v151
	v_exp_f32_e32 v148, v148
	v_exp_f32_e32 v149, v149
	v_exp_f32_e32 v150, v150
	v_exp_f32_e32 v151, v151
	v_add_f32_e32 v148, 1.0, v148
	v_add_f32_e32 v149, 1.0, v149
	v_add_f32_e32 v150, 1.0, v150
	v_add_f32_e32 v151, 1.0, v151
	v_rcp_f32_e32 v148, v148
	v_rcp_f32_e32 v149, v149
	v_rcp_f32_e32 v150, v150
	v_rcp_f32_e32 v151, v151
	s_nop 0
	v_cvt_pk_bf16_f32 v164, v148, v149
	v_cvt_pk_bf16_f32 v165, v150, v151
	v_pk_add_f32 v[148:149], v[26:27], v[192:193]
	v_pk_add_f32 v[150:151], v[28:29], v[194:195]
	v_mul_f32_e32 v148, 0xbfb8aa3b, v148
	v_mul_f32_e32 v149, 0xbfb8aa3b, v149
	v_mul_f32_e32 v150, 0xbfb8aa3b, v150
	v_mul_f32_e32 v151, 0xbfb8aa3b, v151
	v_exp_f32_e32 v148, v148
	v_exp_f32_e32 v149, v149
	v_exp_f32_e32 v150, v150
	v_exp_f32_e32 v151, v151
	v_add_f32_e32 v148, 1.0, v148
	v_add_f32_e32 v149, 1.0, v149
	v_add_f32_e32 v150, 1.0, v150
	v_add_f32_e32 v151, 1.0, v151
	v_rcp_f32_e32 v148, v148
	v_rcp_f32_e32 v149, v149
	v_rcp_f32_e32 v150, v150
	v_rcp_f32_e32 v151, v151
	s_nop 0
	v_cvt_pk_bf16_f32 v166, v148, v149
	v_cvt_pk_bf16_f32 v167, v150, v151
	s_nop 1
	v_permlane16_swap_b32 v164, v166
	v_permlane16_swap_b32 v165, v167
	s_nop 1
	global_store_dwordx4 v158, v[164:167], s[96:97]
	v_pk_add_f32 v[148:149], v[22:23], v[208:209]
	v_pk_add_f32 v[150:151], v[24:25], v[210:211]
	v_mul_f32_e32 v148, 0xbfb8aa3b, v148
	v_mul_f32_e32 v149, 0xbfb8aa3b, v149
	v_mul_f32_e32 v150, 0xbfb8aa3b, v150
	v_mul_f32_e32 v151, 0xbfb8aa3b, v151
	v_exp_f32_e32 v148, v148
	v_exp_f32_e32 v149, v149
	v_exp_f32_e32 v150, v150
	v_exp_f32_e32 v151, v151
	v_add_f32_e32 v148, 1.0, v148
	v_add_f32_e32 v149, 1.0, v149
	v_add_f32_e32 v150, 1.0, v150
	v_add_f32_e32 v151, 1.0, v151
	v_rcp_f32_e32 v148, v148
	v_rcp_f32_e32 v149, v149
	v_rcp_f32_e32 v150, v150
	v_rcp_f32_e32 v151, v151
	s_nop 0
	v_cvt_pk_bf16_f32 v168, v148, v149
	v_cvt_pk_bf16_f32 v169, v150, v151
	v_pk_add_f32 v[148:149], v[18:19], v[212:213]
	v_pk_add_f32 v[150:151], v[20:21], v[214:215]
	v_mul_f32_e32 v148, 0xbfb8aa3b, v148
	v_mul_f32_e32 v149, 0xbfb8aa3b, v149
	v_mul_f32_e32 v150, 0xbfb8aa3b, v150
	v_mul_f32_e32 v151, 0xbfb8aa3b, v151
	v_exp_f32_e32 v148, v148
	v_exp_f32_e32 v149, v149
	v_exp_f32_e32 v150, v150
	v_exp_f32_e32 v151, v151
	v_add_f32_e32 v148, 1.0, v148
	v_add_f32_e32 v149, 1.0, v149
	v_add_f32_e32 v150, 1.0, v150
	v_add_f32_e32 v151, 1.0, v151
	v_rcp_f32_e32 v148, v148
	v_rcp_f32_e32 v149, v149
	v_rcp_f32_e32 v150, v150
	v_rcp_f32_e32 v151, v151
	s_nop 0
	v_cvt_pk_bf16_f32 v170, v148, v149
	v_cvt_pk_bf16_f32 v171, v150, v151
	s_nop 1
	v_permlane16_swap_b32 v168, v170
	v_permlane16_swap_b32 v169, v171
	s_nop 1
	global_store_dwordx4 v158, v[168:171], s[96:97] offset:64
	v_pk_add_f32 v[148:149], v[14:15], v[188:189]
	v_pk_add_f32 v[150:151], v[16:17], v[190:191]
	v_mul_f32_e32 v148, 0xbfb8aa3b, v148
	v_mul_f32_e32 v149, 0xbfb8aa3b, v149
	v_mul_f32_e32 v150, 0xbfb8aa3b, v150
	v_mul_f32_e32 v151, 0xbfb8aa3b, v151
	v_exp_f32_e32 v148, v148
	v_exp_f32_e32 v149, v149
	v_exp_f32_e32 v150, v150
	v_exp_f32_e32 v151, v151
	v_add_f32_e32 v148, 1.0, v148
	v_add_f32_e32 v149, 1.0, v149
	v_add_f32_e32 v150, 1.0, v150
	v_add_f32_e32 v151, 1.0, v151
	v_rcp_f32_e32 v148, v148
	v_rcp_f32_e32 v149, v149
	v_rcp_f32_e32 v150, v150
	v_rcp_f32_e32 v151, v151
	s_nop 0
	v_cvt_pk_bf16_f32 v164, v148, v149
	v_cvt_pk_bf16_f32 v165, v150, v151
	v_pk_add_f32 v[148:149], v[10:11], v[192:193]
	v_pk_add_f32 v[150:151], v[12:13], v[194:195]
	v_mul_f32_e32 v148, 0xbfb8aa3b, v148
	v_mul_f32_e32 v149, 0xbfb8aa3b, v149
	v_mul_f32_e32 v150, 0xbfb8aa3b, v150
	v_mul_f32_e32 v151, 0xbfb8aa3b, v151
	v_exp_f32_e32 v148, v148
	v_exp_f32_e32 v149, v149
	v_exp_f32_e32 v150, v150
	v_exp_f32_e32 v151, v151
	v_add_f32_e32 v148, 1.0, v148
	v_add_f32_e32 v149, 1.0, v149
	v_add_f32_e32 v150, 1.0, v150
	v_add_f32_e32 v151, 1.0, v151
	v_rcp_f32_e32 v148, v148
	v_rcp_f32_e32 v149, v149
	v_rcp_f32_e32 v150, v150
	v_rcp_f32_e32 v151, v151
	s_nop 0
	v_cvt_pk_bf16_f32 v166, v148, v149
	v_cvt_pk_bf16_f32 v167, v150, v151
	s_nop 1
	v_permlane16_swap_b32 v164, v166
	v_permlane16_swap_b32 v165, v167
	s_nop 1
	global_store_dwordx4 v159, v[164:167], s[96:97]
	v_pk_add_f32 v[148:149], v[6:7], v[208:209]
	v_pk_add_f32 v[150:151], v[8:9], v[210:211]
	v_mul_f32_e32 v148, 0xbfb8aa3b, v148
	v_mul_f32_e32 v149, 0xbfb8aa3b, v149
	v_mul_f32_e32 v150, 0xbfb8aa3b, v150
	v_mul_f32_e32 v151, 0xbfb8aa3b, v151
	v_exp_f32_e32 v148, v148
	v_exp_f32_e32 v149, v149
	v_exp_f32_e32 v150, v150
	v_exp_f32_e32 v151, v151
	v_add_f32_e32 v148, 1.0, v148
	v_add_f32_e32 v149, 1.0, v149
	v_add_f32_e32 v150, 1.0, v150
	v_add_f32_e32 v151, 1.0, v151
	v_rcp_f32_e32 v148, v148
	v_rcp_f32_e32 v149, v149
	v_rcp_f32_e32 v150, v150
	v_rcp_f32_e32 v151, v151
	s_nop 0
	v_cvt_pk_bf16_f32 v168, v148, v149
	v_cvt_pk_bf16_f32 v169, v150, v151
	v_pk_add_f32 v[148:149], v[2:3], v[212:213]
	v_pk_add_f32 v[150:151], v[4:5], v[214:215]
	v_mul_f32_e32 v148, 0xbfb8aa3b, v148
	v_mul_f32_e32 v149, 0xbfb8aa3b, v149
	v_mul_f32_e32 v150, 0xbfb8aa3b, v150
	v_mul_f32_e32 v151, 0xbfb8aa3b, v151
	v_exp_f32_e32 v148, v148
	v_exp_f32_e32 v149, v149
	v_exp_f32_e32 v150, v150
	v_exp_f32_e32 v151, v151
	v_add_f32_e32 v148, 1.0, v148
	v_add_f32_e32 v149, 1.0, v149
	v_add_f32_e32 v150, 1.0, v150
	v_add_f32_e32 v151, 1.0, v151
	v_rcp_f32_e32 v148, v148
	v_rcp_f32_e32 v149, v149
	v_rcp_f32_e32 v150, v150
	v_rcp_f32_e32 v151, v151
	s_nop 0
	v_cvt_pk_bf16_f32 v170, v148, v149
	v_cvt_pk_bf16_f32 v171, v150, v151
	s_nop 1
	v_permlane16_swap_b32 v168, v170
	v_permlane16_swap_b32 v169, v171
	s_nop 1
	global_store_dwordx4 v159, v[168:171], s[96:97] offset:64
	s_mul_i32 s2, s49, 0xc0000
	s_add_i32 s2, s2, s20
	s_add_u32 s96, s92, s2
	s_addc_u32 s97, s93, 0
	v_pk_add_f32 v[148:149], v[66:67], v[188:189]
	v_pk_add_f32 v[150:151], v[68:69], v[190:191]
	v_mul_f32_e32 v148, 0xbfb8aa3b, v148
	v_mul_f32_e32 v149, 0xbfb8aa3b, v149
	v_mul_f32_e32 v150, 0xbfb8aa3b, v150
	v_mul_f32_e32 v151, 0xbfb8aa3b, v151
	v_exp_f32_e32 v148, v148
	v_exp_f32_e32 v149, v149
	v_exp_f32_e32 v150, v150
	v_exp_f32_e32 v151, v151
	v_add_f32_e32 v148, 1.0, v148
	v_add_f32_e32 v149, 1.0, v149
	v_add_f32_e32 v150, 1.0, v150
	v_add_f32_e32 v151, 1.0, v151
	v_rcp_f32_e32 v148, v148
	v_rcp_f32_e32 v149, v149
	v_rcp_f32_e32 v150, v150
	v_rcp_f32_e32 v151, v151
	s_nop 0
	v_cvt_pk_bf16_f32 v164, v148, v149
	v_cvt_pk_bf16_f32 v165, v150, v151
	v_pk_add_f32 v[148:149], v[70:71], v[192:193]
	v_pk_add_f32 v[150:151], v[72:73], v[194:195]
	v_mul_f32_e32 v148, 0xbfb8aa3b, v148
	v_mul_f32_e32 v149, 0xbfb8aa3b, v149
	v_mul_f32_e32 v150, 0xbfb8aa3b, v150
	v_mul_f32_e32 v151, 0xbfb8aa3b, v151
	v_exp_f32_e32 v148, v148
	v_exp_f32_e32 v149, v149
	v_exp_f32_e32 v150, v150
	v_exp_f32_e32 v151, v151
	v_add_f32_e32 v148, 1.0, v148
	v_add_f32_e32 v149, 1.0, v149
	v_add_f32_e32 v150, 1.0, v150
	v_add_f32_e32 v151, 1.0, v151
	v_rcp_f32_e32 v148, v148
	v_rcp_f32_e32 v149, v149
	v_rcp_f32_e32 v150, v150
	v_rcp_f32_e32 v151, v151
	s_nop 0
	v_cvt_pk_bf16_f32 v166, v148, v149
	v_cvt_pk_bf16_f32 v167, v150, v151
	s_nop 1
	v_permlane16_swap_b32 v164, v166
	v_permlane16_swap_b32 v165, v167
	s_nop 1
	global_store_dwordx4 v156, v[164:167], s[96:97]
	v_pk_add_f32 v[148:149], v[82:83], v[208:209]
	v_pk_add_f32 v[150:151], v[84:85], v[210:211]
	v_mul_f32_e32 v148, 0xbfb8aa3b, v148
	v_mul_f32_e32 v149, 0xbfb8aa3b, v149
	v_mul_f32_e32 v150, 0xbfb8aa3b, v150
	v_mul_f32_e32 v151, 0xbfb8aa3b, v151
	v_exp_f32_e32 v148, v148
	v_exp_f32_e32 v149, v149
	v_exp_f32_e32 v150, v150
	v_exp_f32_e32 v151, v151
	v_add_f32_e32 v148, 1.0, v148
	v_add_f32_e32 v149, 1.0, v149
	v_add_f32_e32 v150, 1.0, v150
	v_add_f32_e32 v151, 1.0, v151
	v_rcp_f32_e32 v148, v148
	v_rcp_f32_e32 v149, v149
	v_rcp_f32_e32 v150, v150
	v_rcp_f32_e32 v151, v151
	s_nop 0
	v_cvt_pk_bf16_f32 v168, v148, v149
	v_cvt_pk_bf16_f32 v169, v150, v151
	v_pk_add_f32 v[148:149], v[88:89], v[212:213]
	v_pk_add_f32 v[150:151], v[90:91], v[214:215]
	v_mul_f32_e32 v148, 0xbfb8aa3b, v148
	v_mul_f32_e32 v149, 0xbfb8aa3b, v149
	v_mul_f32_e32 v150, 0xbfb8aa3b, v150
	v_mul_f32_e32 v151, 0xbfb8aa3b, v151
	v_exp_f32_e32 v148, v148
	v_exp_f32_e32 v149, v149
	v_exp_f32_e32 v150, v150
	v_exp_f32_e32 v151, v151
	v_add_f32_e32 v148, 1.0, v148
	v_add_f32_e32 v149, 1.0, v149
	v_add_f32_e32 v150, 1.0, v150
	v_add_f32_e32 v151, 1.0, v151
	v_rcp_f32_e32 v148, v148
	v_rcp_f32_e32 v149, v149
	v_rcp_f32_e32 v150, v150
	v_rcp_f32_e32 v151, v151
	s_nop 0
	v_cvt_pk_bf16_f32 v170, v148, v149
	v_cvt_pk_bf16_f32 v171, v150, v151
	s_nop 1
	v_permlane16_swap_b32 v168, v170
	v_permlane16_swap_b32 v169, v171
	s_nop 1
	global_store_dwordx4 v156, v[168:171], s[96:97] offset:64
	v_pk_add_f32 v[148:149], v[92:93], v[188:189]
	v_pk_add_f32 v[150:151], v[94:95], v[190:191]
	v_mul_f32_e32 v148, 0xbfb8aa3b, v148
	v_mul_f32_e32 v149, 0xbfb8aa3b, v149
	v_mul_f32_e32 v150, 0xbfb8aa3b, v150
	v_mul_f32_e32 v151, 0xbfb8aa3b, v151
	v_exp_f32_e32 v148, v148
	v_exp_f32_e32 v149, v149
	v_exp_f32_e32 v150, v150
	v_exp_f32_e32 v151, v151
	v_add_f32_e32 v148, 1.0, v148
	v_add_f32_e32 v149, 1.0, v149
	v_add_f32_e32 v150, 1.0, v150
	v_add_f32_e32 v151, 1.0, v151
	v_rcp_f32_e32 v148, v148
	v_rcp_f32_e32 v149, v149
	v_rcp_f32_e32 v150, v150
	v_rcp_f32_e32 v151, v151
	s_nop 0
	v_cvt_pk_bf16_f32 v164, v148, v149
	v_cvt_pk_bf16_f32 v165, v150, v151
	v_pk_add_f32 v[148:149], v[96:97], v[192:193]
	v_pk_add_f32 v[150:151], v[98:99], v[194:195]
	v_mul_f32_e32 v148, 0xbfb8aa3b, v148
	v_mul_f32_e32 v149, 0xbfb8aa3b, v149
	v_mul_f32_e32 v150, 0xbfb8aa3b, v150
	v_mul_f32_e32 v151, 0xbfb8aa3b, v151
	v_exp_f32_e32 v148, v148
	v_exp_f32_e32 v149, v149
	v_exp_f32_e32 v150, v150
	v_exp_f32_e32 v151, v151
	v_add_f32_e32 v148, 1.0, v148
	v_add_f32_e32 v149, 1.0, v149
	v_add_f32_e32 v150, 1.0, v150
	v_add_f32_e32 v151, 1.0, v151
	v_rcp_f32_e32 v148, v148
	v_rcp_f32_e32 v149, v149
	v_rcp_f32_e32 v150, v150
	v_rcp_f32_e32 v151, v151
	s_nop 0
	v_cvt_pk_bf16_f32 v166, v148, v149
	v_cvt_pk_bf16_f32 v167, v150, v151
	s_nop 1
	v_permlane16_swap_b32 v164, v166
	v_permlane16_swap_b32 v165, v167
	s_nop 1
	global_store_dwordx4 v157, v[164:167], s[96:97]
	v_pk_add_f32 v[148:149], v[100:101], v[208:209]
	v_pk_add_f32 v[150:151], v[102:103], v[210:211]
	v_mul_f32_e32 v148, 0xbfb8aa3b, v148
	v_mul_f32_e32 v149, 0xbfb8aa3b, v149
	v_mul_f32_e32 v150, 0xbfb8aa3b, v150
	v_mul_f32_e32 v151, 0xbfb8aa3b, v151
	v_exp_f32_e32 v148, v148
	v_exp_f32_e32 v149, v149
	v_exp_f32_e32 v150, v150
	v_exp_f32_e32 v151, v151
	v_add_f32_e32 v148, 1.0, v148
	v_add_f32_e32 v149, 1.0, v149
	v_add_f32_e32 v150, 1.0, v150
	v_add_f32_e32 v151, 1.0, v151
	v_rcp_f32_e32 v148, v148
	v_rcp_f32_e32 v149, v149
	v_rcp_f32_e32 v150, v150
	v_rcp_f32_e32 v151, v151
	s_nop 0
	v_cvt_pk_bf16_f32 v168, v148, v149
	v_cvt_pk_bf16_f32 v169, v150, v151
	v_pk_add_f32 v[148:149], v[106:107], v[212:213]
	v_pk_add_f32 v[150:151], v[108:109], v[214:215]
	v_mul_f32_e32 v148, 0xbfb8aa3b, v148
	v_mul_f32_e32 v149, 0xbfb8aa3b, v149
	v_mul_f32_e32 v150, 0xbfb8aa3b, v150
	v_mul_f32_e32 v151, 0xbfb8aa3b, v151
	v_exp_f32_e32 v148, v148
	v_exp_f32_e32 v149, v149
	v_exp_f32_e32 v150, v150
	v_exp_f32_e32 v151, v151
	v_add_f32_e32 v148, 1.0, v148
	v_add_f32_e32 v149, 1.0, v149
	v_add_f32_e32 v150, 1.0, v150
	v_add_f32_e32 v151, 1.0, v151
	v_rcp_f32_e32 v148, v148
	v_rcp_f32_e32 v149, v149
	v_rcp_f32_e32 v150, v150
	v_rcp_f32_e32 v151, v151
	s_nop 0
	v_cvt_pk_bf16_f32 v170, v148, v149
	v_cvt_pk_bf16_f32 v171, v150, v151
	s_nop 1
	v_permlane16_swap_b32 v168, v170
	v_permlane16_swap_b32 v169, v171
	s_nop 1
	global_store_dwordx4 v157, v[168:171], s[96:97] offset:64
	v_pk_add_f32 v[148:149], v[110:111], v[188:189]
	v_pk_add_f32 v[150:151], v[112:113], v[190:191]
	v_mul_f32_e32 v148, 0xbfb8aa3b, v148
	v_mul_f32_e32 v149, 0xbfb8aa3b, v149
	v_mul_f32_e32 v150, 0xbfb8aa3b, v150
	v_mul_f32_e32 v151, 0xbfb8aa3b, v151
	v_exp_f32_e32 v148, v148
	v_exp_f32_e32 v149, v149
	v_exp_f32_e32 v150, v150
	v_exp_f32_e32 v151, v151
	v_add_f32_e32 v148, 1.0, v148
	v_add_f32_e32 v149, 1.0, v149
	v_add_f32_e32 v150, 1.0, v150
	v_add_f32_e32 v151, 1.0, v151
	v_rcp_f32_e32 v148, v148
	v_rcp_f32_e32 v149, v149
	v_rcp_f32_e32 v150, v150
	v_rcp_f32_e32 v151, v151
	s_nop 0
	v_cvt_pk_bf16_f32 v164, v148, v149
	v_cvt_pk_bf16_f32 v165, v150, v151
	v_pk_add_f32 v[148:149], v[114:115], v[192:193]
	v_pk_add_f32 v[150:151], v[116:117], v[194:195]
	v_mul_f32_e32 v148, 0xbfb8aa3b, v148
	v_mul_f32_e32 v149, 0xbfb8aa3b, v149
	v_mul_f32_e32 v150, 0xbfb8aa3b, v150
	v_mul_f32_e32 v151, 0xbfb8aa3b, v151
	v_exp_f32_e32 v148, v148
	v_exp_f32_e32 v149, v149
	v_exp_f32_e32 v150, v150
	v_exp_f32_e32 v151, v151
	v_add_f32_e32 v148, 1.0, v148
	v_add_f32_e32 v149, 1.0, v149
	v_add_f32_e32 v150, 1.0, v150
	v_add_f32_e32 v151, 1.0, v151
	v_rcp_f32_e32 v148, v148
	v_rcp_f32_e32 v149, v149
	v_rcp_f32_e32 v150, v150
	v_rcp_f32_e32 v151, v151
	s_nop 0
	v_cvt_pk_bf16_f32 v166, v148, v149
	v_cvt_pk_bf16_f32 v167, v150, v151
	s_nop 1
	v_permlane16_swap_b32 v164, v166
	v_permlane16_swap_b32 v165, v167
	s_nop 1
	global_store_dwordx4 v158, v[164:167], s[96:97]
	v_pk_add_f32 v[148:149], v[118:119], v[208:209]
	v_pk_add_f32 v[150:151], v[120:121], v[210:211]
	v_mul_f32_e32 v148, 0xbfb8aa3b, v148
	v_mul_f32_e32 v149, 0xbfb8aa3b, v149
	v_mul_f32_e32 v150, 0xbfb8aa3b, v150
	v_mul_f32_e32 v151, 0xbfb8aa3b, v151
	v_exp_f32_e32 v148, v148
	v_exp_f32_e32 v149, v149
	v_exp_f32_e32 v150, v150
	v_exp_f32_e32 v151, v151
	v_add_f32_e32 v148, 1.0, v148
	v_add_f32_e32 v149, 1.0, v149
	v_add_f32_e32 v150, 1.0, v150
	v_add_f32_e32 v151, 1.0, v151
	v_rcp_f32_e32 v148, v148
	v_rcp_f32_e32 v149, v149
	v_rcp_f32_e32 v150, v150
	v_rcp_f32_e32 v151, v151
	s_nop 0
	v_cvt_pk_bf16_f32 v168, v148, v149
	v_cvt_pk_bf16_f32 v169, v150, v151
	v_pk_add_f32 v[148:149], v[122:123], v[212:213]
	v_pk_add_f32 v[150:151], v[124:125], v[214:215]
	v_mul_f32_e32 v148, 0xbfb8aa3b, v148
	v_mul_f32_e32 v149, 0xbfb8aa3b, v149
	v_mul_f32_e32 v150, 0xbfb8aa3b, v150
	v_mul_f32_e32 v151, 0xbfb8aa3b, v151
	v_exp_f32_e32 v148, v148
	v_exp_f32_e32 v149, v149
	v_exp_f32_e32 v150, v150
	v_exp_f32_e32 v151, v151
	v_add_f32_e32 v148, 1.0, v148
	v_add_f32_e32 v149, 1.0, v149
	v_add_f32_e32 v150, 1.0, v150
	v_add_f32_e32 v151, 1.0, v151
	v_rcp_f32_e32 v148, v148
	v_rcp_f32_e32 v149, v149
	v_rcp_f32_e32 v150, v150
	v_rcp_f32_e32 v151, v151
	s_nop 0
	v_cvt_pk_bf16_f32 v170, v148, v149
	v_cvt_pk_bf16_f32 v171, v150, v151
	s_nop 1
	v_permlane16_swap_b32 v168, v170
	v_permlane16_swap_b32 v169, v171
	s_nop 1
	global_store_dwordx4 v158, v[168:171], s[96:97] offset:64
	v_pk_add_f32 v[148:149], v[126:127], v[188:189]
	v_pk_add_f32 v[150:151], v[128:129], v[190:191]
	v_mul_f32_e32 v148, 0xbfb8aa3b, v148
	v_mul_f32_e32 v149, 0xbfb8aa3b, v149
	v_mul_f32_e32 v150, 0xbfb8aa3b, v150
	v_mul_f32_e32 v151, 0xbfb8aa3b, v151
	v_exp_f32_e32 v148, v148
	v_exp_f32_e32 v149, v149
	v_exp_f32_e32 v150, v150
	v_exp_f32_e32 v151, v151
	v_add_f32_e32 v148, 1.0, v148
	v_add_f32_e32 v149, 1.0, v149
	v_add_f32_e32 v150, 1.0, v150
	v_add_f32_e32 v151, 1.0, v151
	v_rcp_f32_e32 v148, v148
	v_rcp_f32_e32 v149, v149
	v_rcp_f32_e32 v150, v150
	v_rcp_f32_e32 v151, v151
	s_nop 0
	v_cvt_pk_bf16_f32 v164, v148, v149
	v_cvt_pk_bf16_f32 v165, v150, v151
	v_pk_add_f32 v[148:149], v[136:137], v[192:193]
	v_pk_add_f32 v[150:151], v[138:139], v[194:195]
	v_mul_f32_e32 v148, 0xbfb8aa3b, v148
	v_mul_f32_e32 v149, 0xbfb8aa3b, v149
	v_mul_f32_e32 v150, 0xbfb8aa3b, v150
	v_mul_f32_e32 v151, 0xbfb8aa3b, v151
	v_exp_f32_e32 v148, v148
	v_exp_f32_e32 v149, v149
	v_exp_f32_e32 v150, v150
	v_exp_f32_e32 v151, v151
	v_add_f32_e32 v148, 1.0, v148
	v_add_f32_e32 v149, 1.0, v149
	v_add_f32_e32 v150, 1.0, v150
	v_add_f32_e32 v151, 1.0, v151
	v_rcp_f32_e32 v148, v148
	v_rcp_f32_e32 v149, v149
	v_rcp_f32_e32 v150, v150
	v_rcp_f32_e32 v151, v151
	s_nop 0
	v_cvt_pk_bf16_f32 v166, v148, v149
	v_cvt_pk_bf16_f32 v167, v150, v151
	s_nop 1
	v_permlane16_swap_b32 v164, v166
	v_permlane16_swap_b32 v165, v167
	s_nop 1
	global_store_dwordx4 v159, v[164:167], s[96:97]
	v_pk_add_f32 v[148:149], v[140:141], v[208:209]
	v_pk_add_f32 v[150:151], v[142:143], v[210:211]
	v_mul_f32_e32 v148, 0xbfb8aa3b, v148
	v_mul_f32_e32 v149, 0xbfb8aa3b, v149
	v_mul_f32_e32 v150, 0xbfb8aa3b, v150
	v_mul_f32_e32 v151, 0xbfb8aa3b, v151
	v_exp_f32_e32 v148, v148
	v_exp_f32_e32 v149, v149
	v_exp_f32_e32 v150, v150
	v_exp_f32_e32 v151, v151
	v_add_f32_e32 v148, 1.0, v148
	v_add_f32_e32 v149, 1.0, v149
	v_add_f32_e32 v150, 1.0, v150
	v_add_f32_e32 v151, 1.0, v151
	v_rcp_f32_e32 v148, v148
	v_rcp_f32_e32 v149, v149
	v_rcp_f32_e32 v150, v150
	v_rcp_f32_e32 v151, v151
	s_nop 0
	v_cvt_pk_bf16_f32 v168, v148, v149
	v_cvt_pk_bf16_f32 v169, v150, v151
	v_pk_add_f32 v[148:149], v[144:145], v[212:213]
	v_pk_add_f32 v[150:151], v[146:147], v[214:215]
	v_mul_f32_e32 v148, 0xbfb8aa3b, v148
	v_mul_f32_e32 v149, 0xbfb8aa3b, v149
	v_mul_f32_e32 v150, 0xbfb8aa3b, v150
	v_mul_f32_e32 v151, 0xbfb8aa3b, v151
	v_exp_f32_e32 v148, v148
	v_exp_f32_e32 v149, v149
	v_exp_f32_e32 v150, v150
	v_exp_f32_e32 v151, v151
	v_add_f32_e32 v148, 1.0, v148
	v_add_f32_e32 v149, 1.0, v149
	v_add_f32_e32 v150, 1.0, v150
	v_add_f32_e32 v151, 1.0, v151
	v_rcp_f32_e32 v148, v148
	v_rcp_f32_e32 v149, v149
	v_rcp_f32_e32 v150, v150
	v_rcp_f32_e32 v151, v151
	s_nop 0
	v_cvt_pk_bf16_f32 v170, v148, v149
	v_cvt_pk_bf16_f32 v171, v150, v151
	s_nop 1
	v_permlane16_swap_b32 v168, v170
	v_permlane16_swap_b32 v169, v171
	s_nop 1
	global_store_dwordx4 v159, v[168:171], s[96:97] offset:64
	s_branch .Lg2_next

.Lg2_g8:
	s_cmp_lt_u32 s37, 8
	s_cbranch_scc1 .Lg2_g8b
	s_cmp_lt_u32 s37, 12
	s_cbranch_scc1 .Lg2_bq
	s_cmp_eq_u32 s37, 14
	s_cbranch_scc1 .Lg2_iq
	s_cmp_eq_u32 s37, 15
	s_cbranch_scc1 .Lg2_iq
	s_branch .Lg2_2p
.Lg2_bq:
	s_load_dwordx2 s[92:93], s[84:85], 0x150
	v_lshrrev_b32_e32 v148, 7, v196
	v_and_b32_e32 v149, 15, v196
	v_lshl_or_b32 v148, v148, 6, v149
	v_bfe_u32 v149, v196, 6, 1
	v_bfe_u32 v150, v196, 4, 2
	v_lshlrev_b32_e32 v148, 10, v148
	v_lshlrev_b32_e32 v149, 7, v149
	v_lshl_or_b32 v149, v150, 3, v149
	v_and_b32_e32 v150, 1, v150
	v_mul_u32_u24_e32 v150, 24, v150
	v_add3_u32 v156, v148, v149, v150
	v_add_u32_e32 v157, 0x4000, v156
	v_add_u32_e32 v158, 0x8000, v156
	v_add_u32_e32 v159, 0xc000, v156
	s_sub_i32 s3, s37, 8
	s_waitcnt lgkmcnt(0)
	s_cmp_eq_u32 s65, 0
	s_cbranch_scc1 .Lg2_w0q
	s_waitcnt vmcnt(12)
	s_branch .Lg2_w1q

.Lg2_w1q:
	s_lshl_b32 s2, s0, 17
	s_lshl_b32 s38, s3, 8
	s_add_i32 s2, s2, s38
	s_add_u32 s96, s92, s2
	s_addc_u32 s97, s93, 0
	v_pk_mul_f32 v[152:153], v[62:63], v[62:63]
	v_pk_fma_f32 v[152:153], v[64:65], v[64:65], v[152:153]
	v_pk_fma_f32 v[152:153], v[58:59], v[58:59], v[152:153]
	v_pk_fma_f32 v[152:153], v[60:61], v[60:61], v[152:153]
	v_pk_fma_f32 v[152:153], v[54:55], v[54:55], v[152:153]
	v_pk_fma_f32 v[152:153], v[56:57], v[56:57], v[152:153]
	v_pk_fma_f32 v[152:153], v[50:51], v[50:51], v[152:153]
	v_pk_fma_f32 v[152:153], v[52:53], v[52:53], v[152:153]
	v_add_f32_e32 v148, v152, v153
	v_mov_b32_e32 v149, v148
	s_nop 1
	v_permlane16_swap_b32 v148, v149
	s_nop 1
	v_add_f32_e32 v148, v148, v149
	v_mov_b32_e32 v149, v148
	s_nop 1
	v_permlane32_swap_b32 v148, v149
	s_nop 1
	v_add_f32_e32 v148, v148, v149
	v_mul_f32_e32 v148, 0x3c800000, v148
	v_add_f32_e32 v148, 0x358637bd, v148
	v_rsq_f32_e32 v148, v148
	s_nop 0
	v_pk_mul_f32 v[62:63], v[62:63], v[148:149] op_sel_hi:[1,0]
	v_pk_mul_f32 v[64:65], v[64:65], v[148:149] op_sel_hi:[1,0]
	v_pk_mul_f32 v[62:63], v[62:63], v[188:189]
	v_pk_mul_f32 v[64:65], v[64:65], v[190:191]
	v_pk_mul_f32 v[58:59], v[58:59], v[148:149] op_sel_hi:[1,0]
	v_pk_mul_f32 v[60:61], v[60:61], v[148:149] op_sel_hi:[1,0]
	v_pk_mul_f32 v[58:59], v[58:59], v[192:193]
	v_pk_mul_f32 v[60:61], v[60:61], v[194:195]
	v_pk_mul_f32 v[54:55], v[54:55], v[148:149] op_sel_hi:[1,0]
	v_pk_mul_f32 v[56:57], v[56:57], v[148:149] op_sel_hi:[1,0]
	v_pk_mul_f32 v[54:55], v[54:55], v[208:209]
	v_pk_mul_f32 v[56:57], v[56:57], v[210:211]
	v_pk_mul_f32 v[50:51], v[50:51], v[148:149] op_sel_hi:[1,0]
	v_pk_mul_f32 v[52:53], v[52:53], v[148:149] op_sel_hi:[1,0]
	v_pk_mul_f32 v[50:51], v[50:51], v[212:213]
	v_pk_mul_f32 v[52:53], v[52:53], v[214:215]
	v_cvt_pk_bf16_f32 v164, v62, v63
	v_cvt_pk_bf16_f32 v165, v64, v65
	v_cvt_pk_bf16_f32 v166, v58, v59
	v_cvt_pk_bf16_f32 v167, v60, v61
	s_nop 1
	v_permlane16_swap_b32 v164, v166
	v_permlane16_swap_b32 v165, v167
	s_nop 1
	global_store_dwordx4 v156, v[164:167], s[96:97]
	v_cvt_pk_bf16_f32 v168, v54, v55
	v_cvt_pk_bf16_f32 v169, v56, v57
	v_cvt_pk_bf16_f32 v170, v50, v51
	v_cvt_pk_bf16_f32 v171, v52, v53
	s_nop 1
	v_permlane16_swap_b32 v168, v170
	v_permlane16_swap_b32 v169, v171
	s_nop 1
	global_store_dwordx4 v156, v[168:171], s[96:97] offset:64
	v_pk_mul_f32 v[152:153], v[46:47], v[46:47]
	v_pk_fma_f32 v[152:153], v[48:49], v[48:49], v[152:153]
	v_pk_fma_f32 v[152:153], v[42:43], v[42:43], v[152:153]
	v_pk_fma_f32 v[152:153], v[44:45], v[44:45], v[152:153]
	v_pk_fma_f32 v[152:153], v[38:39], v[38:39], v[152:153]
	v_pk_fma_f32 v[152:153], v[40:41], v[40:41], v[152:153]
	v_pk_fma_f32 v[152:153], v[34:35], v[34:35], v[152:153]
	v_pk_fma_f32 v[152:153], v[36:37], v[36:37], v[152:153]
	v_add_f32_e32 v148, v152, v153
	v_mov_b32_e32 v149, v148
	s_nop 1
	v_permlane16_swap_b32 v148, v149
	s_nop 1
	v_add_f32_e32 v148, v148, v149
	v_mov_b32_e32 v149, v148
	s_nop 1
	v_permlane32_swap_b32 v148, v149
	s_nop 1
	v_add_f32_e32 v148, v148, v149
	v_mul_f32_e32 v148, 0x3c800000, v148
	v_add_f32_e32 v148, 0x358637bd, v148
	v_rsq_f32_e32 v148, v148
	s_nop 0
	v_pk_mul_f32 v[46:47], v[46:47], v[148:149] op_sel_hi:[1,0]
	v_pk_mul_f32 v[48:49], v[48:49], v[148:149] op_sel_hi:[1,0]
	v_pk_mul_f32 v[46:47], v[46:47], v[188:189]
	v_pk_mul_f32 v[48:49], v[48:49], v[190:191]
	v_pk_mul_f32 v[42:43], v[42:43], v[148:149] op_sel_hi:[1,0]
	v_pk_mul_f32 v[44:45], v[44:45], v[148:149] op_sel_hi:[1,0]
	v_pk_mul_f32 v[42:43], v[42:43], v[192:193]
	v_pk_mul_f32 v[44:45], v[44:45], v[194:195]
	v_pk_mul_f32 v[38:39], v[38:39], v[148:149] op_sel_hi:[1,0]
	v_pk_mul_f32 v[40:41], v[40:41], v[148:149] op_sel_hi:[1,0]
	v_pk_mul_f32 v[38:39], v[38:39], v[208:209]
	v_pk_mul_f32 v[40:41], v[40:41], v[210:211]
	v_pk_mul_f32 v[34:35], v[34:35], v[148:149] op_sel_hi:[1,0]
	v_pk_mul_f32 v[36:37], v[36:37], v[148:149] op_sel_hi:[1,0]
	v_pk_mul_f32 v[34:35], v[34:35], v[212:213]
	v_pk_mul_f32 v[36:37], v[36:37], v[214:215]
	v_cvt_pk_bf16_f32 v164, v46, v47
	v_cvt_pk_bf16_f32 v165, v48, v49
	v_cvt_pk_bf16_f32 v166, v42, v43
	v_cvt_pk_bf16_f32 v167, v44, v45
	s_nop 1
	v_permlane16_swap_b32 v164, v166
	v_permlane16_swap_b32 v165, v167
	s_nop 1
	global_store_dwordx4 v157, v[164:167], s[96:97]
	v_cvt_pk_bf16_f32 v168, v38, v39
	v_cvt_pk_bf16_f32 v169, v40, v41
	v_cvt_pk_bf16_f32 v170, v34, v35
	v_cvt_pk_bf16_f32 v171, v36, v37
	s_nop 1
	v_permlane16_swap_b32 v168, v170
	v_permlane16_swap_b32 v169, v171
	s_nop 1
	global_store_dwordx4 v157, v[168:171], s[96:97] offset:64
	v_pk_mul_f32 v[152:153], v[30:31], v[30:31]
	v_pk_fma_f32 v[152:153], v[32:33], v[32:33], v[152:153]
	v_pk_fma_f32 v[152:153], v[26:27], v[26:27], v[152:153]
	v_pk_fma_f32 v[152:153], v[28:29], v[28:29], v[152:153]
	v_pk_fma_f32 v[152:153], v[22:23], v[22:23], v[152:153]
	v_pk_fma_f32 v[152:153], v[24:25], v[24:25], v[152:153]
	v_pk_fma_f32 v[152:153], v[18:19], v[18:19], v[152:153]
	v_pk_fma_f32 v[152:153], v[20:21], v[20:21], v[152:153]
	v_add_f32_e32 v148, v152, v153
	v_mov_b32_e32 v149, v148
	s_nop 1
	v_permlane16_swap_b32 v148, v149
	s_nop 1
	v_add_f32_e32 v148, v148, v149
	v_mov_b32_e32 v149, v148
	s_nop 1
	v_permlane32_swap_b32 v148, v149
	s_nop 1
	v_add_f32_e32 v148, v148, v149
	v_mul_f32_e32 v148, 0x3c800000, v148
	v_add_f32_e32 v148, 0x358637bd, v148
	v_rsq_f32_e32 v148, v148
	s_nop 0
	v_pk_mul_f32 v[30:31], v[30:31], v[148:149] op_sel_hi:[1,0]
	v_pk_mul_f32 v[32:33], v[32:33], v[148:149] op_sel_hi:[1,0]
	v_pk_mul_f32 v[30:31], v[30:31], v[188:189]
	v_pk_mul_f32 v[32:33], v[32:33], v[190:191]
	v_pk_mul_f32 v[26:27], v[26:27], v[148:149] op_sel_hi:[1,0]
	v_pk_mul_f32 v[28:29], v[28:29], v[148:149] op_sel_hi:[1,0]
	v_pk_mul_f32 v[26:27], v[26:27], v[192:193]
	v_pk_mul_f32 v[28:29], v[28:29], v[194:195]
	v_pk_mul_f32 v[22:23], v[22:23], v[148:149] op_sel_hi:[1,0]
	v_pk_mul_f32 v[24:25], v[24:25], v[148:149] op_sel_hi:[1,0]
	v_pk_mul_f32 v[22:23], v[22:23], v[208:209]
	v_pk_mul_f32 v[24:25], v[24:25], v[210:211]
	v_pk_mul_f32 v[18:19], v[18:19], v[148:149] op_sel_hi:[1,0]
	v_pk_mul_f32 v[20:21], v[20:21], v[148:149] op_sel_hi:[1,0]
	v_pk_mul_f32 v[18:19], v[18:19], v[212:213]
	v_pk_mul_f32 v[20:21], v[20:21], v[214:215]
	v_cvt_pk_bf16_f32 v164, v30, v31
	v_cvt_pk_bf16_f32 v165, v32, v33
	v_cvt_pk_bf16_f32 v166, v26, v27
	v_cvt_pk_bf16_f32 v167, v28, v29
	s_nop 1
	v_permlane16_swap_b32 v164, v166
	v_permlane16_swap_b32 v165, v167
	s_nop 1
	global_store_dwordx4 v158, v[164:167], s[96:97]
	v_cvt_pk_bf16_f32 v168, v22, v23
	v_cvt_pk_bf16_f32 v169, v24, v25
	v_cvt_pk_bf16_f32 v170, v18, v19
	v_cvt_pk_bf16_f32 v171, v20, v21
	s_nop 1
	v_permlane16_swap_b32 v168, v170
	v_permlane16_swap_b32 v169, v171
	s_nop 1
	global_store_dwordx4 v158, v[168:171], s[96:97] offset:64
	v_pk_mul_f32 v[152:153], v[14:15], v[14:15]
	v_pk_fma_f32 v[152:153], v[16:17], v[16:17], v[152:153]
	v_pk_fma_f32 v[152:153], v[10:11], v[10:11], v[152:153]
	v_pk_fma_f32 v[152:153], v[12:13], v[12:13], v[152:153]
	v_pk_fma_f32 v[152:153], v[6:7], v[6:7], v[152:153]
	v_pk_fma_f32 v[152:153], v[8:9], v[8:9], v[152:153]
	v_pk_fma_f32 v[152:153], v[2:3], v[2:3], v[152:153]
	v_pk_fma_f32 v[152:153], v[4:5], v[4:5], v[152:153]
	v_add_f32_e32 v148, v152, v153
	v_mov_b32_e32 v149, v148
	s_nop 1
	v_permlane16_swap_b32 v148, v149
	s_nop 1
	v_add_f32_e32 v148, v148, v149
	v_mov_b32_e32 v149, v148
	s_nop 1
	v_permlane32_swap_b32 v148, v149
	s_nop 1
	v_add_f32_e32 v148, v148, v149
	v_mul_f32_e32 v148, 0x3c800000, v148
	v_add_f32_e32 v148, 0x358637bd, v148
	v_rsq_f32_e32 v148, v148
	s_nop 0
	v_pk_mul_f32 v[14:15], v[14:15], v[148:149] op_sel_hi:[1,0]
	v_pk_mul_f32 v[16:17], v[16:17], v[148:149] op_sel_hi:[1,0]
	v_pk_mul_f32 v[14:15], v[14:15], v[188:189]
	v_pk_mul_f32 v[16:17], v[16:17], v[190:191]
	v_pk_mul_f32 v[10:11], v[10:11], v[148:149] op_sel_hi:[1,0]
	v_pk_mul_f32 v[12:13], v[12:13], v[148:149] op_sel_hi:[1,0]
	v_pk_mul_f32 v[10:11], v[10:11], v[192:193]
	v_pk_mul_f32 v[12:13], v[12:13], v[194:195]
	v_pk_mul_f32 v[6:7], v[6:7], v[148:149] op_sel_hi:[1,0]
	v_pk_mul_f32 v[8:9], v[8:9], v[148:149] op_sel_hi:[1,0]
	v_pk_mul_f32 v[6:7], v[6:7], v[208:209]
	v_pk_mul_f32 v[8:9], v[8:9], v[210:211]
	v_pk_mul_f32 v[2:3], v[2:3], v[148:149] op_sel_hi:[1,0]
	v_pk_mul_f32 v[4:5], v[4:5], v[148:149] op_sel_hi:[1,0]
	v_pk_mul_f32 v[2:3], v[2:3], v[212:213]
	v_pk_mul_f32 v[4:5], v[4:5], v[214:215]
	v_cvt_pk_bf16_f32 v164, v14, v15
	v_cvt_pk_bf16_f32 v165, v16, v17
	v_cvt_pk_bf16_f32 v166, v10, v11
	v_cvt_pk_bf16_f32 v167, v12, v13
	s_nop 1
	v_permlane16_swap_b32 v164, v166
	v_permlane16_swap_b32 v165, v167
	s_nop 1
	global_store_dwordx4 v159, v[164:167], s[96:97]
	v_cvt_pk_bf16_f32 v168, v6, v7
	v_cvt_pk_bf16_f32 v169, v8, v9
	v_cvt_pk_bf16_f32 v170, v2, v3
	v_cvt_pk_bf16_f32 v171, v4, v5
	s_nop 1
	v_permlane16_swap_b32 v168, v170
	v_permlane16_swap_b32 v169, v171
	s_nop 1
	global_store_dwordx4 v159, v[168:171], s[96:97] offset:64
	s_lshl_b32 s2, s49, 17
	s_lshl_b32 s38, s3, 8
	s_add_i32 s2, s2, s38
	s_add_u32 s96, s92, s2
	s_addc_u32 s97, s93, 0
	v_pk_mul_f32 v[152:153], v[66:67], v[66:67]
	v_pk_fma_f32 v[152:153], v[68:69], v[68:69], v[152:153]
	v_pk_fma_f32 v[152:153], v[70:71], v[70:71], v[152:153]
	v_pk_fma_f32 v[152:153], v[72:73], v[72:73], v[152:153]
	v_pk_fma_f32 v[152:153], v[82:83], v[82:83], v[152:153]
	v_pk_fma_f32 v[152:153], v[84:85], v[84:85], v[152:153]
	v_pk_fma_f32 v[152:153], v[88:89], v[88:89], v[152:153]
	v_pk_fma_f32 v[152:153], v[90:91], v[90:91], v[152:153]
	v_add_f32_e32 v148, v152, v153
	v_mov_b32_e32 v149, v148
	s_nop 1
	v_permlane16_swap_b32 v148, v149
	s_nop 1
	v_add_f32_e32 v148, v148, v149
	v_mov_b32_e32 v149, v148
	s_nop 1
	v_permlane32_swap_b32 v148, v149
	s_nop 1
	v_add_f32_e32 v148, v148, v149
	v_mul_f32_e32 v148, 0x3c800000, v148
	v_add_f32_e32 v148, 0x358637bd, v148
	v_rsq_f32_e32 v148, v148
	s_nop 0
	v_pk_mul_f32 v[66:67], v[66:67], v[148:149] op_sel_hi:[1,0]
	v_pk_mul_f32 v[68:69], v[68:69], v[148:149] op_sel_hi:[1,0]
	v_pk_mul_f32 v[66:67], v[66:67], v[188:189]
	v_pk_mul_f32 v[68:69], v[68:69], v[190:191]
	v_pk_mul_f32 v[70:71], v[70:71], v[148:149] op_sel_hi:[1,0]
	v_pk_mul_f32 v[72:73], v[72:73], v[148:149] op_sel_hi:[1,0]
	v_pk_mul_f32 v[70:71], v[70:71], v[192:193]
	v_pk_mul_f32 v[72:73], v[72:73], v[194:195]
	v_pk_mul_f32 v[82:83], v[82:83], v[148:149] op_sel_hi:[1,0]
	v_pk_mul_f32 v[84:85], v[84:85], v[148:149] op_sel_hi:[1,0]
	v_pk_mul_f32 v[82:83], v[82:83], v[208:209]
	v_pk_mul_f32 v[84:85], v[84:85], v[210:211]
	v_pk_mul_f32 v[88:89], v[88:89], v[148:149] op_sel_hi:[1,0]
	v_pk_mul_f32 v[90:91], v[90:91], v[148:149] op_sel_hi:[1,0]
	v_pk_mul_f32 v[88:89], v[88:89], v[212:213]
	v_pk_mul_f32 v[90:91], v[90:91], v[214:215]
	v_cvt_pk_bf16_f32 v164, v66, v67
	v_cvt_pk_bf16_f32 v165, v68, v69
	v_cvt_pk_bf16_f32 v166, v70, v71
	v_cvt_pk_bf16_f32 v167, v72, v73
	s_nop 1
	v_permlane16_swap_b32 v164, v166
	v_permlane16_swap_b32 v165, v167
	s_nop 1
	global_store_dwordx4 v156, v[164:167], s[96:97]
	v_cvt_pk_bf16_f32 v168, v82, v83
	v_cvt_pk_bf16_f32 v169, v84, v85
	v_cvt_pk_bf16_f32 v170, v88, v89
	v_cvt_pk_bf16_f32 v171, v90, v91
	s_nop 1
	v_permlane16_swap_b32 v168, v170
	v_permlane16_swap_b32 v169, v171
	s_nop 1
	global_store_dwordx4 v156, v[168:171], s[96:97] offset:64
	v_pk_mul_f32 v[152:153], v[92:93], v[92:93]
	v_pk_fma_f32 v[152:153], v[94:95], v[94:95], v[152:153]
	v_pk_fma_f32 v[152:153], v[96:97], v[96:97], v[152:153]
	v_pk_fma_f32 v[152:153], v[98:99], v[98:99], v[152:153]
	v_pk_fma_f32 v[152:153], v[100:101], v[100:101], v[152:153]
	v_pk_fma_f32 v[152:153], v[102:103], v[102:103], v[152:153]
	v_pk_fma_f32 v[152:153], v[106:107], v[106:107], v[152:153]
	v_pk_fma_f32 v[152:153], v[108:109], v[108:109], v[152:153]
	v_add_f32_e32 v148, v152, v153
	v_mov_b32_e32 v149, v148
	s_nop 1
	v_permlane16_swap_b32 v148, v149
	s_nop 1
	v_add_f32_e32 v148, v148, v149
	v_mov_b32_e32 v149, v148
	s_nop 1
	v_permlane32_swap_b32 v148, v149
	s_nop 1
	v_add_f32_e32 v148, v148, v149
	v_mul_f32_e32 v148, 0x3c800000, v148
	v_add_f32_e32 v148, 0x358637bd, v148
	v_rsq_f32_e32 v148, v148
	s_nop 0
	v_pk_mul_f32 v[92:93], v[92:93], v[148:149] op_sel_hi:[1,0]
	v_pk_mul_f32 v[94:95], v[94:95], v[148:149] op_sel_hi:[1,0]
	v_pk_mul_f32 v[92:93], v[92:93], v[188:189]
	v_pk_mul_f32 v[94:95], v[94:95], v[190:191]
	v_pk_mul_f32 v[96:97], v[96:97], v[148:149] op_sel_hi:[1,0]
	v_pk_mul_f32 v[98:99], v[98:99], v[148:149] op_sel_hi:[1,0]
	v_pk_mul_f32 v[96:97], v[96:97], v[192:193]
	v_pk_mul_f32 v[98:99], v[98:99], v[194:195]
	v_pk_mul_f32 v[100:101], v[100:101], v[148:149] op_sel_hi:[1,0]
	v_pk_mul_f32 v[102:103], v[102:103], v[148:149] op_sel_hi:[1,0]
	v_pk_mul_f32 v[100:101], v[100:101], v[208:209]
	v_pk_mul_f32 v[102:103], v[102:103], v[210:211]
	v_pk_mul_f32 v[106:107], v[106:107], v[148:149] op_sel_hi:[1,0]
	v_pk_mul_f32 v[108:109], v[108:109], v[148:149] op_sel_hi:[1,0]
	v_pk_mul_f32 v[106:107], v[106:107], v[212:213]
	v_pk_mul_f32 v[108:109], v[108:109], v[214:215]
	v_cvt_pk_bf16_f32 v164, v92, v93
	v_cvt_pk_bf16_f32 v165, v94, v95
	v_cvt_pk_bf16_f32 v166, v96, v97
	v_cvt_pk_bf16_f32 v167, v98, v99
	s_nop 1
	v_permlane16_swap_b32 v164, v166
	v_permlane16_swap_b32 v165, v167
	s_nop 1
	global_store_dwordx4 v157, v[164:167], s[96:97]
	v_cvt_pk_bf16_f32 v168, v100, v101
	v_cvt_pk_bf16_f32 v169, v102, v103
	v_cvt_pk_bf16_f32 v170, v106, v107
	v_cvt_pk_bf16_f32 v171, v108, v109
	s_nop 1
	v_permlane16_swap_b32 v168, v170
	v_permlane16_swap_b32 v169, v171
	s_nop 1
	global_store_dwordx4 v157, v[168:171], s[96:97] offset:64
	v_pk_mul_f32 v[152:153], v[110:111], v[110:111]
	v_pk_fma_f32 v[152:153], v[112:113], v[112:113], v[152:153]
	v_pk_fma_f32 v[152:153], v[114:115], v[114:115], v[152:153]
	v_pk_fma_f32 v[152:153], v[116:117], v[116:117], v[152:153]
	v_pk_fma_f32 v[152:153], v[118:119], v[118:119], v[152:153]
	v_pk_fma_f32 v[152:153], v[120:121], v[120:121], v[152:153]
	v_pk_fma_f32 v[152:153], v[122:123], v[122:123], v[152:153]
	v_pk_fma_f32 v[152:153], v[124:125], v[124:125], v[152:153]
	v_add_f32_e32 v148, v152, v153
	v_mov_b32_e32 v149, v148
	s_nop 1
	v_permlane16_swap_b32 v148, v149
	s_nop 1
	v_add_f32_e32 v148, v148, v149
	v_mov_b32_e32 v149, v148
	s_nop 1
	v_permlane32_swap_b32 v148, v149
	s_nop 1
	v_add_f32_e32 v148, v148, v149
	v_mul_f32_e32 v148, 0x3c800000, v148
	v_add_f32_e32 v148, 0x358637bd, v148
	v_rsq_f32_e32 v148, v148
	s_nop 0
	v_pk_mul_f32 v[110:111], v[110:111], v[148:149] op_sel_hi:[1,0]
	v_pk_mul_f32 v[112:113], v[112:113], v[148:149] op_sel_hi:[1,0]
	v_pk_mul_f32 v[110:111], v[110:111], v[188:189]
	v_pk_mul_f32 v[112:113], v[112:113], v[190:191]
	v_pk_mul_f32 v[114:115], v[114:115], v[148:149] op_sel_hi:[1,0]
	v_pk_mul_f32 v[116:117], v[116:117], v[148:149] op_sel_hi:[1,0]
	v_pk_mul_f32 v[114:115], v[114:115], v[192:193]
	v_pk_mul_f32 v[116:117], v[116:117], v[194:195]
	v_pk_mul_f32 v[118:119], v[118:119], v[148:149] op_sel_hi:[1,0]
	v_pk_mul_f32 v[120:121], v[120:121], v[148:149] op_sel_hi:[1,0]
	v_pk_mul_f32 v[118:119], v[118:119], v[208:209]
	v_pk_mul_f32 v[120:121], v[120:121], v[210:211]
	v_pk_mul_f32 v[122:123], v[122:123], v[148:149] op_sel_hi:[1,0]
	v_pk_mul_f32 v[124:125], v[124:125], v[148:149] op_sel_hi:[1,0]
	v_pk_mul_f32 v[122:123], v[122:123], v[212:213]
	v_pk_mul_f32 v[124:125], v[124:125], v[214:215]
	v_cvt_pk_bf16_f32 v164, v110, v111
	v_cvt_pk_bf16_f32 v165, v112, v113
	v_cvt_pk_bf16_f32 v166, v114, v115
	v_cvt_pk_bf16_f32 v167, v116, v117
	s_nop 1
	v_permlane16_swap_b32 v164, v166
	v_permlane16_swap_b32 v165, v167
	s_nop 1
	global_store_dwordx4 v158, v[164:167], s[96:97]
	v_cvt_pk_bf16_f32 v168, v118, v119
	v_cvt_pk_bf16_f32 v169, v120, v121
	v_cvt_pk_bf16_f32 v170, v122, v123
	v_cvt_pk_bf16_f32 v171, v124, v125
	s_nop 1
	v_permlane16_swap_b32 v168, v170
	v_permlane16_swap_b32 v169, v171
	s_nop 1
	global_store_dwordx4 v158, v[168:171], s[96:97] offset:64
	v_pk_mul_f32 v[152:153], v[126:127], v[126:127]
	v_pk_fma_f32 v[152:153], v[128:129], v[128:129], v[152:153]
	v_pk_fma_f32 v[152:153], v[136:137], v[136:137], v[152:153]
	v_pk_fma_f32 v[152:153], v[138:139], v[138:139], v[152:153]
	v_pk_fma_f32 v[152:153], v[140:141], v[140:141], v[152:153]
	v_pk_fma_f32 v[152:153], v[142:143], v[142:143], v[152:153]
	v_pk_fma_f32 v[152:153], v[144:145], v[144:145], v[152:153]
	v_pk_fma_f32 v[152:153], v[146:147], v[146:147], v[152:153]
	v_add_f32_e32 v148, v152, v153
	v_mov_b32_e32 v149, v148
	s_nop 1
	v_permlane16_swap_b32 v148, v149
	s_nop 1
	v_add_f32_e32 v148, v148, v149
	v_mov_b32_e32 v149, v148
	s_nop 1
	v_permlane32_swap_b32 v148, v149
	s_nop 1
	v_add_f32_e32 v148, v148, v149
	v_mul_f32_e32 v148, 0x3c800000, v148
	v_add_f32_e32 v148, 0x358637bd, v148
	v_rsq_f32_e32 v148, v148
	s_nop 0
	v_pk_mul_f32 v[126:127], v[126:127], v[148:149] op_sel_hi:[1,0]
	v_pk_mul_f32 v[128:129], v[128:129], v[148:149] op_sel_hi:[1,0]
	v_pk_mul_f32 v[126:127], v[126:127], v[188:189]
	v_pk_mul_f32 v[128:129], v[128:129], v[190:191]
	v_pk_mul_f32 v[136:137], v[136:137], v[148:149] op_sel_hi:[1,0]
	v_pk_mul_f32 v[138:139], v[138:139], v[148:149] op_sel_hi:[1,0]
	v_pk_mul_f32 v[136:137], v[136:137], v[192:193]
	v_pk_mul_f32 v[138:139], v[138:139], v[194:195]
	v_pk_mul_f32 v[140:141], v[140:141], v[148:149] op_sel_hi:[1,0]
	v_pk_mul_f32 v[142:143], v[142:143], v[148:149] op_sel_hi:[1,0]
	v_pk_mul_f32 v[140:141], v[140:141], v[208:209]
	v_pk_mul_f32 v[142:143], v[142:143], v[210:211]
	v_pk_mul_f32 v[144:145], v[144:145], v[148:149] op_sel_hi:[1,0]
	v_pk_mul_f32 v[146:147], v[146:147], v[148:149] op_sel_hi:[1,0]
	v_pk_mul_f32 v[144:145], v[144:145], v[212:213]
	v_pk_mul_f32 v[146:147], v[146:147], v[214:215]
	v_cvt_pk_bf16_f32 v164, v126, v127
	v_cvt_pk_bf16_f32 v165, v128, v129
	v_cvt_pk_bf16_f32 v166, v136, v137
	v_cvt_pk_bf16_f32 v167, v138, v139
	s_nop 1
	v_permlane16_swap_b32 v164, v166
	v_permlane16_swap_b32 v165, v167
	s_nop 1
	global_store_dwordx4 v159, v[164:167], s[96:97]
	v_cvt_pk_bf16_f32 v168, v140, v141
	v_cvt_pk_bf16_f32 v169, v142, v143
	v_cvt_pk_bf16_f32 v170, v144, v145
	v_cvt_pk_bf16_f32 v171, v146, v147
	s_nop 1
	v_permlane16_swap_b32 v168, v170
	v_permlane16_swap_b32 v169, v171
	s_nop 1
	global_store_dwordx4 v159, v[168:171], s[96:97] offset:64
	s_branch .Lg2_next
.Lg2_iq:
	s_load_dwordx2 s[92:93], s[84:85], 0x168
	v_lshrrev_b32_e32 v148, 7, v196
	v_and_b32_e32 v149, 15, v196
	v_lshl_or_b32 v148, v148, 6, v149
	v_bfe_u32 v149, v196, 6, 1
	v_bfe_u32 v150, v196, 4, 2
	v_lshlrev_b32_e32 v148, 9, v148
	v_lshlrev_b32_e32 v149, 7, v149
	v_lshl_or_b32 v149, v150, 3, v149
	v_and_b32_e32 v150, 1, v150
	v_mul_u32_u24_e32 v150, 24, v150
	v_add3_u32 v156, v148, v149, v150
	v_add_u32_e32 v157, 0x2000, v156
	v_add_u32_e32 v158, 0x4000, v156
	v_add_u32_e32 v159, 0x6000, v156
	s_sub_i32 s3, s37, 14
	s_waitcnt lgkmcnt(0)
	s_lshl_b32 s2, s0, 16
	s_lshl_b32 s38, s3, 8
	s_add_i32 s2, s2, s38
	s_add_u32 s96, s92, s2
	s_addc_u32 s97, s93, 0
	v_cvt_pk_bf16_f32 v164, v62, v63
	v_cvt_pk_bf16_f32 v165, v64, v65
	v_cvt_pk_bf16_f32 v166, v58, v59
	v_cvt_pk_bf16_f32 v167, v60, v61
	s_nop 1
	v_permlane16_swap_b32 v164, v166
	v_permlane16_swap_b32 v165, v167
	s_nop 1
	global_store_dwordx4 v156, v[164:167], s[96:97]
	v_cvt_pk_bf16_f32 v168, v54, v55
	v_cvt_pk_bf16_f32 v169, v56, v57
	v_cvt_pk_bf16_f32 v170, v50, v51
	v_cvt_pk_bf16_f32 v171, v52, v53
	s_nop 1
	v_permlane16_swap_b32 v168, v170
	v_permlane16_swap_b32 v169, v171
	s_nop 1
	global_store_dwordx4 v156, v[168:171], s[96:97] offset:64
	v_cvt_pk_bf16_f32 v164, v46, v47
	v_cvt_pk_bf16_f32 v165, v48, v49
	v_cvt_pk_bf16_f32 v166, v42, v43
	v_cvt_pk_bf16_f32 v167, v44, v45
	s_nop 1
	v_permlane16_swap_b32 v164, v166
	v_permlane16_swap_b32 v165, v167
	s_nop 1
	global_store_dwordx4 v157, v[164:167], s[96:97]
	v_cvt_pk_bf16_f32 v168, v38, v39
	v_cvt_pk_bf16_f32 v169, v40, v41
	v_cvt_pk_bf16_f32 v170, v34, v35
	v_cvt_pk_bf16_f32 v171, v36, v37
	s_nop 1
	v_permlane16_swap_b32 v168, v170
	v_permlane16_swap_b32 v169, v171
	s_nop 1
	global_store_dwordx4 v157, v[168:171], s[96:97] offset:64
	v_cvt_pk_bf16_f32 v164, v30, v31
	v_cvt_pk_bf16_f32 v165, v32, v33
	v_cvt_pk_bf16_f32 v166, v26, v27
	v_cvt_pk_bf16_f32 v167, v28, v29
	s_nop 1
	v_permlane16_swap_b32 v164, v166
	v_permlane16_swap_b32 v165, v167
	s_nop 1
	global_store_dwordx4 v158, v[164:167], s[96:97]
	v_cvt_pk_bf16_f32 v168, v22, v23
	v_cvt_pk_bf16_f32 v169, v24, v25
	v_cvt_pk_bf16_f32 v170, v18, v19
	v_cvt_pk_bf16_f32 v171, v20, v21
	s_nop 1
	v_permlane16_swap_b32 v168, v170
	v_permlane16_swap_b32 v169, v171
	s_nop 1
	global_store_dwordx4 v158, v[168:171], s[96:97] offset:64
	v_cvt_pk_bf16_f32 v164, v14, v15
	v_cvt_pk_bf16_f32 v165, v16, v17
	v_cvt_pk_bf16_f32 v166, v10, v11
	v_cvt_pk_bf16_f32 v167, v12, v13
	s_nop 1
	v_permlane16_swap_b32 v164, v166
	v_permlane16_swap_b32 v165, v167
	s_nop 1
	global_store_dwordx4 v159, v[164:167], s[96:97]
	v_cvt_pk_bf16_f32 v168, v6, v7
	v_cvt_pk_bf16_f32 v169, v8, v9
	v_cvt_pk_bf16_f32 v170, v2, v3
	v_cvt_pk_bf16_f32 v171, v4, v5
	s_nop 1
	v_permlane16_swap_b32 v168, v170
	v_permlane16_swap_b32 v169, v171
	s_nop 1
	global_store_dwordx4 v159, v[168:171], s[96:97] offset:64
	s_lshl_b32 s2, s49, 16
	s_lshl_b32 s38, s3, 8
	s_add_i32 s2, s2, s38
	s_add_u32 s96, s92, s2
	s_addc_u32 s97, s93, 0
	v_cvt_pk_bf16_f32 v164, v66, v67
	v_cvt_pk_bf16_f32 v165, v68, v69
	v_cvt_pk_bf16_f32 v166, v70, v71
	v_cvt_pk_bf16_f32 v167, v72, v73
	s_nop 1
	v_permlane16_swap_b32 v164, v166
	v_permlane16_swap_b32 v165, v167
	s_nop 1
	global_store_dwordx4 v156, v[164:167], s[96:97]
	v_cvt_pk_bf16_f32 v168, v82, v83
	v_cvt_pk_bf16_f32 v169, v84, v85
	v_cvt_pk_bf16_f32 v170, v88, v89
	v_cvt_pk_bf16_f32 v171, v90, v91
	s_nop 1
	v_permlane16_swap_b32 v168, v170
	v_permlane16_swap_b32 v169, v171
	s_nop 1
	global_store_dwordx4 v156, v[168:171], s[96:97] offset:64
	v_cvt_pk_bf16_f32 v164, v92, v93
	v_cvt_pk_bf16_f32 v165, v94, v95
	v_cvt_pk_bf16_f32 v166, v96, v97
	v_cvt_pk_bf16_f32 v167, v98, v99
	s_nop 1
	v_permlane16_swap_b32 v164, v166
	v_permlane16_swap_b32 v165, v167
	s_nop 1
	global_store_dwordx4 v157, v[164:167], s[96:97]
	v_cvt_pk_bf16_f32 v168, v100, v101
	v_cvt_pk_bf16_f32 v169, v102, v103
	v_cvt_pk_bf16_f32 v170, v106, v107
	v_cvt_pk_bf16_f32 v171, v108, v109
	s_nop 1
	v_permlane16_swap_b32 v168, v170
	v_permlane16_swap_b32 v169, v171
	s_nop 1
	global_store_dwordx4 v157, v[168:171], s[96:97] offset:64
	v_cvt_pk_bf16_f32 v164, v110, v111
	v_cvt_pk_bf16_f32 v165, v112, v113
	v_cvt_pk_bf16_f32 v166, v114, v115
	v_cvt_pk_bf16_f32 v167, v116, v117
	s_nop 1
	v_permlane16_swap_b32 v164, v166
	v_permlane16_swap_b32 v165, v167
	s_nop 1
	global_store_dwordx4 v158, v[164:167], s[96:97]
	v_cvt_pk_bf16_f32 v168, v118, v119
	v_cvt_pk_bf16_f32 v169, v120, v121
	v_cvt_pk_bf16_f32 v170, v122, v123
	v_cvt_pk_bf16_f32 v171, v124, v125
	s_nop 1
	v_permlane16_swap_b32 v168, v170
	v_permlane16_swap_b32 v169, v171
	s_nop 1
	global_store_dwordx4 v158, v[168:171], s[96:97] offset:64
	v_cvt_pk_bf16_f32 v164, v126, v127
	v_cvt_pk_bf16_f32 v165, v128, v129
	v_cvt_pk_bf16_f32 v166, v136, v137
	v_cvt_pk_bf16_f32 v167, v138, v139
	s_nop 1
	v_permlane16_swap_b32 v164, v166
	v_permlane16_swap_b32 v165, v167
	s_nop 1
	global_store_dwordx4 v159, v[164:167], s[96:97]
	v_cvt_pk_bf16_f32 v168, v140, v141
	v_cvt_pk_bf16_f32 v169, v142, v143
	v_cvt_pk_bf16_f32 v170, v144, v145
	v_cvt_pk_bf16_f32 v171, v146, v147
	s_nop 1
	v_permlane16_swap_b32 v168, v170
	v_permlane16_swap_b32 v169, v171
	s_nop 1
	global_store_dwordx4 v159, v[168:171], s[96:97] offset:64
	s_branch .Lg2_next
.Lg2_g8b:
	s_branch .Lg2_2p
	s_cmp_lt_u32 s37, 8
	s_cbranch_scc0 .Lg2_2p
	s_and_b32 s3, s37, 3
	s_cmp_lt_u32 s37, 4
	s_cselect_b32 s2, 0, 8
	s_add_u32 s92, s84, s2
	s_addc_u32 s93, s85, 0
	s_load_dwordx2 s[92:93], s[92:93], 0x140
	v_lshrrev_b32_e32 v148, 7, v196
	v_and_b32_e32 v149, 15, v196
	v_lshl_or_b32 v148, v148, 6, v149
	v_bfe_u32 v149, v196, 6, 1
	v_bfe_u32 v150, v196, 4, 2
	v_lshlrev_b32_e32 v148, 10, v148
	v_lshlrev_b32_e32 v149, 7, v149
	v_lshl_or_b32 v149, v150, 3, v149
	v_and_b32_e32 v150, 1, v150
	v_mul_u32_u24_e32 v150, 24, v150
	v_add3_u32 v156, v148, v149, v150
	v_add_u32_e32 v157, 0x4000, v156
	v_add_u32_e32 v158, 0x8000, v156
	v_add_u32_e32 v159, 0xc000, v156
	s_waitcnt lgkmcnt(0)
	s_lshl_b32 s2, s0, 17
	s_lshl_b32 s38, s3, 8
	s_add_i32 s2, s2, s38
	s_add_u32 s96, s92, s2
	s_addc_u32 s97, s93, 0
	v_mul_f32_e32 v148, 0x3d372713, v62
	v_mul_f32_e32 v149, 0x3d372713, v63
	v_mul_f32_e32 v150, 0x3d372713, v64
	v_mul_f32_e32 v151, 0x3d372713, v65
	v_mul_f32_e32 v148, v62, v148
	v_mul_f32_e32 v149, v63, v149
	v_mul_f32_e32 v150, v64, v150
	v_mul_f32_e32 v151, v65, v151
	v_fma_f32 v148, v62, v148, v62
	v_fma_f32 v149, v63, v149, v63
	v_fma_f32 v150, v64, v150, v64
	v_fma_f32 v151, v65, v151, v65
	v_mul_f32_e32 v148, 0x3f4c422a, v148
	v_mul_f32_e32 v149, 0x3f4c422a, v149
	v_mul_f32_e32 v150, 0x3f4c422a, v150
	v_mul_f32_e32 v151, 0x3f4c422a, v151
	v_add_f32_e32 v148, v148, v148
	v_add_f32_e32 v149, v149, v149
	v_add_f32_e32 v150, v150, v150
	v_add_f32_e32 v151, v151, v151
	v_mul_f32_e32 v148, 0xbfb8aa3b, v148
	v_mul_f32_e32 v149, 0xbfb8aa3b, v149
	v_mul_f32_e32 v150, 0xbfb8aa3b, v150
	v_mul_f32_e32 v151, 0xbfb8aa3b, v151
	v_exp_f32_e32 v148, v148
	v_exp_f32_e32 v149, v149
	v_exp_f32_e32 v150, v150
	v_exp_f32_e32 v151, v151
	v_add_f32_e32 v148, 1.0, v148
	v_add_f32_e32 v149, 1.0, v149
	v_add_f32_e32 v150, 1.0, v150
	v_add_f32_e32 v151, 1.0, v151
	v_rcp_f32_e32 v148, v148
	v_rcp_f32_e32 v149, v149
	v_rcp_f32_e32 v150, v150
	v_rcp_f32_e32 v151, v151
	s_nop 0
	v_pk_mul_f32 v[148:149], v[62:63], v[148:149]
	v_pk_mul_f32 v[150:151], v[64:65], v[150:151]
	v_cvt_pk_bf16_f32 v164, v148, v149
	v_cvt_pk_bf16_f32 v165, v150, v151
	v_mul_f32_e32 v148, 0x3d372713, v58
	v_mul_f32_e32 v149, 0x3d372713, v59
	v_mul_f32_e32 v150, 0x3d372713, v60
	v_mul_f32_e32 v151, 0x3d372713, v61
	v_mul_f32_e32 v148, v58, v148
	v_mul_f32_e32 v149, v59, v149
	v_mul_f32_e32 v150, v60, v150
	v_mul_f32_e32 v151, v61, v151
	v_fma_f32 v148, v58, v148, v58
	v_fma_f32 v149, v59, v149, v59
	v_fma_f32 v150, v60, v150, v60
	v_fma_f32 v151, v61, v151, v61
	v_mul_f32_e32 v148, 0x3f4c422a, v148
	v_mul_f32_e32 v149, 0x3f4c422a, v149
	v_mul_f32_e32 v150, 0x3f4c422a, v150
	v_mul_f32_e32 v151, 0x3f4c422a, v151
	v_add_f32_e32 v148, v148, v148
	v_add_f32_e32 v149, v149, v149
	v_add_f32_e32 v150, v150, v150
	v_add_f32_e32 v151, v151, v151
	v_mul_f32_e32 v148, 0xbfb8aa3b, v148
	v_mul_f32_e32 v149, 0xbfb8aa3b, v149
	v_mul_f32_e32 v150, 0xbfb8aa3b, v150
	v_mul_f32_e32 v151, 0xbfb8aa3b, v151
	v_exp_f32_e32 v148, v148
	v_exp_f32_e32 v149, v149
	v_exp_f32_e32 v150, v150
	v_exp_f32_e32 v151, v151
	v_add_f32_e32 v148, 1.0, v148
	v_add_f32_e32 v149, 1.0, v149
	v_add_f32_e32 v150, 1.0, v150
	v_add_f32_e32 v151, 1.0, v151
	v_rcp_f32_e32 v148, v148
	v_rcp_f32_e32 v149, v149
	v_rcp_f32_e32 v150, v150
	v_rcp_f32_e32 v151, v151
	s_nop 0
	v_pk_mul_f32 v[148:149], v[58:59], v[148:149]
	v_pk_mul_f32 v[150:151], v[60:61], v[150:151]
	v_cvt_pk_bf16_f32 v166, v148, v149
	v_cvt_pk_bf16_f32 v167, v150, v151
	s_nop 1
	v_permlane16_swap_b32 v164, v166
	v_permlane16_swap_b32 v165, v167
	s_nop 1
	global_store_dwordx4 v156, v[164:167], s[96:97]
	v_mul_f32_e32 v148, 0x3d372713, v54
	v_mul_f32_e32 v149, 0x3d372713, v55
	v_mul_f32_e32 v150, 0x3d372713, v56
	v_mul_f32_e32 v151, 0x3d372713, v57
	v_mul_f32_e32 v148, v54, v148
	v_mul_f32_e32 v149, v55, v149
	v_mul_f32_e32 v150, v56, v150
	v_mul_f32_e32 v151, v57, v151
	v_fma_f32 v148, v54, v148, v54
	v_fma_f32 v149, v55, v149, v55
	v_fma_f32 v150, v56, v150, v56
	v_fma_f32 v151, v57, v151, v57
	v_mul_f32_e32 v148, 0x3f4c422a, v148
	v_mul_f32_e32 v149, 0x3f4c422a, v149
	v_mul_f32_e32 v150, 0x3f4c422a, v150
	v_mul_f32_e32 v151, 0x3f4c422a, v151
	v_add_f32_e32 v148, v148, v148
	v_add_f32_e32 v149, v149, v149
	v_add_f32_e32 v150, v150, v150
	v_add_f32_e32 v151, v151, v151
	v_mul_f32_e32 v148, 0xbfb8aa3b, v148
	v_mul_f32_e32 v149, 0xbfb8aa3b, v149
	v_mul_f32_e32 v150, 0xbfb8aa3b, v150
	v_mul_f32_e32 v151, 0xbfb8aa3b, v151
	v_exp_f32_e32 v148, v148
	v_exp_f32_e32 v149, v149
	v_exp_f32_e32 v150, v150
	v_exp_f32_e32 v151, v151
	v_add_f32_e32 v148, 1.0, v148
	v_add_f32_e32 v149, 1.0, v149
	v_add_f32_e32 v150, 1.0, v150
	v_add_f32_e32 v151, 1.0, v151
	v_rcp_f32_e32 v148, v148
	v_rcp_f32_e32 v149, v149
	v_rcp_f32_e32 v150, v150
	v_rcp_f32_e32 v151, v151
	s_nop 0
	v_pk_mul_f32 v[148:149], v[54:55], v[148:149]
	v_pk_mul_f32 v[150:151], v[56:57], v[150:151]
	v_cvt_pk_bf16_f32 v168, v148, v149
	v_cvt_pk_bf16_f32 v169, v150, v151
	v_mul_f32_e32 v148, 0x3d372713, v50
	v_mul_f32_e32 v149, 0x3d372713, v51
	v_mul_f32_e32 v150, 0x3d372713, v52
	v_mul_f32_e32 v151, 0x3d372713, v53
	v_mul_f32_e32 v148, v50, v148
	v_mul_f32_e32 v149, v51, v149
	v_mul_f32_e32 v150, v52, v150
	v_mul_f32_e32 v151, v53, v151
	v_fma_f32 v148, v50, v148, v50
	v_fma_f32 v149, v51, v149, v51
	v_fma_f32 v150, v52, v150, v52
	v_fma_f32 v151, v53, v151, v53
	v_mul_f32_e32 v148, 0x3f4c422a, v148
	v_mul_f32_e32 v149, 0x3f4c422a, v149
	v_mul_f32_e32 v150, 0x3f4c422a, v150
	v_mul_f32_e32 v151, 0x3f4c422a, v151
	v_add_f32_e32 v148, v148, v148
	v_add_f32_e32 v149, v149, v149
	v_add_f32_e32 v150, v150, v150
	v_add_f32_e32 v151, v151, v151
	v_mul_f32_e32 v148, 0xbfb8aa3b, v148
	v_mul_f32_e32 v149, 0xbfb8aa3b, v149
	v_mul_f32_e32 v150, 0xbfb8aa3b, v150
	v_mul_f32_e32 v151, 0xbfb8aa3b, v151
	v_exp_f32_e32 v148, v148
	v_exp_f32_e32 v149, v149
	v_exp_f32_e32 v150, v150
	v_exp_f32_e32 v151, v151
	v_add_f32_e32 v148, 1.0, v148
	v_add_f32_e32 v149, 1.0, v149
	v_add_f32_e32 v150, 1.0, v150
	v_add_f32_e32 v151, 1.0, v151
	v_rcp_f32_e32 v148, v148
	v_rcp_f32_e32 v149, v149
	v_rcp_f32_e32 v150, v150
	v_rcp_f32_e32 v151, v151
	s_nop 0
	v_pk_mul_f32 v[148:149], v[50:51], v[148:149]
	v_pk_mul_f32 v[150:151], v[52:53], v[150:151]
	v_cvt_pk_bf16_f32 v170, v148, v149
	v_cvt_pk_bf16_f32 v171, v150, v151
	s_nop 1
	v_permlane16_swap_b32 v168, v170
	v_permlane16_swap_b32 v169, v171
	s_nop 1
	global_store_dwordx4 v156, v[168:171], s[96:97] offset:64
	v_mul_f32_e32 v148, 0x3d372713, v46
	v_mul_f32_e32 v149, 0x3d372713, v47
	v_mul_f32_e32 v150, 0x3d372713, v48
	v_mul_f32_e32 v151, 0x3d372713, v49
	v_mul_f32_e32 v148, v46, v148
	v_mul_f32_e32 v149, v47, v149
	v_mul_f32_e32 v150, v48, v150
	v_mul_f32_e32 v151, v49, v151
	v_fma_f32 v148, v46, v148, v46
	v_fma_f32 v149, v47, v149, v47
	v_fma_f32 v150, v48, v150, v48
	v_fma_f32 v151, v49, v151, v49
	v_mul_f32_e32 v148, 0x3f4c422a, v148
	v_mul_f32_e32 v149, 0x3f4c422a, v149
	v_mul_f32_e32 v150, 0x3f4c422a, v150
	v_mul_f32_e32 v151, 0x3f4c422a, v151
	v_add_f32_e32 v148, v148, v148
	v_add_f32_e32 v149, v149, v149
	v_add_f32_e32 v150, v150, v150
	v_add_f32_e32 v151, v151, v151
	v_mul_f32_e32 v148, 0xbfb8aa3b, v148
	v_mul_f32_e32 v149, 0xbfb8aa3b, v149
	v_mul_f32_e32 v150, 0xbfb8aa3b, v150
	v_mul_f32_e32 v151, 0xbfb8aa3b, v151
	v_exp_f32_e32 v148, v148
	v_exp_f32_e32 v149, v149
	v_exp_f32_e32 v150, v150
	v_exp_f32_e32 v151, v151
	v_add_f32_e32 v148, 1.0, v148
	v_add_f32_e32 v149, 1.0, v149
	v_add_f32_e32 v150, 1.0, v150
	v_add_f32_e32 v151, 1.0, v151
	v_rcp_f32_e32 v148, v148
	v_rcp_f32_e32 v149, v149
	v_rcp_f32_e32 v150, v150
	v_rcp_f32_e32 v151, v151
	s_nop 0
	v_pk_mul_f32 v[148:149], v[46:47], v[148:149]
	v_pk_mul_f32 v[150:151], v[48:49], v[150:151]
	v_cvt_pk_bf16_f32 v164, v148, v149
	v_cvt_pk_bf16_f32 v165, v150, v151
	v_mul_f32_e32 v148, 0x3d372713, v42
	v_mul_f32_e32 v149, 0x3d372713, v43
	v_mul_f32_e32 v150, 0x3d372713, v44
	v_mul_f32_e32 v151, 0x3d372713, v45
	v_mul_f32_e32 v148, v42, v148
	v_mul_f32_e32 v149, v43, v149
	v_mul_f32_e32 v150, v44, v150
	v_mul_f32_e32 v151, v45, v151
	v_fma_f32 v148, v42, v148, v42
	v_fma_f32 v149, v43, v149, v43
	v_fma_f32 v150, v44, v150, v44
	v_fma_f32 v151, v45, v151, v45
	v_mul_f32_e32 v148, 0x3f4c422a, v148
	v_mul_f32_e32 v149, 0x3f4c422a, v149
	v_mul_f32_e32 v150, 0x3f4c422a, v150
	v_mul_f32_e32 v151, 0x3f4c422a, v151
	v_add_f32_e32 v148, v148, v148
	v_add_f32_e32 v149, v149, v149
	v_add_f32_e32 v150, v150, v150
	v_add_f32_e32 v151, v151, v151
	v_mul_f32_e32 v148, 0xbfb8aa3b, v148
	v_mul_f32_e32 v149, 0xbfb8aa3b, v149
	v_mul_f32_e32 v150, 0xbfb8aa3b, v150
	v_mul_f32_e32 v151, 0xbfb8aa3b, v151
	v_exp_f32_e32 v148, v148
	v_exp_f32_e32 v149, v149
	v_exp_f32_e32 v150, v150
	v_exp_f32_e32 v151, v151
	v_add_f32_e32 v148, 1.0, v148
	v_add_f32_e32 v149, 1.0, v149
	v_add_f32_e32 v150, 1.0, v150
	v_add_f32_e32 v151, 1.0, v151
	v_rcp_f32_e32 v148, v148
	v_rcp_f32_e32 v149, v149
	v_rcp_f32_e32 v150, v150
	v_rcp_f32_e32 v151, v151
	s_nop 0
	v_pk_mul_f32 v[148:149], v[42:43], v[148:149]
	v_pk_mul_f32 v[150:151], v[44:45], v[150:151]
	v_cvt_pk_bf16_f32 v166, v148, v149
	v_cvt_pk_bf16_f32 v167, v150, v151
	s_nop 1
	v_permlane16_swap_b32 v164, v166
	v_permlane16_swap_b32 v165, v167
	s_nop 1
	global_store_dwordx4 v157, v[164:167], s[96:97]
	v_mul_f32_e32 v148, 0x3d372713, v38
	v_mul_f32_e32 v149, 0x3d372713, v39
	v_mul_f32_e32 v150, 0x3d372713, v40
	v_mul_f32_e32 v151, 0x3d372713, v41
	v_mul_f32_e32 v148, v38, v148
	v_mul_f32_e32 v149, v39, v149
	v_mul_f32_e32 v150, v40, v150
	v_mul_f32_e32 v151, v41, v151
	v_fma_f32 v148, v38, v148, v38
	v_fma_f32 v149, v39, v149, v39
	v_fma_f32 v150, v40, v150, v40
	v_fma_f32 v151, v41, v151, v41
	v_mul_f32_e32 v148, 0x3f4c422a, v148
	v_mul_f32_e32 v149, 0x3f4c422a, v149
	v_mul_f32_e32 v150, 0x3f4c422a, v150
	v_mul_f32_e32 v151, 0x3f4c422a, v151
	v_add_f32_e32 v148, v148, v148
	v_add_f32_e32 v149, v149, v149
	v_add_f32_e32 v150, v150, v150
	v_add_f32_e32 v151, v151, v151
	v_mul_f32_e32 v148, 0xbfb8aa3b, v148
	v_mul_f32_e32 v149, 0xbfb8aa3b, v149
	v_mul_f32_e32 v150, 0xbfb8aa3b, v150
	v_mul_f32_e32 v151, 0xbfb8aa3b, v151
	v_exp_f32_e32 v148, v148
	v_exp_f32_e32 v149, v149
	v_exp_f32_e32 v150, v150
	v_exp_f32_e32 v151, v151
	v_add_f32_e32 v148, 1.0, v148
	v_add_f32_e32 v149, 1.0, v149
	v_add_f32_e32 v150, 1.0, v150
	v_add_f32_e32 v151, 1.0, v151
	v_rcp_f32_e32 v148, v148
	v_rcp_f32_e32 v149, v149
	v_rcp_f32_e32 v150, v150
	v_rcp_f32_e32 v151, v151
	s_nop 0
	v_pk_mul_f32 v[148:149], v[38:39], v[148:149]
	v_pk_mul_f32 v[150:151], v[40:41], v[150:151]
	v_cvt_pk_bf16_f32 v168, v148, v149
	v_cvt_pk_bf16_f32 v169, v150, v151
	v_mul_f32_e32 v148, 0x3d372713, v34
	v_mul_f32_e32 v149, 0x3d372713, v35
	v_mul_f32_e32 v150, 0x3d372713, v36
	v_mul_f32_e32 v151, 0x3d372713, v37
	v_mul_f32_e32 v148, v34, v148
	v_mul_f32_e32 v149, v35, v149
	v_mul_f32_e32 v150, v36, v150
	v_mul_f32_e32 v151, v37, v151
	v_fma_f32 v148, v34, v148, v34
	v_fma_f32 v149, v35, v149, v35
	v_fma_f32 v150, v36, v150, v36
	v_fma_f32 v151, v37, v151, v37
	v_mul_f32_e32 v148, 0x3f4c422a, v148
	v_mul_f32_e32 v149, 0x3f4c422a, v149
	v_mul_f32_e32 v150, 0x3f4c422a, v150
	v_mul_f32_e32 v151, 0x3f4c422a, v151
	v_add_f32_e32 v148, v148, v148
	v_add_f32_e32 v149, v149, v149
	v_add_f32_e32 v150, v150, v150
	v_add_f32_e32 v151, v151, v151
	v_mul_f32_e32 v148, 0xbfb8aa3b, v148
	v_mul_f32_e32 v149, 0xbfb8aa3b, v149
	v_mul_f32_e32 v150, 0xbfb8aa3b, v150
	v_mul_f32_e32 v151, 0xbfb8aa3b, v151
	v_exp_f32_e32 v148, v148
	v_exp_f32_e32 v149, v149
	v_exp_f32_e32 v150, v150
	v_exp_f32_e32 v151, v151
	v_add_f32_e32 v148, 1.0, v148
	v_add_f32_e32 v149, 1.0, v149
	v_add_f32_e32 v150, 1.0, v150
	v_add_f32_e32 v151, 1.0, v151
	v_rcp_f32_e32 v148, v148
	v_rcp_f32_e32 v149, v149
	v_rcp_f32_e32 v150, v150
	v_rcp_f32_e32 v151, v151
	s_nop 0
	v_pk_mul_f32 v[148:149], v[34:35], v[148:149]
	v_pk_mul_f32 v[150:151], v[36:37], v[150:151]
	v_cvt_pk_bf16_f32 v170, v148, v149
	v_cvt_pk_bf16_f32 v171, v150, v151
	s_nop 1
	v_permlane16_swap_b32 v168, v170
	v_permlane16_swap_b32 v169, v171
	s_nop 1
	global_store_dwordx4 v157, v[168:171], s[96:97] offset:64
	v_mul_f32_e32 v148, 0x3d372713, v30
	v_mul_f32_e32 v149, 0x3d372713, v31
	v_mul_f32_e32 v150, 0x3d372713, v32
	v_mul_f32_e32 v151, 0x3d372713, v33
	v_mul_f32_e32 v148, v30, v148
	v_mul_f32_e32 v149, v31, v149
	v_mul_f32_e32 v150, v32, v150
	v_mul_f32_e32 v151, v33, v151
	v_fma_f32 v148, v30, v148, v30
	v_fma_f32 v149, v31, v149, v31
	v_fma_f32 v150, v32, v150, v32
	v_fma_f32 v151, v33, v151, v33
	v_mul_f32_e32 v148, 0x3f4c422a, v148
	v_mul_f32_e32 v149, 0x3f4c422a, v149
	v_mul_f32_e32 v150, 0x3f4c422a, v150
	v_mul_f32_e32 v151, 0x3f4c422a, v151
	v_add_f32_e32 v148, v148, v148
	v_add_f32_e32 v149, v149, v149
	v_add_f32_e32 v150, v150, v150
	v_add_f32_e32 v151, v151, v151
	v_mul_f32_e32 v148, 0xbfb8aa3b, v148
	v_mul_f32_e32 v149, 0xbfb8aa3b, v149
	v_mul_f32_e32 v150, 0xbfb8aa3b, v150
	v_mul_f32_e32 v151, 0xbfb8aa3b, v151
	v_exp_f32_e32 v148, v148
	v_exp_f32_e32 v149, v149
	v_exp_f32_e32 v150, v150
	v_exp_f32_e32 v151, v151
	v_add_f32_e32 v148, 1.0, v148
	v_add_f32_e32 v149, 1.0, v149
	v_add_f32_e32 v150, 1.0, v150
	v_add_f32_e32 v151, 1.0, v151
	v_rcp_f32_e32 v148, v148
	v_rcp_f32_e32 v149, v149
	v_rcp_f32_e32 v150, v150
	v_rcp_f32_e32 v151, v151
	s_nop 0
	v_pk_mul_f32 v[148:149], v[30:31], v[148:149]
	v_pk_mul_f32 v[150:151], v[32:33], v[150:151]
	v_cvt_pk_bf16_f32 v164, v148, v149
	v_cvt_pk_bf16_f32 v165, v150, v151
	v_mul_f32_e32 v148, 0x3d372713, v26
	v_mul_f32_e32 v149, 0x3d372713, v27
	v_mul_f32_e32 v150, 0x3d372713, v28
	v_mul_f32_e32 v151, 0x3d372713, v29
	v_mul_f32_e32 v148, v26, v148
	v_mul_f32_e32 v149, v27, v149
	v_mul_f32_e32 v150, v28, v150
	v_mul_f32_e32 v151, v29, v151
	v_fma_f32 v148, v26, v148, v26
	v_fma_f32 v149, v27, v149, v27
	v_fma_f32 v150, v28, v150, v28
	v_fma_f32 v151, v29, v151, v29
	v_mul_f32_e32 v148, 0x3f4c422a, v148
	v_mul_f32_e32 v149, 0x3f4c422a, v149
	v_mul_f32_e32 v150, 0x3f4c422a, v150
	v_mul_f32_e32 v151, 0x3f4c422a, v151
	v_add_f32_e32 v148, v148, v148
	v_add_f32_e32 v149, v149, v149
	v_add_f32_e32 v150, v150, v150
	v_add_f32_e32 v151, v151, v151
	v_mul_f32_e32 v148, 0xbfb8aa3b, v148
	v_mul_f32_e32 v149, 0xbfb8aa3b, v149
	v_mul_f32_e32 v150, 0xbfb8aa3b, v150
	v_mul_f32_e32 v151, 0xbfb8aa3b, v151
	v_exp_f32_e32 v148, v148
	v_exp_f32_e32 v149, v149
	v_exp_f32_e32 v150, v150
	v_exp_f32_e32 v151, v151
	v_add_f32_e32 v148, 1.0, v148
	v_add_f32_e32 v149, 1.0, v149
	v_add_f32_e32 v150, 1.0, v150
	v_add_f32_e32 v151, 1.0, v151
	v_rcp_f32_e32 v148, v148
	v_rcp_f32_e32 v149, v149
	v_rcp_f32_e32 v150, v150
	v_rcp_f32_e32 v151, v151
	s_nop 0
	v_pk_mul_f32 v[148:149], v[26:27], v[148:149]
	v_pk_mul_f32 v[150:151], v[28:29], v[150:151]
	v_cvt_pk_bf16_f32 v166, v148, v149
	v_cvt_pk_bf16_f32 v167, v150, v151
	s_nop 1
	v_permlane16_swap_b32 v164, v166
	v_permlane16_swap_b32 v165, v167
	s_nop 1
	global_store_dwordx4 v158, v[164:167], s[96:97]
	v_mul_f32_e32 v148, 0x3d372713, v22
	v_mul_f32_e32 v149, 0x3d372713, v23
	v_mul_f32_e32 v150, 0x3d372713, v24
	v_mul_f32_e32 v151, 0x3d372713, v25
	v_mul_f32_e32 v148, v22, v148
	v_mul_f32_e32 v149, v23, v149
	v_mul_f32_e32 v150, v24, v150
	v_mul_f32_e32 v151, v25, v151
	v_fma_f32 v148, v22, v148, v22
	v_fma_f32 v149, v23, v149, v23
	v_fma_f32 v150, v24, v150, v24
	v_fma_f32 v151, v25, v151, v25
	v_mul_f32_e32 v148, 0x3f4c422a, v148
	v_mul_f32_e32 v149, 0x3f4c422a, v149
	v_mul_f32_e32 v150, 0x3f4c422a, v150
	v_mul_f32_e32 v151, 0x3f4c422a, v151
	v_add_f32_e32 v148, v148, v148
	v_add_f32_e32 v149, v149, v149
	v_add_f32_e32 v150, v150, v150
	v_add_f32_e32 v151, v151, v151
	v_mul_f32_e32 v148, 0xbfb8aa3b, v148
	v_mul_f32_e32 v149, 0xbfb8aa3b, v149
	v_mul_f32_e32 v150, 0xbfb8aa3b, v150
	v_mul_f32_e32 v151, 0xbfb8aa3b, v151
	v_exp_f32_e32 v148, v148
	v_exp_f32_e32 v149, v149
	v_exp_f32_e32 v150, v150
	v_exp_f32_e32 v151, v151
	v_add_f32_e32 v148, 1.0, v148
	v_add_f32_e32 v149, 1.0, v149
	v_add_f32_e32 v150, 1.0, v150
	v_add_f32_e32 v151, 1.0, v151
	v_rcp_f32_e32 v148, v148
	v_rcp_f32_e32 v149, v149
	v_rcp_f32_e32 v150, v150
	v_rcp_f32_e32 v151, v151
	s_nop 0
	v_pk_mul_f32 v[148:149], v[22:23], v[148:149]
	v_pk_mul_f32 v[150:151], v[24:25], v[150:151]
	v_cvt_pk_bf16_f32 v168, v148, v149
	v_cvt_pk_bf16_f32 v169, v150, v151
	v_mul_f32_e32 v148, 0x3d372713, v18
	v_mul_f32_e32 v149, 0x3d372713, v19
	v_mul_f32_e32 v150, 0x3d372713, v20
	v_mul_f32_e32 v151, 0x3d372713, v21
	v_mul_f32_e32 v148, v18, v148
	v_mul_f32_e32 v149, v19, v149
	v_mul_f32_e32 v150, v20, v150
	v_mul_f32_e32 v151, v21, v151
	v_fma_f32 v148, v18, v148, v18
	v_fma_f32 v149, v19, v149, v19
	v_fma_f32 v150, v20, v150, v20
	v_fma_f32 v151, v21, v151, v21
	v_mul_f32_e32 v148, 0x3f4c422a, v148
	v_mul_f32_e32 v149, 0x3f4c422a, v149
	v_mul_f32_e32 v150, 0x3f4c422a, v150
	v_mul_f32_e32 v151, 0x3f4c422a, v151
	v_add_f32_e32 v148, v148, v148
	v_add_f32_e32 v149, v149, v149
	v_add_f32_e32 v150, v150, v150
	v_add_f32_e32 v151, v151, v151
	v_mul_f32_e32 v148, 0xbfb8aa3b, v148
	v_mul_f32_e32 v149, 0xbfb8aa3b, v149
	v_mul_f32_e32 v150, 0xbfb8aa3b, v150
	v_mul_f32_e32 v151, 0xbfb8aa3b, v151
	v_exp_f32_e32 v148, v148
	v_exp_f32_e32 v149, v149
	v_exp_f32_e32 v150, v150
	v_exp_f32_e32 v151, v151
	v_add_f32_e32 v148, 1.0, v148
	v_add_f32_e32 v149, 1.0, v149
	v_add_f32_e32 v150, 1.0, v150
	v_add_f32_e32 v151, 1.0, v151
	v_rcp_f32_e32 v148, v148
	v_rcp_f32_e32 v149, v149
	v_rcp_f32_e32 v150, v150
	v_rcp_f32_e32 v151, v151
	s_nop 0
	v_pk_mul_f32 v[148:149], v[18:19], v[148:149]
	v_pk_mul_f32 v[150:151], v[20:21], v[150:151]
	v_cvt_pk_bf16_f32 v170, v148, v149
	v_cvt_pk_bf16_f32 v171, v150, v151
	s_nop 1
	v_permlane16_swap_b32 v168, v170
	v_permlane16_swap_b32 v169, v171
	s_nop 1
	global_store_dwordx4 v158, v[168:171], s[96:97] offset:64
	v_mul_f32_e32 v148, 0x3d372713, v14
	v_mul_f32_e32 v149, 0x3d372713, v15
	v_mul_f32_e32 v150, 0x3d372713, v16
	v_mul_f32_e32 v151, 0x3d372713, v17
	v_mul_f32_e32 v148, v14, v148
	v_mul_f32_e32 v149, v15, v149
	v_mul_f32_e32 v150, v16, v150
	v_mul_f32_e32 v151, v17, v151
	v_fma_f32 v148, v14, v148, v14
	v_fma_f32 v149, v15, v149, v15
	v_fma_f32 v150, v16, v150, v16
	v_fma_f32 v151, v17, v151, v17
	v_mul_f32_e32 v148, 0x3f4c422a, v148
	v_mul_f32_e32 v149, 0x3f4c422a, v149
	v_mul_f32_e32 v150, 0x3f4c422a, v150
	v_mul_f32_e32 v151, 0x3f4c422a, v151
	v_add_f32_e32 v148, v148, v148
	v_add_f32_e32 v149, v149, v149
	v_add_f32_e32 v150, v150, v150
	v_add_f32_e32 v151, v151, v151
	v_mul_f32_e32 v148, 0xbfb8aa3b, v148
	v_mul_f32_e32 v149, 0xbfb8aa3b, v149
	v_mul_f32_e32 v150, 0xbfb8aa3b, v150
	v_mul_f32_e32 v151, 0xbfb8aa3b, v151
	v_exp_f32_e32 v148, v148
	v_exp_f32_e32 v149, v149
	v_exp_f32_e32 v150, v150
	v_exp_f32_e32 v151, v151
	v_add_f32_e32 v148, 1.0, v148
	v_add_f32_e32 v149, 1.0, v149
	v_add_f32_e32 v150, 1.0, v150
	v_add_f32_e32 v151, 1.0, v151
	v_rcp_f32_e32 v148, v148
	v_rcp_f32_e32 v149, v149
	v_rcp_f32_e32 v150, v150
	v_rcp_f32_e32 v151, v151
	s_nop 0
	v_pk_mul_f32 v[148:149], v[14:15], v[148:149]
	v_pk_mul_f32 v[150:151], v[16:17], v[150:151]
	v_cvt_pk_bf16_f32 v164, v148, v149
	v_cvt_pk_bf16_f32 v165, v150, v151
	v_mul_f32_e32 v148, 0x3d372713, v10
	v_mul_f32_e32 v149, 0x3d372713, v11
	v_mul_f32_e32 v150, 0x3d372713, v12
	v_mul_f32_e32 v151, 0x3d372713, v13
	v_mul_f32_e32 v148, v10, v148
	v_mul_f32_e32 v149, v11, v149
	v_mul_f32_e32 v150, v12, v150
	v_mul_f32_e32 v151, v13, v151
	v_fma_f32 v148, v10, v148, v10
	v_fma_f32 v149, v11, v149, v11
	v_fma_f32 v150, v12, v150, v12
	v_fma_f32 v151, v13, v151, v13
	v_mul_f32_e32 v148, 0x3f4c422a, v148
	v_mul_f32_e32 v149, 0x3f4c422a, v149
	v_mul_f32_e32 v150, 0x3f4c422a, v150
	v_mul_f32_e32 v151, 0x3f4c422a, v151
	v_add_f32_e32 v148, v148, v148
	v_add_f32_e32 v149, v149, v149
	v_add_f32_e32 v150, v150, v150
	v_add_f32_e32 v151, v151, v151
	v_mul_f32_e32 v148, 0xbfb8aa3b, v148
	v_mul_f32_e32 v149, 0xbfb8aa3b, v149
	v_mul_f32_e32 v150, 0xbfb8aa3b, v150
	v_mul_f32_e32 v151, 0xbfb8aa3b, v151
	v_exp_f32_e32 v148, v148
	v_exp_f32_e32 v149, v149
	v_exp_f32_e32 v150, v150
	v_exp_f32_e32 v151, v151
	v_add_f32_e32 v148, 1.0, v148
	v_add_f32_e32 v149, 1.0, v149
	v_add_f32_e32 v150, 1.0, v150
	v_add_f32_e32 v151, 1.0, v151
	v_rcp_f32_e32 v148, v148
	v_rcp_f32_e32 v149, v149
	v_rcp_f32_e32 v150, v150
	v_rcp_f32_e32 v151, v151
	s_nop 0
	v_pk_mul_f32 v[148:149], v[10:11], v[148:149]
	v_pk_mul_f32 v[150:151], v[12:13], v[150:151]
	v_cvt_pk_bf16_f32 v166, v148, v149
	v_cvt_pk_bf16_f32 v167, v150, v151
	s_nop 1
	v_permlane16_swap_b32 v164, v166
	v_permlane16_swap_b32 v165, v167
	s_nop 1
	global_store_dwordx4 v159, v[164:167], s[96:97]
	v_mul_f32_e32 v148, 0x3d372713, v6
	v_mul_f32_e32 v149, 0x3d372713, v7
	v_mul_f32_e32 v150, 0x3d372713, v8
	v_mul_f32_e32 v151, 0x3d372713, v9
	v_mul_f32_e32 v148, v6, v148
	v_mul_f32_e32 v149, v7, v149
	v_mul_f32_e32 v150, v8, v150
	v_mul_f32_e32 v151, v9, v151
	v_fma_f32 v148, v6, v148, v6
	v_fma_f32 v149, v7, v149, v7
	v_fma_f32 v150, v8, v150, v8
	v_fma_f32 v151, v9, v151, v9
	v_mul_f32_e32 v148, 0x3f4c422a, v148
	v_mul_f32_e32 v149, 0x3f4c422a, v149
	v_mul_f32_e32 v150, 0x3f4c422a, v150
	v_mul_f32_e32 v151, 0x3f4c422a, v151
	v_add_f32_e32 v148, v148, v148
	v_add_f32_e32 v149, v149, v149
	v_add_f32_e32 v150, v150, v150
	v_add_f32_e32 v151, v151, v151
	v_mul_f32_e32 v148, 0xbfb8aa3b, v148
	v_mul_f32_e32 v149, 0xbfb8aa3b, v149
	v_mul_f32_e32 v150, 0xbfb8aa3b, v150
	v_mul_f32_e32 v151, 0xbfb8aa3b, v151
	v_exp_f32_e32 v148, v148
	v_exp_f32_e32 v149, v149
	v_exp_f32_e32 v150, v150
	v_exp_f32_e32 v151, v151
	v_add_f32_e32 v148, 1.0, v148
	v_add_f32_e32 v149, 1.0, v149
	v_add_f32_e32 v150, 1.0, v150
	v_add_f32_e32 v151, 1.0, v151
	v_rcp_f32_e32 v148, v148
	v_rcp_f32_e32 v149, v149
	v_rcp_f32_e32 v150, v150
	v_rcp_f32_e32 v151, v151
	s_nop 0
	v_pk_mul_f32 v[148:149], v[6:7], v[148:149]
	v_pk_mul_f32 v[150:151], v[8:9], v[150:151]
	v_cvt_pk_bf16_f32 v168, v148, v149
	v_cvt_pk_bf16_f32 v169, v150, v151
	v_mul_f32_e32 v148, 0x3d372713, v2
	v_mul_f32_e32 v149, 0x3d372713, v3
	v_mul_f32_e32 v150, 0x3d372713, v4
	v_mul_f32_e32 v151, 0x3d372713, v5
	v_mul_f32_e32 v148, v2, v148
	v_mul_f32_e32 v149, v3, v149
	v_mul_f32_e32 v150, v4, v150
	v_mul_f32_e32 v151, v5, v151
	v_fma_f32 v148, v2, v148, v2
	v_fma_f32 v149, v3, v149, v3
	v_fma_f32 v150, v4, v150, v4
	v_fma_f32 v151, v5, v151, v5
	v_mul_f32_e32 v148, 0x3f4c422a, v148
	v_mul_f32_e32 v149, 0x3f4c422a, v149
	v_mul_f32_e32 v150, 0x3f4c422a, v150
	v_mul_f32_e32 v151, 0x3f4c422a, v151
	v_add_f32_e32 v148, v148, v148
	v_add_f32_e32 v149, v149, v149
	v_add_f32_e32 v150, v150, v150
	v_add_f32_e32 v151, v151, v151
	v_mul_f32_e32 v148, 0xbfb8aa3b, v148
	v_mul_f32_e32 v149, 0xbfb8aa3b, v149
	v_mul_f32_e32 v150, 0xbfb8aa3b, v150
	v_mul_f32_e32 v151, 0xbfb8aa3b, v151
	v_exp_f32_e32 v148, v148
	v_exp_f32_e32 v149, v149
	v_exp_f32_e32 v150, v150
	v_exp_f32_e32 v151, v151
	v_add_f32_e32 v148, 1.0, v148
	v_add_f32_e32 v149, 1.0, v149
	v_add_f32_e32 v150, 1.0, v150
	v_add_f32_e32 v151, 1.0, v151
	v_rcp_f32_e32 v148, v148
	v_rcp_f32_e32 v149, v149
	v_rcp_f32_e32 v150, v150
	v_rcp_f32_e32 v151, v151
	s_nop 0
	v_pk_mul_f32 v[148:149], v[2:3], v[148:149]
	v_pk_mul_f32 v[150:151], v[4:5], v[150:151]
	v_cvt_pk_bf16_f32 v170, v148, v149
	v_cvt_pk_bf16_f32 v171, v150, v151
	s_nop 1
	v_permlane16_swap_b32 v168, v170
	v_permlane16_swap_b32 v169, v171
	s_nop 1
	global_store_dwordx4 v159, v[168:171], s[96:97] offset:64
	s_lshl_b32 s2, s49, 17
	s_lshl_b32 s38, s3, 8
	s_add_i32 s2, s2, s38
	s_add_u32 s96, s92, s2
	s_addc_u32 s97, s93, 0
	v_mul_f32_e32 v148, 0x3d372713, v66
	v_mul_f32_e32 v149, 0x3d372713, v67
	v_mul_f32_e32 v150, 0x3d372713, v68
	v_mul_f32_e32 v151, 0x3d372713, v69
	v_mul_f32_e32 v148, v66, v148
	v_mul_f32_e32 v149, v67, v149
	v_mul_f32_e32 v150, v68, v150
	v_mul_f32_e32 v151, v69, v151
	v_fma_f32 v148, v66, v148, v66
	v_fma_f32 v149, v67, v149, v67
	v_fma_f32 v150, v68, v150, v68
	v_fma_f32 v151, v69, v151, v69
	v_mul_f32_e32 v148, 0x3f4c422a, v148
	v_mul_f32_e32 v149, 0x3f4c422a, v149
	v_mul_f32_e32 v150, 0x3f4c422a, v150
	v_mul_f32_e32 v151, 0x3f4c422a, v151
	v_add_f32_e32 v148, v148, v148
	v_add_f32_e32 v149, v149, v149
	v_add_f32_e32 v150, v150, v150
	v_add_f32_e32 v151, v151, v151
	v_mul_f32_e32 v148, 0xbfb8aa3b, v148
	v_mul_f32_e32 v149, 0xbfb8aa3b, v149
	v_mul_f32_e32 v150, 0xbfb8aa3b, v150
	v_mul_f32_e32 v151, 0xbfb8aa3b, v151
	v_exp_f32_e32 v148, v148
	v_exp_f32_e32 v149, v149
	v_exp_f32_e32 v150, v150
	v_exp_f32_e32 v151, v151
	v_add_f32_e32 v148, 1.0, v148
	v_add_f32_e32 v149, 1.0, v149
	v_add_f32_e32 v150, 1.0, v150
	v_add_f32_e32 v151, 1.0, v151
	v_rcp_f32_e32 v148, v148
	v_rcp_f32_e32 v149, v149
	v_rcp_f32_e32 v150, v150
	v_rcp_f32_e32 v151, v151
	s_nop 0
	v_pk_mul_f32 v[148:149], v[66:67], v[148:149]
	v_pk_mul_f32 v[150:151], v[68:69], v[150:151]
	v_cvt_pk_bf16_f32 v164, v148, v149
	v_cvt_pk_bf16_f32 v165, v150, v151
	v_mul_f32_e32 v148, 0x3d372713, v70
	v_mul_f32_e32 v149, 0x3d372713, v71
	v_mul_f32_e32 v150, 0x3d372713, v72
	v_mul_f32_e32 v151, 0x3d372713, v73
	v_mul_f32_e32 v148, v70, v148
	v_mul_f32_e32 v149, v71, v149
	v_mul_f32_e32 v150, v72, v150
	v_mul_f32_e32 v151, v73, v151
	v_fma_f32 v148, v70, v148, v70
	v_fma_f32 v149, v71, v149, v71
	v_fma_f32 v150, v72, v150, v72
	v_fma_f32 v151, v73, v151, v73
	v_mul_f32_e32 v148, 0x3f4c422a, v148
	v_mul_f32_e32 v149, 0x3f4c422a, v149
	v_mul_f32_e32 v150, 0x3f4c422a, v150
	v_mul_f32_e32 v151, 0x3f4c422a, v151
	v_add_f32_e32 v148, v148, v148
	v_add_f32_e32 v149, v149, v149
	v_add_f32_e32 v150, v150, v150
	v_add_f32_e32 v151, v151, v151
	v_mul_f32_e32 v148, 0xbfb8aa3b, v148
	v_mul_f32_e32 v149, 0xbfb8aa3b, v149
	v_mul_f32_e32 v150, 0xbfb8aa3b, v150
	v_mul_f32_e32 v151, 0xbfb8aa3b, v151
	v_exp_f32_e32 v148, v148
	v_exp_f32_e32 v149, v149
	v_exp_f32_e32 v150, v150
	v_exp_f32_e32 v151, v151
	v_add_f32_e32 v148, 1.0, v148
	v_add_f32_e32 v149, 1.0, v149
	v_add_f32_e32 v150, 1.0, v150
	v_add_f32_e32 v151, 1.0, v151
	v_rcp_f32_e32 v148, v148
	v_rcp_f32_e32 v149, v149
	v_rcp_f32_e32 v150, v150
	v_rcp_f32_e32 v151, v151
	s_nop 0
	v_pk_mul_f32 v[148:149], v[70:71], v[148:149]
	v_pk_mul_f32 v[150:151], v[72:73], v[150:151]
	v_cvt_pk_bf16_f32 v166, v148, v149
	v_cvt_pk_bf16_f32 v167, v150, v151
	s_nop 1
	v_permlane16_swap_b32 v164, v166
	v_permlane16_swap_b32 v165, v167
	s_nop 1
	global_store_dwordx4 v156, v[164:167], s[96:97]
	v_mul_f32_e32 v148, 0x3d372713, v82
	v_mul_f32_e32 v149, 0x3d372713, v83
	v_mul_f32_e32 v150, 0x3d372713, v84
	v_mul_f32_e32 v151, 0x3d372713, v85
	v_mul_f32_e32 v148, v82, v148
	v_mul_f32_e32 v149, v83, v149
	v_mul_f32_e32 v150, v84, v150
	v_mul_f32_e32 v151, v85, v151
	v_fma_f32 v148, v82, v148, v82
	v_fma_f32 v149, v83, v149, v83
	v_fma_f32 v150, v84, v150, v84
	v_fma_f32 v151, v85, v151, v85
	v_mul_f32_e32 v148, 0x3f4c422a, v148
	v_mul_f32_e32 v149, 0x3f4c422a, v149
	v_mul_f32_e32 v150, 0x3f4c422a, v150
	v_mul_f32_e32 v151, 0x3f4c422a, v151
	v_add_f32_e32 v148, v148, v148
	v_add_f32_e32 v149, v149, v149
	v_add_f32_e32 v150, v150, v150
	v_add_f32_e32 v151, v151, v151
	v_mul_f32_e32 v148, 0xbfb8aa3b, v148
	v_mul_f32_e32 v149, 0xbfb8aa3b, v149
	v_mul_f32_e32 v150, 0xbfb8aa3b, v150
	v_mul_f32_e32 v151, 0xbfb8aa3b, v151
	v_exp_f32_e32 v148, v148
	v_exp_f32_e32 v149, v149
	v_exp_f32_e32 v150, v150
	v_exp_f32_e32 v151, v151
	v_add_f32_e32 v148, 1.0, v148
	v_add_f32_e32 v149, 1.0, v149
	v_add_f32_e32 v150, 1.0, v150
	v_add_f32_e32 v151, 1.0, v151
	v_rcp_f32_e32 v148, v148
	v_rcp_f32_e32 v149, v149
	v_rcp_f32_e32 v150, v150
	v_rcp_f32_e32 v151, v151
	s_nop 0
	v_pk_mul_f32 v[148:149], v[82:83], v[148:149]
	v_pk_mul_f32 v[150:151], v[84:85], v[150:151]
	v_cvt_pk_bf16_f32 v168, v148, v149
	v_cvt_pk_bf16_f32 v169, v150, v151
	v_mul_f32_e32 v148, 0x3d372713, v88
	v_mul_f32_e32 v149, 0x3d372713, v89
	v_mul_f32_e32 v150, 0x3d372713, v90
	v_mul_f32_e32 v151, 0x3d372713, v91
	v_mul_f32_e32 v148, v88, v148
	v_mul_f32_e32 v149, v89, v149
	v_mul_f32_e32 v150, v90, v150
	v_mul_f32_e32 v151, v91, v151
	v_fma_f32 v148, v88, v148, v88
	v_fma_f32 v149, v89, v149, v89
	v_fma_f32 v150, v90, v150, v90
	v_fma_f32 v151, v91, v151, v91
	v_mul_f32_e32 v148, 0x3f4c422a, v148
	v_mul_f32_e32 v149, 0x3f4c422a, v149
	v_mul_f32_e32 v150, 0x3f4c422a, v150
	v_mul_f32_e32 v151, 0x3f4c422a, v151
	v_add_f32_e32 v148, v148, v148
	v_add_f32_e32 v149, v149, v149
	v_add_f32_e32 v150, v150, v150
	v_add_f32_e32 v151, v151, v151
	v_mul_f32_e32 v148, 0xbfb8aa3b, v148
	v_mul_f32_e32 v149, 0xbfb8aa3b, v149
	v_mul_f32_e32 v150, 0xbfb8aa3b, v150
	v_mul_f32_e32 v151, 0xbfb8aa3b, v151
	v_exp_f32_e32 v148, v148
	v_exp_f32_e32 v149, v149
	v_exp_f32_e32 v150, v150
	v_exp_f32_e32 v151, v151
	v_add_f32_e32 v148, 1.0, v148
	v_add_f32_e32 v149, 1.0, v149
	v_add_f32_e32 v150, 1.0, v150
	v_add_f32_e32 v151, 1.0, v151
	v_rcp_f32_e32 v148, v148
	v_rcp_f32_e32 v149, v149
	v_rcp_f32_e32 v150, v150
	v_rcp_f32_e32 v151, v151
	s_nop 0
	v_pk_mul_f32 v[148:149], v[88:89], v[148:149]
	v_pk_mul_f32 v[150:151], v[90:91], v[150:151]
	v_cvt_pk_bf16_f32 v170, v148, v149
	v_cvt_pk_bf16_f32 v171, v150, v151
	s_nop 1
	v_permlane16_swap_b32 v168, v170
	v_permlane16_swap_b32 v169, v171
	s_nop 1
	global_store_dwordx4 v156, v[168:171], s[96:97] offset:64
	v_mul_f32_e32 v148, 0x3d372713, v92
	v_mul_f32_e32 v149, 0x3d372713, v93
	v_mul_f32_e32 v150, 0x3d372713, v94
	v_mul_f32_e32 v151, 0x3d372713, v95
	v_mul_f32_e32 v148, v92, v148
	v_mul_f32_e32 v149, v93, v149
	v_mul_f32_e32 v150, v94, v150
	v_mul_f32_e32 v151, v95, v151
	v_fma_f32 v148, v92, v148, v92
	v_fma_f32 v149, v93, v149, v93
	v_fma_f32 v150, v94, v150, v94
	v_fma_f32 v151, v95, v151, v95
	v_mul_f32_e32 v148, 0x3f4c422a, v148
	v_mul_f32_e32 v149, 0x3f4c422a, v149
	v_mul_f32_e32 v150, 0x3f4c422a, v150
	v_mul_f32_e32 v151, 0x3f4c422a, v151
	v_add_f32_e32 v148, v148, v148
	v_add_f32_e32 v149, v149, v149
	v_add_f32_e32 v150, v150, v150
	v_add_f32_e32 v151, v151, v151
	v_mul_f32_e32 v148, 0xbfb8aa3b, v148
	v_mul_f32_e32 v149, 0xbfb8aa3b, v149
	v_mul_f32_e32 v150, 0xbfb8aa3b, v150
	v_mul_f32_e32 v151, 0xbfb8aa3b, v151
	v_exp_f32_e32 v148, v148
	v_exp_f32_e32 v149, v149
	v_exp_f32_e32 v150, v150
	v_exp_f32_e32 v151, v151
	v_add_f32_e32 v148, 1.0, v148
	v_add_f32_e32 v149, 1.0, v149
	v_add_f32_e32 v150, 1.0, v150
	v_add_f32_e32 v151, 1.0, v151
	v_rcp_f32_e32 v148, v148
	v_rcp_f32_e32 v149, v149
	v_rcp_f32_e32 v150, v150
	v_rcp_f32_e32 v151, v151
	s_nop 0
	v_pk_mul_f32 v[148:149], v[92:93], v[148:149]
	v_pk_mul_f32 v[150:151], v[94:95], v[150:151]
	v_cvt_pk_bf16_f32 v164, v148, v149
	v_cvt_pk_bf16_f32 v165, v150, v151
	v_mul_f32_e32 v148, 0x3d372713, v96
	v_mul_f32_e32 v149, 0x3d372713, v97
	v_mul_f32_e32 v150, 0x3d372713, v98
	v_mul_f32_e32 v151, 0x3d372713, v99
	v_mul_f32_e32 v148, v96, v148
	v_mul_f32_e32 v149, v97, v149
	v_mul_f32_e32 v150, v98, v150
	v_mul_f32_e32 v151, v99, v151
	v_fma_f32 v148, v96, v148, v96
	v_fma_f32 v149, v97, v149, v97
	v_fma_f32 v150, v98, v150, v98
	v_fma_f32 v151, v99, v151, v99
	v_mul_f32_e32 v148, 0x3f4c422a, v148
	v_mul_f32_e32 v149, 0x3f4c422a, v149
	v_mul_f32_e32 v150, 0x3f4c422a, v150
	v_mul_f32_e32 v151, 0x3f4c422a, v151
	v_add_f32_e32 v148, v148, v148
	v_add_f32_e32 v149, v149, v149
	v_add_f32_e32 v150, v150, v150
	v_add_f32_e32 v151, v151, v151
	v_mul_f32_e32 v148, 0xbfb8aa3b, v148
	v_mul_f32_e32 v149, 0xbfb8aa3b, v149
	v_mul_f32_e32 v150, 0xbfb8aa3b, v150
	v_mul_f32_e32 v151, 0xbfb8aa3b, v151
	v_exp_f32_e32 v148, v148
	v_exp_f32_e32 v149, v149
	v_exp_f32_e32 v150, v150
	v_exp_f32_e32 v151, v151
	v_add_f32_e32 v148, 1.0, v148
	v_add_f32_e32 v149, 1.0, v149
	v_add_f32_e32 v150, 1.0, v150
	v_add_f32_e32 v151, 1.0, v151
	v_rcp_f32_e32 v148, v148
	v_rcp_f32_e32 v149, v149
	v_rcp_f32_e32 v150, v150
	v_rcp_f32_e32 v151, v151
	s_nop 0
	v_pk_mul_f32 v[148:149], v[96:97], v[148:149]
	v_pk_mul_f32 v[150:151], v[98:99], v[150:151]
	v_cvt_pk_bf16_f32 v166, v148, v149
	v_cvt_pk_bf16_f32 v167, v150, v151
	s_nop 1
	v_permlane16_swap_b32 v164, v166
	v_permlane16_swap_b32 v165, v167
	s_nop 1
	global_store_dwordx4 v157, v[164:167], s[96:97]
	v_mul_f32_e32 v148, 0x3d372713, v100
	v_mul_f32_e32 v149, 0x3d372713, v101
	v_mul_f32_e32 v150, 0x3d372713, v102
	v_mul_f32_e32 v151, 0x3d372713, v103
	v_mul_f32_e32 v148, v100, v148
	v_mul_f32_e32 v149, v101, v149
	v_mul_f32_e32 v150, v102, v150
	v_mul_f32_e32 v151, v103, v151
	v_fma_f32 v148, v100, v148, v100
	v_fma_f32 v149, v101, v149, v101
	v_fma_f32 v150, v102, v150, v102
	v_fma_f32 v151, v103, v151, v103
	v_mul_f32_e32 v148, 0x3f4c422a, v148
	v_mul_f32_e32 v149, 0x3f4c422a, v149
	v_mul_f32_e32 v150, 0x3f4c422a, v150
	v_mul_f32_e32 v151, 0x3f4c422a, v151
	v_add_f32_e32 v148, v148, v148
	v_add_f32_e32 v149, v149, v149
	v_add_f32_e32 v150, v150, v150
	v_add_f32_e32 v151, v151, v151
	v_mul_f32_e32 v148, 0xbfb8aa3b, v148
	v_mul_f32_e32 v149, 0xbfb8aa3b, v149
	v_mul_f32_e32 v150, 0xbfb8aa3b, v150
	v_mul_f32_e32 v151, 0xbfb8aa3b, v151
	v_exp_f32_e32 v148, v148
	v_exp_f32_e32 v149, v149
	v_exp_f32_e32 v150, v150
	v_exp_f32_e32 v151, v151
	v_add_f32_e32 v148, 1.0, v148
	v_add_f32_e32 v149, 1.0, v149
	v_add_f32_e32 v150, 1.0, v150
	v_add_f32_e32 v151, 1.0, v151
	v_rcp_f32_e32 v148, v148
	v_rcp_f32_e32 v149, v149
	v_rcp_f32_e32 v150, v150
	v_rcp_f32_e32 v151, v151
	s_nop 0
	v_pk_mul_f32 v[148:149], v[100:101], v[148:149]
	v_pk_mul_f32 v[150:151], v[102:103], v[150:151]
	v_cvt_pk_bf16_f32 v168, v148, v149
	v_cvt_pk_bf16_f32 v169, v150, v151
	v_mul_f32_e32 v148, 0x3d372713, v106
	v_mul_f32_e32 v149, 0x3d372713, v107
	v_mul_f32_e32 v150, 0x3d372713, v108
	v_mul_f32_e32 v151, 0x3d372713, v109
	v_mul_f32_e32 v148, v106, v148
	v_mul_f32_e32 v149, v107, v149
	v_mul_f32_e32 v150, v108, v150
	v_mul_f32_e32 v151, v109, v151
	v_fma_f32 v148, v106, v148, v106
	v_fma_f32 v149, v107, v149, v107
	v_fma_f32 v150, v108, v150, v108
	v_fma_f32 v151, v109, v151, v109
	v_mul_f32_e32 v148, 0x3f4c422a, v148
	v_mul_f32_e32 v149, 0x3f4c422a, v149
	v_mul_f32_e32 v150, 0x3f4c422a, v150
	v_mul_f32_e32 v151, 0x3f4c422a, v151
	v_add_f32_e32 v148, v148, v148
	v_add_f32_e32 v149, v149, v149
	v_add_f32_e32 v150, v150, v150
	v_add_f32_e32 v151, v151, v151
	v_mul_f32_e32 v148, 0xbfb8aa3b, v148
	v_mul_f32_e32 v149, 0xbfb8aa3b, v149
	v_mul_f32_e32 v150, 0xbfb8aa3b, v150
	v_mul_f32_e32 v151, 0xbfb8aa3b, v151
	v_exp_f32_e32 v148, v148
	v_exp_f32_e32 v149, v149
	v_exp_f32_e32 v150, v150
	v_exp_f32_e32 v151, v151
	v_add_f32_e32 v148, 1.0, v148
	v_add_f32_e32 v149, 1.0, v149
	v_add_f32_e32 v150, 1.0, v150
	v_add_f32_e32 v151, 1.0, v151
	v_rcp_f32_e32 v148, v148
	v_rcp_f32_e32 v149, v149
	v_rcp_f32_e32 v150, v150
	v_rcp_f32_e32 v151, v151
	s_nop 0
	v_pk_mul_f32 v[148:149], v[106:107], v[148:149]
	v_pk_mul_f32 v[150:151], v[108:109], v[150:151]
	v_cvt_pk_bf16_f32 v170, v148, v149
	v_cvt_pk_bf16_f32 v171, v150, v151
	s_nop 1
	v_permlane16_swap_b32 v168, v170
	v_permlane16_swap_b32 v169, v171
	s_nop 1
	global_store_dwordx4 v157, v[168:171], s[96:97] offset:64
	v_mul_f32_e32 v148, 0x3d372713, v110
	v_mul_f32_e32 v149, 0x3d372713, v111
	v_mul_f32_e32 v150, 0x3d372713, v112
	v_mul_f32_e32 v151, 0x3d372713, v113
	v_mul_f32_e32 v148, v110, v148
	v_mul_f32_e32 v149, v111, v149
	v_mul_f32_e32 v150, v112, v150
	v_mul_f32_e32 v151, v113, v151
	v_fma_f32 v148, v110, v148, v110
	v_fma_f32 v149, v111, v149, v111
	v_fma_f32 v150, v112, v150, v112
	v_fma_f32 v151, v113, v151, v113
	v_mul_f32_e32 v148, 0x3f4c422a, v148
	v_mul_f32_e32 v149, 0x3f4c422a, v149
	v_mul_f32_e32 v150, 0x3f4c422a, v150
	v_mul_f32_e32 v151, 0x3f4c422a, v151
	v_add_f32_e32 v148, v148, v148
	v_add_f32_e32 v149, v149, v149
	v_add_f32_e32 v150, v150, v150
	v_add_f32_e32 v151, v151, v151
	v_mul_f32_e32 v148, 0xbfb8aa3b, v148
	v_mul_f32_e32 v149, 0xbfb8aa3b, v149
	v_mul_f32_e32 v150, 0xbfb8aa3b, v150
	v_mul_f32_e32 v151, 0xbfb8aa3b, v151
	v_exp_f32_e32 v148, v148
	v_exp_f32_e32 v149, v149
	v_exp_f32_e32 v150, v150
	v_exp_f32_e32 v151, v151
	v_add_f32_e32 v148, 1.0, v148
	v_add_f32_e32 v149, 1.0, v149
	v_add_f32_e32 v150, 1.0, v150
	v_add_f32_e32 v151, 1.0, v151
	v_rcp_f32_e32 v148, v148
	v_rcp_f32_e32 v149, v149
	v_rcp_f32_e32 v150, v150
	v_rcp_f32_e32 v151, v151
	s_nop 0
	v_pk_mul_f32 v[148:149], v[110:111], v[148:149]
	v_pk_mul_f32 v[150:151], v[112:113], v[150:151]
	v_cvt_pk_bf16_f32 v164, v148, v149
	v_cvt_pk_bf16_f32 v165, v150, v151
	v_mul_f32_e32 v148, 0x3d372713, v114
	v_mul_f32_e32 v149, 0x3d372713, v115
	v_mul_f32_e32 v150, 0x3d372713, v116
	v_mul_f32_e32 v151, 0x3d372713, v117
	v_mul_f32_e32 v148, v114, v148
	v_mul_f32_e32 v149, v115, v149
	v_mul_f32_e32 v150, v116, v150
	v_mul_f32_e32 v151, v117, v151
	v_fma_f32 v148, v114, v148, v114
	v_fma_f32 v149, v115, v149, v115
	v_fma_f32 v150, v116, v150, v116
	v_fma_f32 v151, v117, v151, v117
	v_mul_f32_e32 v148, 0x3f4c422a, v148
	v_mul_f32_e32 v149, 0x3f4c422a, v149
	v_mul_f32_e32 v150, 0x3f4c422a, v150
	v_mul_f32_e32 v151, 0x3f4c422a, v151
	v_add_f32_e32 v148, v148, v148
	v_add_f32_e32 v149, v149, v149
	v_add_f32_e32 v150, v150, v150
	v_add_f32_e32 v151, v151, v151
	v_mul_f32_e32 v148, 0xbfb8aa3b, v148
	v_mul_f32_e32 v149, 0xbfb8aa3b, v149
	v_mul_f32_e32 v150, 0xbfb8aa3b, v150
	v_mul_f32_e32 v151, 0xbfb8aa3b, v151
	v_exp_f32_e32 v148, v148
	v_exp_f32_e32 v149, v149
	v_exp_f32_e32 v150, v150
	v_exp_f32_e32 v151, v151
	v_add_f32_e32 v148, 1.0, v148
	v_add_f32_e32 v149, 1.0, v149
	v_add_f32_e32 v150, 1.0, v150
	v_add_f32_e32 v151, 1.0, v151
	v_rcp_f32_e32 v148, v148
	v_rcp_f32_e32 v149, v149
	v_rcp_f32_e32 v150, v150
	v_rcp_f32_e32 v151, v151
	s_nop 0
	v_pk_mul_f32 v[148:149], v[114:115], v[148:149]
	v_pk_mul_f32 v[150:151], v[116:117], v[150:151]
	v_cvt_pk_bf16_f32 v166, v148, v149
	v_cvt_pk_bf16_f32 v167, v150, v151
	s_nop 1
	v_permlane16_swap_b32 v164, v166
	v_permlane16_swap_b32 v165, v167
	s_nop 1
	global_store_dwordx4 v158, v[164:167], s[96:97]
	v_mul_f32_e32 v148, 0x3d372713, v118
	v_mul_f32_e32 v149, 0x3d372713, v119
	v_mul_f32_e32 v150, 0x3d372713, v120
	v_mul_f32_e32 v151, 0x3d372713, v121
	v_mul_f32_e32 v148, v118, v148
	v_mul_f32_e32 v149, v119, v149
	v_mul_f32_e32 v150, v120, v150
	v_mul_f32_e32 v151, v121, v151
	v_fma_f32 v148, v118, v148, v118
	v_fma_f32 v149, v119, v149, v119
	v_fma_f32 v150, v120, v150, v120
	v_fma_f32 v151, v121, v151, v121
	v_mul_f32_e32 v148, 0x3f4c422a, v148
	v_mul_f32_e32 v149, 0x3f4c422a, v149
	v_mul_f32_e32 v150, 0x3f4c422a, v150
	v_mul_f32_e32 v151, 0x3f4c422a, v151
	v_add_f32_e32 v148, v148, v148
	v_add_f32_e32 v149, v149, v149
	v_add_f32_e32 v150, v150, v150
	v_add_f32_e32 v151, v151, v151
	v_mul_f32_e32 v148, 0xbfb8aa3b, v148
	v_mul_f32_e32 v149, 0xbfb8aa3b, v149
	v_mul_f32_e32 v150, 0xbfb8aa3b, v150
	v_mul_f32_e32 v151, 0xbfb8aa3b, v151
	v_exp_f32_e32 v148, v148
	v_exp_f32_e32 v149, v149
	v_exp_f32_e32 v150, v150
	v_exp_f32_e32 v151, v151
	v_add_f32_e32 v148, 1.0, v148
	v_add_f32_e32 v149, 1.0, v149
	v_add_f32_e32 v150, 1.0, v150
	v_add_f32_e32 v151, 1.0, v151
	v_rcp_f32_e32 v148, v148
	v_rcp_f32_e32 v149, v149
	v_rcp_f32_e32 v150, v150
	v_rcp_f32_e32 v151, v151
	s_nop 0
	v_pk_mul_f32 v[148:149], v[118:119], v[148:149]
	v_pk_mul_f32 v[150:151], v[120:121], v[150:151]
	v_cvt_pk_bf16_f32 v168, v148, v149
	v_cvt_pk_bf16_f32 v169, v150, v151
	v_mul_f32_e32 v148, 0x3d372713, v122
	v_mul_f32_e32 v149, 0x3d372713, v123
	v_mul_f32_e32 v150, 0x3d372713, v124
	v_mul_f32_e32 v151, 0x3d372713, v125
	v_mul_f32_e32 v148, v122, v148
	v_mul_f32_e32 v149, v123, v149
	v_mul_f32_e32 v150, v124, v150
	v_mul_f32_e32 v151, v125, v151
	v_fma_f32 v148, v122, v148, v122
	v_fma_f32 v149, v123, v149, v123
	v_fma_f32 v150, v124, v150, v124
	v_fma_f32 v151, v125, v151, v125
	v_mul_f32_e32 v148, 0x3f4c422a, v148
	v_mul_f32_e32 v149, 0x3f4c422a, v149
	v_mul_f32_e32 v150, 0x3f4c422a, v150
	v_mul_f32_e32 v151, 0x3f4c422a, v151
	v_add_f32_e32 v148, v148, v148
	v_add_f32_e32 v149, v149, v149
	v_add_f32_e32 v150, v150, v150
	v_add_f32_e32 v151, v151, v151
	v_mul_f32_e32 v148, 0xbfb8aa3b, v148
	v_mul_f32_e32 v149, 0xbfb8aa3b, v149
	v_mul_f32_e32 v150, 0xbfb8aa3b, v150
	v_mul_f32_e32 v151, 0xbfb8aa3b, v151
	v_exp_f32_e32 v148, v148
	v_exp_f32_e32 v149, v149
	v_exp_f32_e32 v150, v150
	v_exp_f32_e32 v151, v151
	v_add_f32_e32 v148, 1.0, v148
	v_add_f32_e32 v149, 1.0, v149
	v_add_f32_e32 v150, 1.0, v150
	v_add_f32_e32 v151, 1.0, v151
	v_rcp_f32_e32 v148, v148
	v_rcp_f32_e32 v149, v149
	v_rcp_f32_e32 v150, v150
	v_rcp_f32_e32 v151, v151
	s_nop 0
	v_pk_mul_f32 v[148:149], v[122:123], v[148:149]
	v_pk_mul_f32 v[150:151], v[124:125], v[150:151]
	v_cvt_pk_bf16_f32 v170, v148, v149
	v_cvt_pk_bf16_f32 v171, v150, v151
	s_nop 1
	v_permlane16_swap_b32 v168, v170
	v_permlane16_swap_b32 v169, v171
	s_nop 1
	global_store_dwordx4 v158, v[168:171], s[96:97] offset:64
	v_mul_f32_e32 v148, 0x3d372713, v126
	v_mul_f32_e32 v149, 0x3d372713, v127
	v_mul_f32_e32 v150, 0x3d372713, v128
	v_mul_f32_e32 v151, 0x3d372713, v129
	v_mul_f32_e32 v148, v126, v148
	v_mul_f32_e32 v149, v127, v149
	v_mul_f32_e32 v150, v128, v150
	v_mul_f32_e32 v151, v129, v151
	v_fma_f32 v148, v126, v148, v126
	v_fma_f32 v149, v127, v149, v127
	v_fma_f32 v150, v128, v150, v128
	v_fma_f32 v151, v129, v151, v129
	v_mul_f32_e32 v148, 0x3f4c422a, v148
	v_mul_f32_e32 v149, 0x3f4c422a, v149
	v_mul_f32_e32 v150, 0x3f4c422a, v150
	v_mul_f32_e32 v151, 0x3f4c422a, v151
	v_add_f32_e32 v148, v148, v148
	v_add_f32_e32 v149, v149, v149
	v_add_f32_e32 v150, v150, v150
	v_add_f32_e32 v151, v151, v151
	v_mul_f32_e32 v148, 0xbfb8aa3b, v148
	v_mul_f32_e32 v149, 0xbfb8aa3b, v149
	v_mul_f32_e32 v150, 0xbfb8aa3b, v150
	v_mul_f32_e32 v151, 0xbfb8aa3b, v151
	v_exp_f32_e32 v148, v148
	v_exp_f32_e32 v149, v149
	v_exp_f32_e32 v150, v150
	v_exp_f32_e32 v151, v151
	v_add_f32_e32 v148, 1.0, v148
	v_add_f32_e32 v149, 1.0, v149
	v_add_f32_e32 v150, 1.0, v150
	v_add_f32_e32 v151, 1.0, v151
	v_rcp_f32_e32 v148, v148
	v_rcp_f32_e32 v149, v149
	v_rcp_f32_e32 v150, v150
	v_rcp_f32_e32 v151, v151
	s_nop 0
	v_pk_mul_f32 v[148:149], v[126:127], v[148:149]
	v_pk_mul_f32 v[150:151], v[128:129], v[150:151]
	v_cvt_pk_bf16_f32 v164, v148, v149
	v_cvt_pk_bf16_f32 v165, v150, v151
	v_mul_f32_e32 v148, 0x3d372713, v136
	v_mul_f32_e32 v149, 0x3d372713, v137
	v_mul_f32_e32 v150, 0x3d372713, v138
	v_mul_f32_e32 v151, 0x3d372713, v139
	v_mul_f32_e32 v148, v136, v148
	v_mul_f32_e32 v149, v137, v149
	v_mul_f32_e32 v150, v138, v150
	v_mul_f32_e32 v151, v139, v151
	v_fma_f32 v148, v136, v148, v136
	v_fma_f32 v149, v137, v149, v137
	v_fma_f32 v150, v138, v150, v138
	v_fma_f32 v151, v139, v151, v139
	v_mul_f32_e32 v148, 0x3f4c422a, v148
	v_mul_f32_e32 v149, 0x3f4c422a, v149
	v_mul_f32_e32 v150, 0x3f4c422a, v150
	v_mul_f32_e32 v151, 0x3f4c422a, v151
	v_add_f32_e32 v148, v148, v148
	v_add_f32_e32 v149, v149, v149
	v_add_f32_e32 v150, v150, v150
	v_add_f32_e32 v151, v151, v151
	v_mul_f32_e32 v148, 0xbfb8aa3b, v148
	v_mul_f32_e32 v149, 0xbfb8aa3b, v149
	v_mul_f32_e32 v150, 0xbfb8aa3b, v150
	v_mul_f32_e32 v151, 0xbfb8aa3b, v151
	v_exp_f32_e32 v148, v148
	v_exp_f32_e32 v149, v149
	v_exp_f32_e32 v150, v150
	v_exp_f32_e32 v151, v151
	v_add_f32_e32 v148, 1.0, v148
	v_add_f32_e32 v149, 1.0, v149
	v_add_f32_e32 v150, 1.0, v150
	v_add_f32_e32 v151, 1.0, v151
	v_rcp_f32_e32 v148, v148
	v_rcp_f32_e32 v149, v149
	v_rcp_f32_e32 v150, v150
	v_rcp_f32_e32 v151, v151
	s_nop 0
	v_pk_mul_f32 v[148:149], v[136:137], v[148:149]
	v_pk_mul_f32 v[150:151], v[138:139], v[150:151]
	v_cvt_pk_bf16_f32 v166, v148, v149
	v_cvt_pk_bf16_f32 v167, v150, v151
	s_nop 1
	v_permlane16_swap_b32 v164, v166
	v_permlane16_swap_b32 v165, v167
	s_nop 1
	global_store_dwordx4 v159, v[164:167], s[96:97]
	v_mul_f32_e32 v148, 0x3d372713, v140
	v_mul_f32_e32 v149, 0x3d372713, v141
	v_mul_f32_e32 v150, 0x3d372713, v142
	v_mul_f32_e32 v151, 0x3d372713, v143
	v_mul_f32_e32 v148, v140, v148
	v_mul_f32_e32 v149, v141, v149
	v_mul_f32_e32 v150, v142, v150
	v_mul_f32_e32 v151, v143, v151
	v_fma_f32 v148, v140, v148, v140
	v_fma_f32 v149, v141, v149, v141
	v_fma_f32 v150, v142, v150, v142
	v_fma_f32 v151, v143, v151, v143
	v_mul_f32_e32 v148, 0x3f4c422a, v148
	v_mul_f32_e32 v149, 0x3f4c422a, v149
	v_mul_f32_e32 v150, 0x3f4c422a, v150
	v_mul_f32_e32 v151, 0x3f4c422a, v151
	v_add_f32_e32 v148, v148, v148
	v_add_f32_e32 v149, v149, v149
	v_add_f32_e32 v150, v150, v150
	v_add_f32_e32 v151, v151, v151
	v_mul_f32_e32 v148, 0xbfb8aa3b, v148
	v_mul_f32_e32 v149, 0xbfb8aa3b, v149
	v_mul_f32_e32 v150, 0xbfb8aa3b, v150
	v_mul_f32_e32 v151, 0xbfb8aa3b, v151
	v_exp_f32_e32 v148, v148
	v_exp_f32_e32 v149, v149
	v_exp_f32_e32 v150, v150
	v_exp_f32_e32 v151, v151
	v_add_f32_e32 v148, 1.0, v148
	v_add_f32_e32 v149, 1.0, v149
	v_add_f32_e32 v150, 1.0, v150
	v_add_f32_e32 v151, 1.0, v151
	v_rcp_f32_e32 v148, v148
	v_rcp_f32_e32 v149, v149
	v_rcp_f32_e32 v150, v150
	v_rcp_f32_e32 v151, v151
	s_nop 0
	v_pk_mul_f32 v[148:149], v[140:141], v[148:149]
	v_pk_mul_f32 v[150:151], v[142:143], v[150:151]
	v_cvt_pk_bf16_f32 v168, v148, v149
	v_cvt_pk_bf16_f32 v169, v150, v151
	v_mul_f32_e32 v148, 0x3d372713, v144
	v_mul_f32_e32 v149, 0x3d372713, v145
	v_mul_f32_e32 v150, 0x3d372713, v146
	v_mul_f32_e32 v151, 0x3d372713, v147
	v_mul_f32_e32 v148, v144, v148
	v_mul_f32_e32 v149, v145, v149
	v_mul_f32_e32 v150, v146, v150
	v_mul_f32_e32 v151, v147, v151
	v_fma_f32 v148, v144, v148, v144
	v_fma_f32 v149, v145, v149, v145
	v_fma_f32 v150, v146, v150, v146
	v_fma_f32 v151, v147, v151, v147
	v_mul_f32_e32 v148, 0x3f4c422a, v148
	v_mul_f32_e32 v149, 0x3f4c422a, v149
	v_mul_f32_e32 v150, 0x3f4c422a, v150
	v_mul_f32_e32 v151, 0x3f4c422a, v151
	v_add_f32_e32 v148, v148, v148
	v_add_f32_e32 v149, v149, v149
	v_add_f32_e32 v150, v150, v150
	v_add_f32_e32 v151, v151, v151
	v_mul_f32_e32 v148, 0xbfb8aa3b, v148
	v_mul_f32_e32 v149, 0xbfb8aa3b, v149
	v_mul_f32_e32 v150, 0xbfb8aa3b, v150
	v_mul_f32_e32 v151, 0xbfb8aa3b, v151
	v_exp_f32_e32 v148, v148
	v_exp_f32_e32 v149, v149
	v_exp_f32_e32 v150, v150
	v_exp_f32_e32 v151, v151
	v_add_f32_e32 v148, 1.0, v148
	v_add_f32_e32 v149, 1.0, v149
	v_add_f32_e32 v150, 1.0, v150
	v_add_f32_e32 v151, 1.0, v151
	v_rcp_f32_e32 v148, v148
	v_rcp_f32_e32 v149, v149
	v_rcp_f32_e32 v150, v150
	v_rcp_f32_e32 v151, v151
	s_nop 0
	v_pk_mul_f32 v[148:149], v[144:145], v[148:149]
	v_pk_mul_f32 v[150:151], v[146:147], v[150:151]
	v_cvt_pk_bf16_f32 v170, v148, v149
	v_cvt_pk_bf16_f32 v171, v150, v151
	s_nop 1
	v_permlane16_swap_b32 v168, v170
	v_permlane16_swap_b32 v169, v171
	s_nop 1
	global_store_dwordx4 v159, v[168:171], s[96:97] offset:64
	s_branch .Lg2_next
